# sc1 also on the PLE-projection (pp) and PLE-gate (h3) epilogue stores, with nt streams and sc1 ACT stores
# speedup vs baseline: 1.0082x; 1.0082x over previous
; __device__ __forceinline__ unsigned cvt_pk(float lo, float hi) { unsigned r; asm("v_cvt_pk_bf16_f32 %0, %1, %2" : "=v"(r) : "v"(lo), "v"(hi)); return r; }
;     __device__ __forceinline__ void operator()(AccRef acc, const pg8::Unit& u, int wr, int wc, int, int) const {
;     ...
; #pragma unroll
;         for (int ai = 0; ai < 2; ++ai)
; #pragma unroll
;             for (int m = 0; m < 4; ++m) {
;                 const int row = u.pm * 256 + ai * 128 + wr * 64 + m * 16 + fr;
; #pragma unroll
;                 for (int bj = 0; bj < 2; ++bj) {
;                     const int c0 = u.pn * 256 + bj * 128 + wc * 32 + 8 * fq;
;                     const f32x4 o0 = acc[ai][bj][m][0], o1 = acc[ai][bj][m][1];
;                     v4u w; w.x = cvt_pk(o0[0], o0[1]); w.y = cvt_pk(o0[2], o0[3]); w.z = cvt_pk(o1[0], o1[1]); w.w = cvt_pk(o1[2], o1[3]);
;                     *(v4u*)(PP + (size_t)row * DM + c0) = w;
;                 }
.LBB0_696:
	s_mov_b64 s[58:59], s[44:45]
	s_mov_b64 s[62:63], s[46:47]
	s_add_u32 s58, s58, 0x3600000
	v_mov_b32_e32 v137, v196
	s_addc_u32 s59, s59, 0
	s_lshl_b32 s15, s56, 8
	s_add_i32 s15, s15, s35
	v_and_or_b32 v136, v137, 15, s15
	s_lshl_b32 s15, s54, 8
	v_ashrrev_i32_e32 v137, 1, v137
	v_and_b32_e32 v137, -8, v137
	s_or_b32 s15, s15, s28
	v_cvt_pk_bf16_f32 v68, v68, v69
	v_cvt_pk_bf16_f32 v69, v70, v71
	v_cvt_pk_bf16_f32 v70, v64, v65
	v_add_u32_e32 v64, 0x80, v136
	v_add_u32_e32 v144, s15, v137
	v_ashrrev_i32_e32 v137, 31, v136
	v_ashrrev_i32_e32 v65, 31, v64
	v_lshlrev_b64 v[146:147], 11, v[136:137]
	v_ashrrev_i32_e32 v145, 31, v144
	v_cvt_pk_bf16_f32 v112, v112, v113
	v_cvt_pk_bf16_f32 v113, v114, v115
	v_cvt_pk_bf16_f32 v114, v104, v105
	v_or_b32_e32 v104, 16, v136
	v_lshlrev_b64 v[64:65], 11, v[64:65]
	v_cvt_pk_bf16_f32 v48, v48, v49
	v_cvt_pk_bf16_f32 v49, v50, v51
	v_cvt_pk_bf16_f32 v50, v40, v41
	v_add_u32_e32 v40, 0x90, v136
	v_lshl_add_u64 v[146:147], s[58:59], 0, v[146:147]
	v_cvt_pk_bf16_f32 v124, v124, v125
	v_cvt_pk_bf16_f32 v125, v126, v127
	v_cvt_pk_bf16_f32 v126, v120, v121
	v_lshlrev_b64 v[120:121], 1, v[144:145]
	v_ashrrev_i32_e32 v105, 31, v104
	v_lshl_add_u64 v[64:65], s[58:59], 0, v[64:65]
	v_ashrrev_i32_e32 v41, 31, v40
	v_cvt_pk_bf16_f32 v127, v122, v123
	v_lshl_add_u64 v[122:123], v[146:147], 0, v[120:121]
	v_lshlrev_b64 v[104:105], 11, v[104:105]
	v_cvt_pk_bf16_f32 v96, v96, v97
	v_cvt_pk_bf16_f32 v97, v98, v99
	v_cvt_pk_bf16_f32 v98, v88, v89
	v_or_b32_e32 v88, 32, v136
	v_cvt_pk_bf16_f32 v60, v60, v61
	v_cvt_pk_bf16_f32 v61, v62, v63
	v_cvt_pk_bf16_f32 v62, v56, v57
	v_lshl_add_u64 v[56:57], v[64:65], 0, v[120:121]
	v_lshlrev_b64 v[40:41], 11, v[40:41]
	v_cvt_pk_bf16_f32 v32, v32, v33
	v_cvt_pk_bf16_f32 v33, v34, v35
	v_cvt_pk_bf16_f32 v34, v24, v25
	v_add_u32_e32 v24, 0xa0, v136
	v_cvt_pk_bf16_f32 v115, v106, v107
	global_store_dwordx4 v[122:123], v[112:115], off offset:256 sc1
	v_ashrrev_i32_e32 v89, 31, v88
	v_cvt_pk_bf16_f32 v51, v42, v43
	global_store_dwordx4 v[56:57], v[48:51], off offset:256 sc1
	v_lshl_add_u64 v[112:113], s[58:59], 0, v[104:105]
	v_ashrrev_i32_e32 v25, 31, v24
	v_lshl_add_u64 v[48:49], s[58:59], 0, v[40:41]
	v_cvt_pk_bf16_f32 v106, v108, v109
	v_lshl_add_u64 v[108:109], v[112:113], 0, v[120:121]
	v_lshlrev_b64 v[88:89], 11, v[88:89]
	v_cvt_pk_bf16_f32 v80, v80, v81
	v_cvt_pk_bf16_f32 v81, v82, v83
	v_cvt_pk_bf16_f32 v82, v72, v73
	v_or_b32_e32 v72, 48, v136
	v_cvt_pk_bf16_f32 v42, v44, v45
	v_lshl_add_u64 v[44:45], v[48:49], 0, v[120:121]
	v_lshlrev_b64 v[24:25], 11, v[24:25]
	v_cvt_pk_bf16_f32 v16, v16, v17
	v_cvt_pk_bf16_f32 v17, v18, v19
	v_cvt_pk_bf16_f32 v18, v8, v9
	v_add_u32_e32 v8, 0xb0, v136
	v_cvt_pk_bf16_f32 v99, v90, v91
	global_store_dwordx4 v[108:109], v[96:99], off offset:256 sc1
	v_ashrrev_i32_e32 v73, 31, v72
	v_cvt_pk_bf16_f32 v35, v26, v27
	global_store_dwordx4 v[44:45], v[32:35], off offset:256 sc1
	v_lshl_add_u64 v[96:97], s[58:59], 0, v[88:89]
	v_ashrrev_i32_e32 v9, 31, v8
	v_lshl_add_u64 v[32:33], s[58:59], 0, v[24:25]
	v_cvt_pk_bf16_f32 v90, v92, v93
	v_lshl_add_u64 v[92:93], v[96:97], 0, v[120:121]
	v_lshlrev_b64 v[72:73], 11, v[72:73]
	v_cvt_pk_bf16_f32 v26, v28, v29
	v_lshl_add_u64 v[28:29], v[32:33], 0, v[120:121]
	v_lshlrev_b64 v[8:9], 11, v[8:9]
	v_cvt_pk_bf16_f32 v83, v74, v75
	global_store_dwordx4 v[92:93], v[80:83], off offset:256 sc1
	v_cvt_pk_bf16_f32 v19, v10, v11
	global_store_dwordx4 v[28:29], v[16:19], off offset:256 sc1
	v_readlane_b32 s86, v249, 46
	v_lshl_add_u64 v[80:81], s[58:59], 0, v[72:73]
	v_lshl_add_u64 v[16:17], s[58:59], 0, v[8:9]
	v_readlane_b32 s74, v249, 39
	v_cvt_pk_bf16_f32 v74, v76, v77
	v_lshl_add_u64 v[76:77], v[80:81], 0, v[120:121]
	v_cvt_pk_bf16_f32 v10, v12, v13
	v_lshl_add_u64 v[12:13], v[16:17], 0, v[120:121]
	s_andn2_b64 vcc, exec, s[30:31]
	s_mov_b64 s[30:31], -1
	v_readlane_b32 s87, v249, 47
	v_readlane_b32 s75, v249, 40
	global_store_dwordx4 v[122:123], v[124:127], off sc1
	v_cvt_pk_bf16_f32 v104, v116, v117
	v_cvt_pk_bf16_f32 v105, v118, v119
	v_cvt_pk_bf16_f32 v107, v110, v111
	global_store_dwordx4 v[108:109], v[104:107], off sc1
	v_cvt_pk_bf16_f32 v88, v100, v101
	v_cvt_pk_bf16_f32 v89, v102, v103
	v_cvt_pk_bf16_f32 v91, v94, v95
	global_store_dwordx4 v[92:93], v[88:91], off sc1
	v_cvt_pk_bf16_f32 v72, v84, v85
	v_cvt_pk_bf16_f32 v73, v86, v87
	v_cvt_pk_bf16_f32 v75, v78, v79
	global_store_dwordx4 v[76:77], v[72:75], off sc1
	v_cvt_pk_bf16_f32 v71, v66, v67
	global_store_dwordx4 v[76:77], v[68:71], off offset:256 sc1
	v_cvt_pk_bf16_f32 v63, v58, v59
	global_store_dwordx4 v[56:57], v[60:63], off sc1
	v_cvt_pk_bf16_f32 v40, v52, v53
	v_cvt_pk_bf16_f32 v41, v54, v55
	v_cvt_pk_bf16_f32 v43, v46, v47
	global_store_dwordx4 v[44:45], v[40:43], off sc1
	v_cvt_pk_bf16_f32 v24, v36, v37
	v_cvt_pk_bf16_f32 v25, v38, v39
	v_cvt_pk_bf16_f32 v27, v30, v31
	global_store_dwordx4 v[28:29], v[24:27], off sc1
	v_cvt_pk_bf16_f32 v8, v20, v21
	v_cvt_pk_bf16_f32 v9, v22, v23
	v_cvt_pk_bf16_f32 v11, v14, v15
	global_store_dwordx4 v[12:13], v[8:11], off sc1
	v_cvt_pk_bf16_f32 v4, v4, v5
	v_cvt_pk_bf16_f32 v5, v6, v7
	v_cvt_pk_bf16_f32 v6, v0, v1
	v_cvt_pk_bf16_f32 v7, v2, v3
	global_store_dwordx4 v[12:13], v[4:7], off offset:256 sc1
	s_cbranch_vccnz .LBB0_686
	s_andn2_b64 vcc, exec, s[10:11]
	s_cbranch_vccnz .LBB0_685
	s_barrier
	s_branch .LBB0_685

; __device__ __forceinline__ float fexp2(float x) { return __builtin_amdgcn_exp2f(x); }
; __device__ __forceinline__ float frcp(float x) { return __builtin_amdgcn_rcpf(x); }
;     __device__ __forceinline__ void operator()(AccRef acc, const pg8::Unit& u, int wr, int wc, int, int) const {
;     ...
;         for (int ai = 0; ai < 2; ++ai) {
;             v4u hwv[4][2], pwv[4][2];
; #pragma unroll
;             for (int m = 0; m < 4; ++m) { const int row = u.pm * 256 + ai * 128 + wr * 64 + m * 16 + fr;
; #pragma unroll
;                 for (int bj = 0; bj < 2; ++bj) { const size_t off = (size_t)row * DM + u.pn * 256 + bj * 128 + wc * 32 + 8 * fq; hwv[m][bj] = *(const v4u*)(HB + off); pwv[m][bj] = *(const v4u*)(XB + off); } }
;             asm volatile("" ::: "memory");
; #pragma unroll
;             for (int m = 0; m < 4; ++m) {
;                 const int row = u.pm * 256 + ai * 128 + wr * 64 + m * 16 + fr;
;                 float ss = 0.f;
; #pragma unroll
;                 for (int bj = 0; bj < 2; ++bj) {
;                     const int c0 = u.pn * 256 + bj * 128 + wc * 32 + 8 * fq;
;                     const v4u hw = hwv[m][bj], pw = pwv[m][bj];
;                     const float hh[8] = {bf_lo(hw.x), bf_hi(hw.x), bf_lo(hw.y), bf_hi(hw.y), bf_lo(hw.z), bf_hi(hw.z), bf_lo(hw.w), bf_hi(hw.w)};
;                     const float pp[8] = {bf_lo(pw.x), bf_hi(pw.x), bf_lo(pw.y), bf_hi(pw.y), bf_lo(pw.z), bf_hi(pw.z), bf_lo(pw.w), bf_hi(pw.w)};
;                     float o[8];
; #pragma unroll
;                     for (int j = 0; j < 4; ++j) {
;                         o[j] = hh[j] + pp[j] * frcp(1.0f + fexp2(-acc[ai][bj][m][0][j] * LOG2E));
;                         o[4 + j] = hh[4 + j] + pp[4 + j] * frcp(1.0f + fexp2(-acc[ai][bj][m][1][j] * LOG2E));
;                     }
.LBB0_833:
	s_mov_b64 s[42:43], s[44:45]
	s_mov_b64 s[48:49], s[46:47]
	s_add_u32 s54, s42, 0x7800000
	s_addc_u32 s55, s43, 0
	s_add_u32 s48, s42, 0x3600000
	s_addc_u32 s49, s43, 0
	s_add_u32 s42, s42, 0x43000
	v_mov_b32_e32 v134, v196
	s_addc_u32 s43, s43, 0
	s_lshl_b32 s15, s52, 8
	s_add_i32 s15, s15, s35
	s_lshl_b32 s50, s50, 8
	v_ashrrev_i32_e32 v128, 1, v134
	v_and_or_b32 v190, v134, 15, s15
	s_ashr_i32 s51, s50, 31
	v_and_b32_e32 v128, -8, v128
	v_ashrrev_i32_e32 v129, 31, v128
	s_or_b64 s[62:63], s[50:51], s[28:29]
	v_ashrrev_i32_e32 v191, 31, v190
	v_lshl_add_u64 v[188:189], s[62:63], 0, v[128:129]
	v_lshlrev_b64 v[130:131], 10, v[190:191]
	v_lshl_add_u64 v[130:131], v[188:189], 0, v[130:131]
	v_lshlrev_b64 v[130:131], 1, v[130:131]
	v_lshl_add_u64 v[132:133], s[54:55], 0, v[130:131]
	v_lshl_add_u64 v[130:131], s[48:49], 0, v[130:131]
	global_load_dwordx4 v[204:207], v[132:133], off
	global_load_dwordx4 v[212:215], v[132:133], off offset:256
	global_load_dwordx4 v[208:211], v[130:131], off
	global_load_dwordx4 v[216:219], v[130:131], off offset:256
	v_mul_f32_e32 v124, 0xbfb8aa3b, v124
	v_exp_f32_e32 v124, v124
	v_mul_f32_e32 v120, 0xbfb8aa3b, v120
	v_exp_f32_e32 v120, v120
	v_mul_f32_e32 v125, 0xbfb8aa3b, v125
	v_add_f32_e32 v124, 1.0, v124
	v_rcp_f32_e32 v225, v124
	v_or_b32_e32 v194, 16, v190
	v_or_b32_e32 v192, 32, v190
	v_or_b32_e32 v124, 48, v190
	v_exp_f32_e32 v224, v125
	v_add_f32_e32 v120, 1.0, v120
	s_or_b32 s15, s50, s28
	v_ashrrev_i32_e32 v195, 31, v194
	v_ashrrev_i32_e32 v193, 31, v192
	v_ashrrev_i32_e32 v125, 31, v124
	v_cmp_gt_u32_e32 vcc, 16, v134
	v_rcp_f32_e32 v226, v120
	v_add_u32_e32 v120, s15, v128
	v_lshlrev_b64 v[128:129], 11, v[190:191]
	v_lshlrev_b64 v[134:135], 10, v[194:195]
	v_lshlrev_b64 v[136:137], 10, v[192:193]
	v_lshlrev_b64 v[138:139], 10, v[124:125]
	v_lshl_add_u64 v[220:221], s[48:49], 0, v[128:129]
	v_lshl_add_u64 v[128:129], v[134:135], 0, v[188:189]
	v_lshl_add_u64 v[134:135], v[136:137], 0, v[188:189]
	v_lshl_add_u64 v[136:137], v[138:139], 0, v[188:189]
	v_lshlrev_b64 v[128:129], 1, v[128:129]
	v_lshlrev_b64 v[134:135], 1, v[134:135]
	v_lshlrev_b64 v[132:133], 1, v[136:137]
	v_lshl_add_u64 v[130:131], s[54:55], 0, v[128:129]
	v_lshl_add_u64 v[128:129], s[48:49], 0, v[128:129]
	v_lshl_add_u64 v[136:137], s[54:55], 0, v[134:135]
	v_lshl_add_u64 v[134:135], s[48:49], 0, v[134:135]
	v_lshl_add_u64 v[138:139], s[54:55], 0, v[132:133]
	v_lshl_add_u64 v[222:223], s[48:49], 0, v[132:133]
	global_load_dwordx4 v[172:175], v[130:131], off
	global_load_dwordx4 v[164:167], v[130:131], off offset:256
	global_load_dwordx4 v[168:171], v[128:129], off
	global_load_dwordx4 v[160:163], v[128:129], off offset:256
	global_load_dwordx4 v[156:159], v[136:137], off
	global_load_dwordx4 v[148:151], v[136:137], off offset:256
	global_load_dwordx4 v[152:155], v[134:135], off
	global_load_dwordx4 v[144:147], v[134:135], off offset:256
	global_load_dwordx4 v[140:143], v[138:139], off
	s_nop 0
	global_load_dwordx4 v[132:135], v[138:139], off offset:256
	s_nop 0
	global_load_dwordx4 v[136:139], v[222:223], off
	global_load_dwordx4 v[128:131], v[222:223], off offset:256
	v_mul_f32_e32 v121, 0xbfb8aa3b, v121
	v_exp_f32_e32 v121, v121
	v_mul_f32_e32 v126, 0xbfb8aa3b, v126
	v_exp_f32_e32 v126, v126
	v_mul_f32_e32 v112, 0xbfb8aa3b, v112
	v_add_f32_e32 v121, 1.0, v121
	v_rcp_f32_e32 v121, v121
	v_exp_f32_e32 v112, v112
	v_mul_f32_e32 v122, 0xbfb8aa3b, v122
	v_mul_f32_e32 v123, 0xbfb8aa3b, v123
	v_exp_f32_e32 v122, v122
	v_exp_f32_e32 v123, v123
	v_add_f32_e32 v112, 1.0, v112
	v_mul_f32_e32 v113, 0xbfb8aa3b, v113
	v_rcp_f32_e32 v112, v112
	v_exp_f32_e32 v113, v113
	v_add_f32_e32 v224, 1.0, v224
	v_add_f32_e32 v122, 1.0, v122
	v_add_f32_e32 v123, 1.0, v123
	v_rcp_f32_e32 v224, v224
	v_rcp_f32_e32 v122, v122
	v_rcp_f32_e32 v123, v123
	v_mul_f32_e32 v114, 0xbfb8aa3b, v114
	v_exp_f32_e32 v114, v114
	v_mul_f32_e32 v116, 0xbfb8aa3b, v116
	v_exp_f32_e32 v116, v116
	v_mul_f32_e32 v117, 0xbfb8aa3b, v117
	v_exp_f32_e32 v117, v117
	v_mul_f32_e32 v115, 0xbfb8aa3b, v115
	v_add_f32_e32 v116, 1.0, v116
	v_rcp_f32_e32 v116, v116
	v_add_f32_e32 v117, 1.0, v117
	v_rcp_f32_e32 v117, v117
	v_exp_f32_e32 v115, v115
	s_waitcnt vmcnt(0)
	v_lshlrev_b32_e32 v229, 16, v206
	v_and_b32_e32 v230, 0xffff0000, v206
	v_lshlrev_b32_e32 v231, 16, v207
	v_and_b32_e32 v232, 0xffff0000, v207
	v_lshlrev_b32_e32 v206, 16, v209
	v_and_b32_e32 v207, 0xffff0000, v209
	v_and_b32_e32 v209, 0xffff0000, v210
	v_fmac_f32_e32 v230, v121, v209
	v_add_f32_e32 v121, 1.0, v126
	v_mul_f32_e32 v126, 0xbfb8aa3b, v127
	v_rcp_f32_e32 v121, v121
	v_exp_f32_e32 v126, v126
	v_lshlrev_b32_e32 v222, 16, v204
	v_and_b32_e32 v223, 0xffff0000, v204
	v_lshlrev_b32_e32 v227, 16, v205
	v_and_b32_e32 v228, 0xffff0000, v205
	v_lshlrev_b32_e32 v204, 16, v208
	v_and_b32_e32 v205, 0xffff0000, v208
	v_lshlrev_b32_e32 v208, 16, v210
	v_fmac_f32_e32 v229, v226, v208
	v_add_f32_e32 v126, 1.0, v126
	v_fmac_f32_e32 v227, v121, v206
	v_lshlrev_b32_e32 v127, 16, v213
	v_and_b32_e32 v208, 0xffff0000, v213
	v_lshlrev_b32_e32 v209, 16, v214
	v_lshlrev_b32_e32 v121, 16, v216
	v_and_b32_e32 v213, 0xffff0000, v216
	v_lshlrev_b32_e32 v216, 16, v218
	v_rcp_f32_e32 v126, v126
	v_fmac_f32_e32 v209, v112, v216
	v_add_f32_e32 v112, 1.0, v113
	v_mul_f32_e32 v113, 0xbfb8aa3b, v118
	v_rcp_f32_e32 v112, v112
	v_exp_f32_e32 v113, v113
	v_lshlrev_b32_e32 v210, 16, v211
	v_and_b32_e32 v211, 0xffff0000, v211
	v_fmac_f32_e32 v223, v224, v205
	v_fmac_f32_e32 v231, v122, v210
	v_fmac_f32_e32 v228, v126, v207
	v_fmac_f32_e32 v232, v123, v211
	v_lshlrev_b32_e32 v123, 16, v212
	v_and_b32_e32 v126, 0xffff0000, v212
; __device__ __forceinline__ unsigned cvt_pk(float lo, float hi) { unsigned r; asm("v_cvt_pk_bf16_f32 %0, %1, %2" : "=v"(r) : "v"(lo), "v"(hi)); return r; }
; __device__ __forceinline__ float fexp2(float x) { return __builtin_amdgcn_exp2f(x); }
; __device__ __forceinline__ float frcp(float x) { return __builtin_amdgcn_rcpf(x); }
;     __device__ __forceinline__ void operator()(AccRef acc, const pg8::Unit& u, int wr, int wc, int, int) const {
;     ...
;             for (int m = 0; m < 4; ++m) {
;                 const int row = u.pm * 256 + ai * 128 + wr * 64 + m * 16 + fr;
;                 float ss = 0.f;
; #pragma unroll
;                 for (int bj = 0; bj < 2; ++bj) {
;                     const int c0 = u.pn * 256 + bj * 128 + wc * 32 + 8 * fq;
;                     const v4u hw = hwv[m][bj], pw = pwv[m][bj];
;                     const float hh[8] = {bf_lo(hw.x), bf_hi(hw.x), bf_lo(hw.y), bf_hi(hw.y), bf_lo(hw.z), bf_hi(hw.z), bf_lo(hw.w), bf_hi(hw.w)};
;                     const float pp[8] = {bf_lo(pw.x), bf_hi(pw.x), bf_lo(pw.y), bf_hi(pw.y), bf_lo(pw.z), bf_hi(pw.z), bf_lo(pw.w), bf_hi(pw.w)};
;                     float o[8];
; #pragma unroll
;                     for (int j = 0; j < 4; ++j) {
;                         o[j] = hh[j] + pp[j] * frcp(1.0f + fexp2(-acc[ai][bj][m][0][j] * LOG2E));
;                         o[4 + j] = hh[4 + j] + pp[4 + j] * frcp(1.0f + fexp2(-acc[ai][bj][m][1][j] * LOG2E));
;                     }
;                     v4u w; w.x = cvt_pk(o[0], o[1]); w.y = cvt_pk(o[2], o[3]); w.z = cvt_pk(o[4], o[5]); w.w = cvt_pk(o[6], o[7]);
;                     *(v4u*)(XB + (size_t)row * DM + c0) = w;
; #pragma unroll
;                     for (int j = 0; j < 8; ++j) ss += o[j] * o[j];
;                 }
;                 ss += __shfl_xor(ss, 16); ss += __shfl_xor(ss, 32);
;                 if (fq == 0) __hip_atomic_fetch_add(ssq + row, ss, __ATOMIC_RELAXED, __HIP_MEMORY_SCOPE_AGENT);
;             }
	v_and_b32_e32 v210, 0xffff0000, v214
	v_lshlrev_b32_e32 v211, 16, v215
	v_and_b32_e32 v212, 0xffff0000, v215
	v_lshlrev_b32_e32 v214, 16, v217
	v_and_b32_e32 v215, 0xffff0000, v217
	v_and_b32_e32 v217, 0xffff0000, v218
	v_fmac_f32_e32 v222, v225, v204
	v_mul_f32_e32 v122, v223, v223
	v_fmac_f32_e32 v210, v112, v217
	v_add_f32_e32 v112, 1.0, v113
	v_add_f32_e32 v113, 1.0, v114
	v_mul_f32_e32 v114, 0xbfb8aa3b, v119
	v_fmac_f32_e32 v122, v222, v222
	v_exp_f32_e32 v114, v114
	v_fmac_f32_e32 v122, v227, v227
	v_fmac_f32_e32 v122, v228, v228
	v_fmac_f32_e32 v122, v229, v229
	v_fmac_f32_e32 v122, v230, v230
	v_rcp_f32_e32 v112, v112
	v_add_f32_e32 v114, 1.0, v114
	v_fmac_f32_e32 v122, v231, v231
	v_rcp_f32_e32 v114, v114
	v_fmac_f32_e32 v122, v232, v232
	v_fmac_f32_e32 v123, v116, v121
	v_fmac_f32_e32 v126, v117, v213
	v_fmac_f32_e32 v122, v123, v123
	v_rcp_f32_e32 v113, v113
	v_add_f32_e32 v115, 1.0, v115
	v_fmac_f32_e32 v127, v112, v214
	v_fmac_f32_e32 v122, v126, v126
	v_rcp_f32_e32 v115, v115
	v_fmac_f32_e32 v208, v114, v215
	v_fmac_f32_e32 v122, v127, v127
	v_fmac_f32_e32 v122, v208, v208
	v_lshlrev_b32_e32 v218, 16, v219
	v_fmac_f32_e32 v122, v209, v209
	v_and_b32_e32 v219, 0xffff0000, v219
	v_fmac_f32_e32 v211, v113, v218
	v_fmac_f32_e32 v122, v210, v210
	v_fmac_f32_e32 v212, v115, v219
	v_fmac_f32_e32 v122, v211, v211
	v_fmac_f32_e32 v122, v212, v212
	ds_bpermute_b32 v112, v197, v122
	v_ashrrev_i32_e32 v121, 31, v120
	v_lshl_add_u64 v[118:119], v[120:121], 1, v[220:221]
	v_cvt_pk_bf16_f32 v204, v222, v223
	v_cvt_pk_bf16_f32 v205, v227, v228
	s_waitcnt lgkmcnt(0)
	v_add_f32_e32 v112, v122, v112
	ds_bpermute_b32 v113, v198, v112
	v_cvt_pk_bf16_f32 v206, v229, v230
	v_cvt_pk_bf16_f32 v207, v231, v232
	global_store_dwordx4 v[118:119], v[204:207], off sc1
	v_cvt_pk_bf16_f32 v114, v123, v126
	v_cvt_pk_bf16_f32 v115, v127, v208
	v_cvt_pk_bf16_f32 v116, v209, v210
	v_cvt_pk_bf16_f32 v117, v211, v212
	global_store_dwordx4 v[118:119], v[114:117], off offset:256 sc1
	s_and_saveexec_b64 s[50:51], vcc
	s_cbranch_execz .LBB0_835
	s_waitcnt lgkmcnt(0)
	v_add_f32_e32 v114, v112, v113
	v_lshl_add_u64 v[112:113], v[190:191], 2, s[42:43]
	global_atomic_add_f32 v[112:113], v114, off
.LBB0_835:
	s_or_b64 exec, exec, s[50:51]
	v_mul_f32_e32 v104, 0xbfb8aa3b, v104
	v_exp_f32_e32 v104, v104
	v_mul_f32_e32 v105, 0xbfb8aa3b, v105
	v_exp_f32_e32 v105, v105
	v_lshlrev_b32_e32 v114, 16, v172
	v_add_f32_e32 v104, 1.0, v104
	v_rcp_f32_e32 v104, v104
	v_and_b32_e32 v115, 0xffff0000, v172
	v_lshlrev_b32_e32 v118, 16, v174
	v_lshlrev_b32_e32 v172, 16, v170
	v_fmac_f32_e32 v118, v104, v172
	v_add_f32_e32 v104, 1.0, v105
	v_mul_f32_e32 v105, 0xbfb8aa3b, v110
	v_mul_f32_e32 v106, 0xbfb8aa3b, v106
	v_rcp_f32_e32 v104, v104
	v_exp_f32_e32 v105, v105
	v_exp_f32_e32 v106, v106
	v_mul_f32_e32 v109, 0xbfb8aa3b, v109
	v_mul_f32_e32 v108, 0xbfb8aa3b, v108
	v_exp_f32_e32 v109, v109
	v_and_b32_e32 v119, 0xffff0000, v174
	v_exp_f32_e32 v108, v108
	v_and_b32_e32 v170, 0xffff0000, v170
	v_fmac_f32_e32 v119, v104, v170
	v_add_f32_e32 v104, 1.0, v105
	v_add_f32_e32 v105, 1.0, v106
	v_mul_f32_e32 v106, 0xbfb8aa3b, v111
	v_exp_f32_e32 v106, v106
	v_add_f32_e32 v109, 1.0, v109
	v_add_f32_e32 v108, 1.0, v108
	v_rcp_f32_e32 v109, v109
	v_mul_f32_e32 v107, 0xbfb8aa3b, v107
	v_rcp_f32_e32 v108, v108
	v_exp_f32_e32 v107, v107
	v_mul_f32_e32 v96, 0xbfb8aa3b, v96
	v_rcp_f32_e32 v104, v104
	v_add_f32_e32 v106, 1.0, v106
	v_exp_f32_e32 v96, v96
	v_and_b32_e32 v127, 0xffff0000, v168
	v_rcp_f32_e32 v106, v106
	v_lshlrev_b32_e32 v126, 16, v168
	v_fmac_f32_e32 v115, v109, v127
	v_lshlrev_b32_e32 v116, 16, v173
	v_lshlrev_b32_e32 v168, 16, v169
	v_fmac_f32_e32 v114, v108, v126
	v_add_f32_e32 v107, 1.0, v107
	v_mul_f32_e32 v108, v115, v115
	v_and_b32_e32 v117, 0xffff0000, v173
	v_and_b32_e32 v169, 0xffff0000, v169
	v_rcp_f32_e32 v107, v107
	v_fmac_f32_e32 v116, v104, v168
	v_fmac_f32_e32 v108, v114, v114
	v_add_f32_e32 v96, 1.0, v96
	v_mul_f32_e32 v97, 0xbfb8aa3b, v97
	v_fmac_f32_e32 v117, v106, v169
	v_fmac_f32_e32 v108, v116, v116
	v_rcp_f32_e32 v96, v96
	v_exp_f32_e32 v97, v97
	v_fmac_f32_e32 v108, v117, v117
	v_and_b32_e32 v123, 0xffff0000, v175
	v_lshlrev_b32_e32 v173, 16, v171
	v_and_b32_e32 v171, 0xffff0000, v171
	v_fmac_f32_e32 v108, v118, v118
	v_fmac_f32_e32 v123, v107, v171
	v_cvt_pk_bf16_f32 v104, v114, v115
	v_cvt_pk_bf16_f32 v106, v118, v119
	v_fmac_f32_e32 v108, v119, v119
	v_lshlrev_b32_e32 v115, 16, v166
	v_lshlrev_b32_e32 v107, 16, v160
	v_and_b32_e32 v119, 0xffff0000, v160
	v_lshlrev_b32_e32 v160, 16, v162
	v_rcp_f32_e32 v105, v105
	v_fmac_f32_e32 v115, v96, v160
	v_add_f32_e32 v96, 1.0, v97
	v_mul_f32_e32 v97, 0xbfb8aa3b, v102
	v_mul_f32_e32 v98, 0xbfb8aa3b, v98
	v_rcp_f32_e32 v96, v96
	v_exp_f32_e32 v97, v97
	v_exp_f32_e32 v98, v98
	v_mul_f32_e32 v100, 0xbfb8aa3b, v100
	v_lshlrev_b32_e32 v122, 16, v175
	v_exp_f32_e32 v100, v100
	v_mul_f32_e32 v101, 0xbfb8aa3b, v101
	v_fmac_f32_e32 v122, v105, v173
	v_cvt_pk_bf16_f32 v105, v116, v117
	v_and_b32_e32 v116, 0xffff0000, v166
	v_lshlrev_b32_e32 v126, 16, v161
	v_and_b32_e32 v127, 0xffff0000, v161
	v_and_b32_e32 v161, 0xffff0000, v162
	v_exp_f32_e32 v101, v101
	v_fmac_f32_e32 v116, v96, v161
	v_add_f32_e32 v96, 1.0, v97
	v_add_f32_e32 v97, 1.0, v98
	v_mul_f32_e32 v98, 0xbfb8aa3b, v103
	v_exp_f32_e32 v98, v98
	v_add_f32_e32 v100, 1.0, v100
	v_rcp_f32_e32 v100, v100
	v_add_f32_e32 v101, 1.0, v101
	v_rcp_f32_e32 v101, v101
	v_mul_f32_e32 v99, 0xbfb8aa3b, v99
	v_rcp_f32_e32 v96, v96
	v_exp_f32_e32 v99, v99
	v_add_f32_e32 v98, 1.0, v98
	v_fmac_f32_e32 v108, v122, v122
	v_lshlrev_b32_e32 v109, 16, v164
	v_rcp_f32_e32 v98, v98
	v_fmac_f32_e32 v108, v123, v123
	v_and_b32_e32 v110, 0xffff0000, v164
	v_fmac_f32_e32 v109, v100, v107
	v_lshlrev_b32_e32 v111, 16, v165
	v_fmac_f32_e32 v110, v101, v119
	v_fmac_f32_e32 v108, v109, v109
	v_and_b32_e32 v114, 0xffff0000, v165
	v_rcp_f32_e32 v97, v97
	v_add_f32_e32 v99, 1.0, v99
	v_fmac_f32_e32 v111, v96, v126
	v_fmac_f32_e32 v108, v110, v110
	v_rcp_f32_e32 v99, v99
	v_fmac_f32_e32 v114, v98, v127
	v_fmac_f32_e32 v108, v111, v111
	v_fmac_f32_e32 v108, v114, v114
	v_lshlrev_b32_e32 v117, 16, v167
	v_lshlrev_b32_e32 v162, 16, v163
	v_fmac_f32_e32 v108, v115, v115
	v_and_b32_e32 v118, 0xffff0000, v167
	v_and_b32_e32 v163, 0xffff0000, v163
	v_fmac_f32_e32 v117, v97, v162
	v_fmac_f32_e32 v108, v116, v116
	v_fmac_f32_e32 v118, v99, v163
	v_fmac_f32_e32 v108, v117, v117
	v_fmac_f32_e32 v108, v118, v118
	ds_bpermute_b32 v96, v197, v108
	s_waitcnt lgkmcnt(1)
; __device__ __forceinline__ unsigned cvt_pk(float lo, float hi) { unsigned r; asm("v_cvt_pk_bf16_f32 %0, %1, %2" : "=v"(r) : "v"(lo), "v"(hi)); return r; }
; __device__ __forceinline__ float fexp2(float x) { return __builtin_amdgcn_exp2f(x); }
; __device__ __forceinline__ float frcp(float x) { return __builtin_amdgcn_rcpf(x); }
;     __device__ __forceinline__ void operator()(AccRef acc, const pg8::Unit& u, int wr, int wc, int, int) const {
;     ...
;                 for (int bj = 0; bj < 2; ++bj) {
;                     const int c0 = u.pn * 256 + bj * 128 + wc * 32 + 8 * fq;
;                     const v4u hw = hwv[m][bj], pw = pwv[m][bj];
;                     const float hh[8] = {bf_lo(hw.x), bf_hi(hw.x), bf_lo(hw.y), bf_hi(hw.y), bf_lo(hw.z), bf_hi(hw.z), bf_lo(hw.w), bf_hi(hw.w)};
;                     const float pp[8] = {bf_lo(pw.x), bf_hi(pw.x), bf_lo(pw.y), bf_hi(pw.y), bf_lo(pw.z), bf_hi(pw.z), bf_lo(pw.w), bf_hi(pw.w)};
;                     float o[8];
; #pragma unroll
;                     for (int j = 0; j < 4; ++j) {
;                         o[j] = hh[j] + pp[j] * frcp(1.0f + fexp2(-acc[ai][bj][m][0][j] * LOG2E));
;                         o[4 + j] = hh[4 + j] + pp[4 + j] * frcp(1.0f + fexp2(-acc[ai][bj][m][1][j] * LOG2E));
;                     }
;                     v4u w; w.x = cvt_pk(o[0], o[1]); w.y = cvt_pk(o[2], o[3]); w.z = cvt_pk(o[4], o[5]); w.w = cvt_pk(o[6], o[7]);
;                     *(v4u*)(XB + (size_t)row * DM + c0) = w;
; #pragma unroll
;                     for (int j = 0; j < 8; ++j) ss += o[j] * o[j];
;                 }
;                 ss += __shfl_xor(ss, 16); ss += __shfl_xor(ss, 32);
;                 if (fq == 0) __hip_atomic_fetch_add(ssq + row, ss, __ATOMIC_RELAXED, __HIP_MEMORY_SCOPE_AGENT);
;             }
	v_lshlrev_b64 v[112:113], 11, v[194:195]
	v_lshl_add_u64 v[112:113], s[48:49], 0, v[112:113]
	v_lshl_add_u64 v[102:103], v[120:121], 1, v[112:113]
	v_cvt_pk_bf16_f32 v107, v122, v123
	s_waitcnt lgkmcnt(0)
	v_add_f32_e32 v96, v108, v96
	ds_bpermute_b32 v97, v198, v96
	global_store_dwordx4 v[102:103], v[104:107], off sc1
	v_cvt_pk_bf16_f32 v98, v109, v110
	v_cvt_pk_bf16_f32 v99, v111, v114
	v_cvt_pk_bf16_f32 v100, v115, v116
	v_cvt_pk_bf16_f32 v101, v117, v118
	global_store_dwordx4 v[102:103], v[98:101], off offset:256 sc1
	s_and_saveexec_b64 s[50:51], vcc
	s_cbranch_execz .LBB0_837
	s_waitcnt lgkmcnt(0)
	v_add_f32_e32 v98, v96, v97
	v_lshl_add_u64 v[96:97], v[194:195], 2, s[42:43]
	global_atomic_add_f32 v[96:97], v98, off
.LBB0_837:
	s_or_b64 exec, exec, s[50:51]
	v_mul_f32_e32 v88, 0xbfb8aa3b, v88
	v_exp_f32_e32 v88, v88
	v_mul_f32_e32 v89, 0xbfb8aa3b, v89
	v_exp_f32_e32 v89, v89
	v_lshlrev_b32_e32 v102, 16, v158
	v_add_f32_e32 v88, 1.0, v88
	v_rcp_f32_e32 v88, v88
	v_lshlrev_b32_e32 v110, 16, v154
	v_mul_f32_e32 v93, 0xbfb8aa3b, v93
	v_mul_f32_e32 v92, 0xbfb8aa3b, v92
	v_exp_f32_e32 v93, v93
	v_fmac_f32_e32 v102, v88, v110
	v_add_f32_e32 v88, 1.0, v89
	v_mul_f32_e32 v89, 0xbfb8aa3b, v94
	v_mul_f32_e32 v90, 0xbfb8aa3b, v90
	v_exp_f32_e32 v92, v92
	v_rcp_f32_e32 v88, v88
	v_exp_f32_e32 v89, v89
	v_exp_f32_e32 v90, v90
	v_mul_f32_e32 v80, 0xbfb8aa3b, v80
	v_exp_f32_e32 v80, v80
	v_and_b32_e32 v103, 0xffff0000, v158
	v_and_b32_e32 v111, 0xffff0000, v154
	v_add_f32_e32 v93, 1.0, v93
	v_add_f32_e32 v92, 1.0, v92
	v_rcp_f32_e32 v93, v93
	v_fmac_f32_e32 v103, v88, v111
	v_add_f32_e32 v88, 1.0, v89
	v_add_f32_e32 v89, 1.0, v90
	v_mul_f32_e32 v90, 0xbfb8aa3b, v95
	v_rcp_f32_e32 v92, v92
	v_rcp_f32_e32 v88, v88
	v_exp_f32_e32 v90, v90
	v_add_f32_e32 v80, 1.0, v80
	v_mul_f32_e32 v81, 0xbfb8aa3b, v81
	v_rcp_f32_e32 v80, v80
	v_exp_f32_e32 v81, v81
	v_and_b32_e32 v99, 0xffff0000, v156
	v_and_b32_e32 v107, 0xffff0000, v152
	v_lshlrev_b32_e32 v98, 16, v156
	v_lshlrev_b32_e32 v100, 16, v157
	v_lshlrev_b32_e32 v106, 16, v152
	v_lshlrev_b32_e32 v108, 16, v153
	v_fmac_f32_e32 v99, v93, v107
	v_fmac_f32_e32 v98, v92, v106
	v_add_f32_e32 v90, 1.0, v90
	v_fmac_f32_e32 v100, v88, v108
	v_cvt_pk_bf16_f32 v88, v98, v99
	v_mul_f32_e32 v92, v99, v99
	v_lshlrev_b32_e32 v99, 16, v150
	v_lshlrev_b32_e32 v108, 16, v146
	v_rcp_f32_e32 v89, v89
	v_rcp_f32_e32 v90, v90
	v_fmac_f32_e32 v99, v80, v108
	v_add_f32_e32 v80, 1.0, v81
	v_mul_f32_e32 v81, 0xbfb8aa3b, v86
	v_mul_f32_e32 v82, 0xbfb8aa3b, v82
	v_mul_f32_e32 v91, 0xbfb8aa3b, v91
	v_rcp_f32_e32 v80, v80
	v_exp_f32_e32 v81, v81
	v_exp_f32_e32 v82, v82
	v_exp_f32_e32 v91, v91
	v_mul_f32_e32 v84, 0xbfb8aa3b, v84
	v_and_b32_e32 v101, 0xffff0000, v157
	v_lshlrev_b32_e32 v104, 16, v159
	v_and_b32_e32 v109, 0xffff0000, v153
	v_lshlrev_b32_e32 v112, 16, v155
	v_fmac_f32_e32 v92, v98, v98
	v_exp_f32_e32 v84, v84
	v_mul_f32_e32 v85, 0xbfb8aa3b, v85
	v_fmac_f32_e32 v104, v89, v112
	v_fmac_f32_e32 v101, v90, v109
	v_cvt_pk_bf16_f32 v89, v100, v101
	v_fmac_f32_e32 v92, v100, v100
	v_and_b32_e32 v100, 0xffff0000, v150
	v_and_b32_e32 v109, 0xffff0000, v146
	v_exp_f32_e32 v85, v85
	v_fmac_f32_e32 v100, v80, v109
	v_add_f32_e32 v80, 1.0, v81
	v_add_f32_e32 v81, 1.0, v82
	v_mul_f32_e32 v82, 0xbfb8aa3b, v87
	v_add_f32_e32 v91, 1.0, v91
	v_exp_f32_e32 v82, v82
	v_rcp_f32_e32 v91, v91
	v_add_f32_e32 v84, 1.0, v84
	v_fmac_f32_e32 v92, v101, v101
	v_rcp_f32_e32 v84, v84
	v_add_f32_e32 v85, 1.0, v85
	v_fmac_f32_e32 v92, v102, v102
	v_rcp_f32_e32 v85, v85
	v_mul_f32_e32 v83, 0xbfb8aa3b, v83
	v_and_b32_e32 v105, 0xffff0000, v159
	v_and_b32_e32 v113, 0xffff0000, v155
	v_fmac_f32_e32 v92, v103, v103
	v_rcp_f32_e32 v80, v80
	v_exp_f32_e32 v83, v83
	v_add_f32_e32 v82, 1.0, v82
	v_fmac_f32_e32 v105, v91, v113
	v_fmac_f32_e32 v92, v104, v104
	v_lshlrev_b32_e32 v93, 16, v148
	v_lshlrev_b32_e32 v91, 16, v144
	v_rcp_f32_e32 v82, v82
	v_cvt_pk_bf16_f32 v90, v102, v103
	v_fmac_f32_e32 v92, v105, v105
	v_and_b32_e32 v94, 0xffff0000, v148
	v_and_b32_e32 v103, 0xffff0000, v144
	v_fmac_f32_e32 v93, v84, v91
	v_lshlrev_b32_e32 v95, 16, v149
	v_lshlrev_b32_e32 v106, 16, v145
	v_fmac_f32_e32 v94, v85, v103
	v_fmac_f32_e32 v92, v93, v93
	v_and_b32_e32 v98, 0xffff0000, v149
	v_and_b32_e32 v107, 0xffff0000, v145
	v_rcp_f32_e32 v81, v81
	v_add_f32_e32 v83, 1.0, v83
	v_fmac_f32_e32 v95, v80, v106
	v_fmac_f32_e32 v92, v94, v94
	v_rcp_f32_e32 v83, v83
	v_fmac_f32_e32 v98, v82, v107
	v_fmac_f32_e32 v92, v95, v95
	v_fmac_f32_e32 v92, v98, v98
	v_lshlrev_b32_e32 v101, 16, v151
	v_lshlrev_b32_e32 v110, 16, v147
	v_fmac_f32_e32 v92, v99, v99
	v_and_b32_e32 v102, 0xffff0000, v151
	v_and_b32_e32 v111, 0xffff0000, v147
	v_fmac_f32_e32 v101, v81, v110
	v_fmac_f32_e32 v92, v100, v100
	v_fmac_f32_e32 v102, v83, v111
	v_fmac_f32_e32 v92, v101, v101
	v_fmac_f32_e32 v92, v102, v102
	ds_bpermute_b32 v80, v197, v92
	s_waitcnt lgkmcnt(1)
	v_lshlrev_b64 v[96:97], 11, v[192:193]
	v_lshl_add_u64 v[96:97], s[48:49], 0, v[96:97]
	v_lshl_add_u64 v[86:87], v[120:121], 1, v[96:97]
	v_cvt_pk_bf16_f32 v91, v104, v105
	s_waitcnt lgkmcnt(0)
	v_add_f32_e32 v80, v92, v80
	ds_bpermute_b32 v81, v198, v80
	global_store_dwordx4 v[86:87], v[88:91], off sc1
	v_cvt_pk_bf16_f32 v82, v93, v94
	v_cvt_pk_bf16_f32 v83, v95, v98
	v_cvt_pk_bf16_f32 v84, v99, v100
	v_cvt_pk_bf16_f32 v85, v101, v102
	global_store_dwordx4 v[86:87], v[82:85], off offset:256 sc1
	s_and_saveexec_b64 s[50:51], vcc
	s_cbranch_execz .LBB0_839
	s_waitcnt lgkmcnt(0)
	v_add_f32_e32 v82, v80, v81
	v_lshl_add_u64 v[80:81], v[192:193], 2, s[42:43]
	global_atomic_add_f32 v[80:81], v82, off
; __device__ __forceinline__ unsigned cvt_pk(float lo, float hi) { unsigned r; asm("v_cvt_pk_bf16_f32 %0, %1, %2" : "=v"(r) : "v"(lo), "v"(hi)); return r; }
; __device__ __forceinline__ float fexp2(float x) { return __builtin_amdgcn_exp2f(x); }
; __device__ __forceinline__ float frcp(float x) { return __builtin_amdgcn_rcpf(x); }
;     __device__ __forceinline__ void operator()(AccRef acc, const pg8::Unit& u, int wr, int wc, int, int) const {
;     ...
;                 for (int bj = 0; bj < 2; ++bj) {
;                     const int c0 = u.pn * 256 + bj * 128 + wc * 32 + 8 * fq;
;                     const v4u hw = hwv[m][bj], pw = pwv[m][bj];
;                     const float hh[8] = {bf_lo(hw.x), bf_hi(hw.x), bf_lo(hw.y), bf_hi(hw.y), bf_lo(hw.z), bf_hi(hw.z), bf_lo(hw.w), bf_hi(hw.w)};
;                     const float pp[8] = {bf_lo(pw.x), bf_hi(pw.x), bf_lo(pw.y), bf_hi(pw.y), bf_lo(pw.z), bf_hi(pw.z), bf_lo(pw.w), bf_hi(pw.w)};
;                     float o[8];
; #pragma unroll
;                     for (int j = 0; j < 4; ++j) {
;                         o[j] = hh[j] + pp[j] * frcp(1.0f + fexp2(-acc[ai][bj][m][0][j] * LOG2E));
;                         o[4 + j] = hh[4 + j] + pp[4 + j] * frcp(1.0f + fexp2(-acc[ai][bj][m][1][j] * LOG2E));
;                     }
;                     v4u w; w.x = cvt_pk(o[0], o[1]); w.y = cvt_pk(o[2], o[3]); w.z = cvt_pk(o[4], o[5]); w.w = cvt_pk(o[6], o[7]);
;                     *(v4u*)(XB + (size_t)row * DM + c0) = w;
; #pragma unroll
;                     for (int j = 0; j < 8; ++j) ss += o[j] * o[j];
;                 }
;                 ss += __shfl_xor(ss, 16); ss += __shfl_xor(ss, 32);
;                 if (fq == 0) __hip_atomic_fetch_add(ssq + row, ss, __ATOMIC_RELAXED, __HIP_MEMORY_SCOPE_AGENT);
;             }
.LBB0_839:
	s_or_b64 exec, exec, s[50:51]
	v_mul_f32_e32 v72, 0xbfb8aa3b, v72
	v_exp_f32_e32 v72, v72
	v_mul_f32_e32 v73, 0xbfb8aa3b, v73
	v_exp_f32_e32 v73, v73
	v_lshlrev_b32_e32 v86, 16, v142
	v_add_f32_e32 v72, 1.0, v72
	v_rcp_f32_e32 v72, v72
	v_lshlrev_b32_e32 v94, 16, v138
	v_mul_f32_e32 v77, 0xbfb8aa3b, v77
	v_mul_f32_e32 v76, 0xbfb8aa3b, v76
	v_exp_f32_e32 v77, v77
	v_fmac_f32_e32 v86, v72, v94
	v_add_f32_e32 v72, 1.0, v73
	v_mul_f32_e32 v73, 0xbfb8aa3b, v78
	v_mul_f32_e32 v74, 0xbfb8aa3b, v74
	v_exp_f32_e32 v76, v76
	v_rcp_f32_e32 v72, v72
	v_exp_f32_e32 v73, v73
	v_exp_f32_e32 v74, v74
	v_mul_f32_e32 v64, 0xbfb8aa3b, v64
	v_exp_f32_e32 v64, v64
	v_and_b32_e32 v87, 0xffff0000, v142
	v_and_b32_e32 v95, 0xffff0000, v138
	v_add_f32_e32 v77, 1.0, v77
	v_add_f32_e32 v76, 1.0, v76
	v_rcp_f32_e32 v77, v77
	v_fmac_f32_e32 v87, v72, v95
	v_add_f32_e32 v72, 1.0, v73
	v_add_f32_e32 v73, 1.0, v74
	v_mul_f32_e32 v74, 0xbfb8aa3b, v79
	v_rcp_f32_e32 v76, v76
	v_rcp_f32_e32 v72, v72
	v_exp_f32_e32 v74, v74
	v_add_f32_e32 v64, 1.0, v64
	v_mul_f32_e32 v65, 0xbfb8aa3b, v65
	v_rcp_f32_e32 v64, v64
	v_exp_f32_e32 v65, v65
	v_and_b32_e32 v83, 0xffff0000, v140
	v_and_b32_e32 v91, 0xffff0000, v136
	v_lshlrev_b32_e32 v82, 16, v140
	v_lshlrev_b32_e32 v84, 16, v141
	v_lshlrev_b32_e32 v90, 16, v136
	v_lshlrev_b32_e32 v92, 16, v137
	v_fmac_f32_e32 v83, v77, v91
	v_fmac_f32_e32 v82, v76, v90
	v_add_f32_e32 v74, 1.0, v74
	v_fmac_f32_e32 v84, v72, v92
	v_cvt_pk_bf16_f32 v72, v82, v83
	v_mul_f32_e32 v76, v83, v83
	v_lshlrev_b32_e32 v83, 16, v134
	v_lshlrev_b32_e32 v92, 16, v130
	v_rcp_f32_e32 v73, v73
	v_rcp_f32_e32 v74, v74
	v_fmac_f32_e32 v83, v64, v92
	v_add_f32_e32 v64, 1.0, v65
	v_mul_f32_e32 v65, 0xbfb8aa3b, v70
	v_mul_f32_e32 v66, 0xbfb8aa3b, v66
	v_mul_f32_e32 v75, 0xbfb8aa3b, v75
	v_rcp_f32_e32 v64, v64
	v_exp_f32_e32 v65, v65
	v_exp_f32_e32 v66, v66
	v_exp_f32_e32 v75, v75
	v_mul_f32_e32 v68, 0xbfb8aa3b, v68
	v_and_b32_e32 v85, 0xffff0000, v141
	v_lshlrev_b32_e32 v88, 16, v143
	v_and_b32_e32 v93, 0xffff0000, v137
	v_lshlrev_b32_e32 v96, 16, v139
	v_fmac_f32_e32 v76, v82, v82
	v_exp_f32_e32 v68, v68
	v_mul_f32_e32 v69, 0xbfb8aa3b, v69
	v_fmac_f32_e32 v88, v73, v96
	v_fmac_f32_e32 v85, v74, v93
	v_cvt_pk_bf16_f32 v73, v84, v85
	v_fmac_f32_e32 v76, v84, v84
	v_and_b32_e32 v84, 0xffff0000, v134
	v_and_b32_e32 v93, 0xffff0000, v130
	v_exp_f32_e32 v69, v69
	v_fmac_f32_e32 v84, v64, v93
	v_add_f32_e32 v64, 1.0, v65
	v_add_f32_e32 v65, 1.0, v66
	v_mul_f32_e32 v66, 0xbfb8aa3b, v71
	v_add_f32_e32 v75, 1.0, v75
	v_exp_f32_e32 v66, v66
	v_rcp_f32_e32 v75, v75
	v_add_f32_e32 v68, 1.0, v68
	v_fmac_f32_e32 v76, v85, v85
	v_rcp_f32_e32 v68, v68
	v_add_f32_e32 v69, 1.0, v69
	v_fmac_f32_e32 v76, v86, v86
	v_rcp_f32_e32 v69, v69
	v_mul_f32_e32 v67, 0xbfb8aa3b, v67
	v_and_b32_e32 v89, 0xffff0000, v143
	v_and_b32_e32 v97, 0xffff0000, v139
	v_fmac_f32_e32 v76, v87, v87
	v_rcp_f32_e32 v64, v64
	v_exp_f32_e32 v67, v67
	v_add_f32_e32 v66, 1.0, v66
	v_fmac_f32_e32 v89, v75, v97
	v_fmac_f32_e32 v76, v88, v88
	v_lshlrev_b32_e32 v77, 16, v132
	v_lshlrev_b32_e32 v75, 16, v128
	v_rcp_f32_e32 v66, v66
	v_cvt_pk_bf16_f32 v74, v86, v87
	v_fmac_f32_e32 v76, v89, v89
	v_and_b32_e32 v78, 0xffff0000, v132
	v_and_b32_e32 v87, 0xffff0000, v128
	v_fmac_f32_e32 v77, v68, v75
	v_lshlrev_b32_e32 v79, 16, v133
	v_lshlrev_b32_e32 v90, 16, v129
	v_fmac_f32_e32 v78, v69, v87
	v_fmac_f32_e32 v76, v77, v77
	v_and_b32_e32 v82, 0xffff0000, v133
	v_and_b32_e32 v91, 0xffff0000, v129
	v_rcp_f32_e32 v65, v65
	v_add_f32_e32 v67, 1.0, v67
	v_fmac_f32_e32 v79, v64, v90
	v_fmac_f32_e32 v76, v78, v78
	v_rcp_f32_e32 v67, v67
	v_fmac_f32_e32 v82, v66, v91
	v_fmac_f32_e32 v76, v79, v79
	v_fmac_f32_e32 v76, v82, v82
	v_lshlrev_b32_e32 v85, 16, v135
	v_lshlrev_b32_e32 v94, 16, v131
	v_fmac_f32_e32 v76, v83, v83
	v_and_b32_e32 v86, 0xffff0000, v135
	v_and_b32_e32 v95, 0xffff0000, v131
	v_fmac_f32_e32 v85, v65, v94
	v_fmac_f32_e32 v76, v84, v84
	v_fmac_f32_e32 v86, v67, v95
	v_fmac_f32_e32 v76, v85, v85
	v_fmac_f32_e32 v76, v86, v86
	ds_bpermute_b32 v64, v197, v76
	s_waitcnt lgkmcnt(1)
	v_lshlrev_b64 v[80:81], 11, v[124:125]
	v_lshl_add_u64 v[80:81], s[48:49], 0, v[80:81]
	v_lshl_add_u64 v[70:71], v[120:121], 1, v[80:81]
	v_cvt_pk_bf16_f32 v75, v88, v89
	s_waitcnt lgkmcnt(0)
	v_add_f32_e32 v64, v76, v64
	ds_bpermute_b32 v65, v198, v64
	global_store_dwordx4 v[70:71], v[72:75], off sc1
	v_cvt_pk_bf16_f32 v66, v77, v78
	v_cvt_pk_bf16_f32 v67, v79, v82
	v_cvt_pk_bf16_f32 v68, v83, v84
	v_cvt_pk_bf16_f32 v69, v85, v86
	global_store_dwordx4 v[70:71], v[66:69], off offset:256 sc1
	s_and_saveexec_b64 s[50:51], vcc
	s_cbranch_execz .LBB0_841
	s_waitcnt lgkmcnt(0)
	v_add_f32_e32 v66, v64, v65
	v_lshl_add_u64 v[64:65], v[124:125], 2, s[42:43]
	global_atomic_add_f32 v[64:65], v66, off
; __device__ __forceinline__ unsigned cvt_pk(float lo, float hi) { unsigned r; asm("v_cvt_pk_bf16_f32 %0, %1, %2" : "=v"(r) : "v"(lo), "v"(hi)); return r; }
; __device__ __forceinline__ float fexp2(float x) { return __builtin_amdgcn_exp2f(x); }
;     __device__ __forceinline__ void operator()(AccRef acc, const pg8::Unit& u, int wr, int wc, int, int) const {
;     ...
;         for (int ai = 0; ai < 2; ++ai) {
;             v4u hwv[4][2], pwv[4][2];
; #pragma unroll
;             for (int m = 0; m < 4; ++m) { const int row = u.pm * 256 + ai * 128 + wr * 64 + m * 16 + fr;
; #pragma unroll
;                 for (int bj = 0; bj < 2; ++bj) { const size_t off = (size_t)row * DM + u.pn * 256 + bj * 128 + wc * 32 + 8 * fq; hwv[m][bj] = *(const v4u*)(HB + off); pwv[m][bj] = *(const v4u*)(XB + off); } }
;             asm volatile("" ::: "memory");
; #pragma unroll
;             for (int m = 0; m < 4; ++m) {
;                 const int row = u.pm * 256 + ai * 128 + wr * 64 + m * 16 + fr;
;                 float ss = 0.f;
; #pragma unroll
;                 for (int bj = 0; bj < 2; ++bj) {
;                     const int c0 = u.pn * 256 + bj * 128 + wc * 32 + 8 * fq;
;                     const v4u hw = hwv[m][bj], pw = pwv[m][bj];
;                     const float hh[8] = {bf_lo(hw.x), bf_hi(hw.x), bf_lo(hw.y), bf_hi(hw.y), bf_lo(hw.z), bf_hi(hw.z), bf_lo(hw.w), bf_hi(hw.w)};
;                     const float pp[8] = {bf_lo(pw.x), bf_hi(pw.x), bf_lo(pw.y), bf_hi(pw.y), bf_lo(pw.z), bf_hi(pw.z), bf_lo(pw.w), bf_hi(pw.w)};
;                     float o[8];
; #pragma unroll
;                     for (int j = 0; j < 4; ++j) {
;                         o[j] = hh[j] + pp[j] * frcp(1.0f + fexp2(-acc[ai][bj][m][0][j] * LOG2E));
;                         o[4 + j] = hh[4 + j] + pp[4 + j] * frcp(1.0f + fexp2(-acc[ai][bj][m][1][j] * LOG2E));
;                     }
;                     v4u w; w.x = cvt_pk(o[0], o[1]); w.y = cvt_pk(o[2], o[3]); w.z = cvt_pk(o[4], o[5]); w.w = cvt_pk(o[6], o[7]);
;                     *(v4u*)(XB + (size_t)row * DM + c0) = w;
; #pragma unroll
;                     for (int j = 0; j < 8; ++j) ss += o[j] * o[j];
;                 }
;                 ss += __shfl_xor(ss, 16); ss += __shfl_xor(ss, 32);
;                 if (fq == 0) __hip_atomic_fetch_add(ssq + row, ss, __ATOMIC_RELAXED, __HIP_MEMORY_SCOPE_AGENT);
;             }
.LBB0_841:
	s_or_b64 exec, exec, s[50:51]
	v_add_u32_e32 v118, 0x80, v190
	v_ashrrev_i32_e32 v119, 31, v118
	s_waitcnt lgkmcnt(0)
	v_lshlrev_b64 v[64:65], 10, v[118:119]
	v_lshl_add_u64 v[64:65], v[64:65], 0, v[188:189]
	v_lshlrev_b64 v[64:65], 1, v[64:65]
	v_lshl_add_u64 v[66:67], s[54:55], 0, v[64:65]
	v_lshl_add_u64 v[64:65], s[48:49], 0, v[64:65]
	global_load_dwordx4 v[122:125], v[66:67], off
	global_load_dwordx4 v[130:133], v[66:67], off offset:256
	global_load_dwordx4 v[126:129], v[64:65], off
	global_load_dwordx4 v[134:137], v[64:65], off offset:256
	v_add_u32_e32 v116, 0x90, v190
	v_add_u32_e32 v114, 0xa0, v190
	v_add_u32_e32 v112, 0xb0, v190
	v_mul_f32_e32 v60, 0xbfb8aa3b, v60
	v_mul_f32_e32 v56, 0xbfb8aa3b, v56
	v_mul_f32_e32 v61, 0xbfb8aa3b, v61
	v_mul_f32_e32 v57, 0xbfb8aa3b, v57
	v_ashrrev_i32_e32 v117, 31, v116
	v_ashrrev_i32_e32 v115, 31, v114
	v_ashrrev_i32_e32 v113, 31, v112
	v_exp_f32_e32 v72, v60
	v_exp_f32_e32 v73, v56
	v_exp_f32_e32 v74, v61
	v_exp_f32_e32 v75, v57
	v_lshlrev_b64 v[56:57], 10, v[116:117]
	v_lshlrev_b64 v[60:61], 10, v[114:115]
	v_lshlrev_b64 v[68:69], 10, v[112:113]
	v_lshl_add_u64 v[56:57], v[56:57], 0, v[188:189]
	v_lshl_add_u64 v[60:61], v[60:61], 0, v[188:189]
	v_lshl_add_u64 v[68:69], v[68:69], 0, v[188:189]
	v_lshlrev_b64 v[70:71], 11, v[118:119]
	v_lshlrev_b64 v[56:57], 1, v[56:57]
	v_lshlrev_b64 v[60:61], 1, v[60:61]
	v_lshlrev_b64 v[66:67], 1, v[68:69]
	v_lshl_add_u64 v[138:139], s[48:49], 0, v[70:71]
	v_lshl_add_u64 v[68:69], s[54:55], 0, v[56:57]
	v_lshl_add_u64 v[70:71], s[54:55], 0, v[60:61]
	v_lshl_add_u64 v[64:65], s[54:55], 0, v[66:67]
	v_lshl_add_u64 v[66:67], s[48:49], 0, v[66:67]
	v_lshl_add_u64 v[56:57], s[48:49], 0, v[56:57]
	v_lshl_add_u64 v[60:61], s[48:49], 0, v[60:61]
	v_add_f32_e32 v140, 1.0, v72
	v_add_f32_e32 v141, 1.0, v73
	v_add_f32_e32 v142, 1.0, v74
	v_add_f32_e32 v143, 1.0, v75
	global_load_dwordx4 v[108:111], v[68:69], off
	global_load_dwordx4 v[100:103], v[68:69], off offset:256
	global_load_dwordx4 v[104:107], v[56:57], off
	global_load_dwordx4 v[96:99], v[56:57], off offset:256
	global_load_dwordx4 v[92:95], v[70:71], off
	global_load_dwordx4 v[84:87], v[70:71], off offset:256
	global_load_dwordx4 v[88:91], v[60:61], off
	global_load_dwordx4 v[80:83], v[60:61], off offset:256
	global_load_dwordx4 v[76:79], v[64:65], off
	s_nop 0
	global_load_dwordx4 v[68:71], v[64:65], off offset:256
	global_load_dwordx4 v[72:75], v[66:67], off
	s_nop 0
	global_load_dwordx4 v[64:67], v[66:67], off offset:256
	v_mul_f32_e32 v58, 0xbfb8aa3b, v58
	v_exp_f32_e32 v58, v58
	v_rcp_f32_e32 v57, v141
	v_mul_f32_e32 v62, 0xbfb8aa3b, v62
	v_rcp_f32_e32 v60, v142
	v_exp_f32_e32 v62, v62
	v_rcp_f32_e32 v56, v140
	v_mul_f32_e32 v48, 0xbfb8aa3b, v48
	v_exp_f32_e32 v48, v48
	v_add_f32_e32 v62, 1.0, v62
	v_mul_f32_e32 v49, 0xbfb8aa3b, v49
	v_exp_f32_e32 v49, v49
	v_add_f32_e32 v48, 1.0, v48
	v_rcp_f32_e32 v48, v48
	v_rcp_f32_e32 v61, v143
	v_mul_f32_e32 v50, 0xbfb8aa3b, v50
	v_mul_f32_e32 v59, 0xbfb8aa3b, v59
	v_exp_f32_e32 v50, v50
	v_exp_f32_e32 v59, v59
	v_mul_f32_e32 v52, 0xbfb8aa3b, v52
	v_exp_f32_e32 v52, v52
	v_mul_f32_e32 v53, 0xbfb8aa3b, v53
	v_exp_f32_e32 v53, v53
	v_add_f32_e32 v59, 1.0, v59
	v_rcp_f32_e32 v59, v59
	v_add_f32_e32 v52, 1.0, v52
	v_rcp_f32_e32 v52, v52
	v_add_f32_e32 v53, 1.0, v53
	v_rcp_f32_e32 v53, v53
	v_mul_f32_e32 v51, 0xbfb8aa3b, v51
	v_exp_f32_e32 v51, v51
	s_waitcnt vmcnt(15)
	v_lshlrev_b32_e32 v142, 16, v124
	v_lshlrev_b32_e32 v140, 16, v122
	s_waitcnt vmcnt(13)
	v_lshlrev_b32_e32 v146, 16, v128
	v_fmac_f32_e32 v142, v57, v146
	v_add_f32_e32 v57, 1.0, v58
	v_mul_f32_e32 v58, 0xbfb8aa3b, v63
	v_exp_f32_e32 v58, v58
	v_lshlrev_b32_e32 v144, 16, v126
	v_fmac_f32_e32 v140, v56, v144
	v_rcp_f32_e32 v56, v62
	v_add_f32_e32 v58, 1.0, v58
	v_and_b32_e32 v122, 0xffff0000, v122
	v_and_b32_e32 v126, 0xffff0000, v126
	v_rcp_f32_e32 v58, v58
	v_fmac_f32_e32 v122, v60, v126
	v_rcp_f32_e32 v57, v57
	v_lshlrev_b32_e32 v141, 16, v123
	v_lshlrev_b32_e32 v145, 16, v127
	v_mul_f32_e32 v60, v122, v122
	v_and_b32_e32 v123, 0xffff0000, v123
	v_and_b32_e32 v127, 0xffff0000, v127
	v_fmac_f32_e32 v141, v56, v145
	v_fmac_f32_e32 v60, v140, v140
	v_lshlrev_b32_e32 v143, 16, v125
	v_lshlrev_b32_e32 v147, 16, v129
	v_fmac_f32_e32 v123, v58, v127
	v_fmac_f32_e32 v60, v141, v141
	v_fmac_f32_e32 v143, v57, v147
	v_cvt_pk_bf16_f32 v56, v140, v122
	v_cvt_pk_bf16_f32 v57, v141, v123
	v_fmac_f32_e32 v60, v123, v123
	v_lshlrev_b32_e32 v63, 16, v131
	v_and_b32_e32 v122, 0xffff0000, v131
	v_lshlrev_b32_e32 v123, 16, v132
	s_waitcnt vmcnt(12)
	v_lshlrev_b32_e32 v131, 16, v136
	v_fmac_f32_e32 v123, v48, v131
	v_add_f32_e32 v48, 1.0, v49
	v_mul_f32_e32 v49, 0xbfb8aa3b, v54
	v_rcp_f32_e32 v48, v48
	v_exp_f32_e32 v49, v49
	v_and_b32_e32 v124, 0xffff0000, v124
	v_and_b32_e32 v128, 0xffff0000, v128
	v_fmac_f32_e32 v124, v61, v128
	v_fmac_f32_e32 v60, v142, v142
	v_cvt_pk_bf16_f32 v58, v142, v124
	v_fmac_f32_e32 v60, v124, v124
	v_and_b32_e32 v124, 0xffff0000, v132
	v_and_b32_e32 v132, 0xffff0000, v136
	v_fmac_f32_e32 v124, v48, v132
	v_add_f32_e32 v48, 1.0, v49
	v_add_f32_e32 v49, 1.0, v50
	v_mul_f32_e32 v50, 0xbfb8aa3b, v55
	v_exp_f32_e32 v50, v50
	v_and_b32_e32 v125, 0xffff0000, v125
	v_and_b32_e32 v129, 0xffff0000, v129
	v_rcp_f32_e32 v48, v48
	v_add_f32_e32 v50, 1.0, v50
	v_fmac_f32_e32 v125, v59, v129
	v_fmac_f32_e32 v60, v143, v143
	v_lshlrev_b32_e32 v61, 16, v130
	v_lshlrev_b32_e32 v59, 16, v134
	v_rcp_f32_e32 v50, v50
	v_fmac_f32_e32 v60, v125, v125
	v_and_b32_e32 v62, 0xffff0000, v130
	v_and_b32_e32 v128, 0xffff0000, v134
	v_fmac_f32_e32 v61, v52, v59
	v_lshlrev_b32_e32 v129, 16, v135
	v_fmac_f32_e32 v62, v53, v128
	v_fmac_f32_e32 v60, v61, v61
	v_and_b32_e32 v130, 0xffff0000, v135
	v_rcp_f32_e32 v49, v49
	v_add_f32_e32 v51, 1.0, v51
	v_fmac_f32_e32 v63, v48, v129
	v_fmac_f32_e32 v60, v62, v62
	v_rcp_f32_e32 v51, v51
	v_fmac_f32_e32 v122, v50, v130
	v_fmac_f32_e32 v60, v63, v63
	v_fmac_f32_e32 v60, v122, v122
	v_lshlrev_b32_e32 v126, 16, v133
	v_and_b32_e32 v127, 0xffff0000, v133
	v_lshlrev_b32_e32 v133, 16, v137
	v_fmac_f32_e32 v60, v123, v123
	v_and_b32_e32 v134, 0xffff0000, v137
	v_fmac_f32_e32 v126, v49, v133
	v_fmac_f32_e32 v60, v124, v124
	v_fmac_f32_e32 v127, v51, v134
	v_fmac_f32_e32 v60, v126, v126
	v_fmac_f32_e32 v60, v127, v127
	ds_bpermute_b32 v48, v197, v60
	v_lshl_add_u64 v[54:55], v[120:121], 1, v[138:139]
	v_cvt_pk_bf16_f32 v59, v143, v125
	global_store_dwordx4 v[54:55], v[56:59], off sc1
	v_cvt_pk_bf16_f32 v50, v61, v62
	s_waitcnt lgkmcnt(0)
	v_add_f32_e32 v48, v60, v48
	ds_bpermute_b32 v49, v198, v48
	v_cvt_pk_bf16_f32 v51, v63, v122
	v_cvt_pk_bf16_f32 v52, v123, v124
	v_cvt_pk_bf16_f32 v53, v126, v127
	global_store_dwordx4 v[54:55], v[50:53], off offset:256 sc1
	s_and_saveexec_b64 s[50:51], vcc
	s_cbranch_execz .LBB0_843
	s_waitcnt lgkmcnt(0)
	v_add_f32_e32 v50, v48, v49
	v_lshl_add_u64 v[48:49], v[118:119], 2, s[42:43]
	global_atomic_add_f32 v[48:49], v50, off
; __device__ __forceinline__ unsigned cvt_pk(float lo, float hi) { unsigned r; asm("v_cvt_pk_bf16_f32 %0, %1, %2" : "=v"(r) : "v"(lo), "v"(hi)); return r; }
; __device__ __forceinline__ float fexp2(float x) { return __builtin_amdgcn_exp2f(x); }
; __device__ __forceinline__ float frcp(float x) { return __builtin_amdgcn_rcpf(x); }
;     __device__ __forceinline__ void operator()(AccRef acc, const pg8::Unit& u, int wr, int wc, int, int) const {
;     ...
;                 for (int bj = 0; bj < 2; ++bj) {
;                     const int c0 = u.pn * 256 + bj * 128 + wc * 32 + 8 * fq;
;                     const v4u hw = hwv[m][bj], pw = pwv[m][bj];
;                     const float hh[8] = {bf_lo(hw.x), bf_hi(hw.x), bf_lo(hw.y), bf_hi(hw.y), bf_lo(hw.z), bf_hi(hw.z), bf_lo(hw.w), bf_hi(hw.w)};
;                     const float pp[8] = {bf_lo(pw.x), bf_hi(pw.x), bf_lo(pw.y), bf_hi(pw.y), bf_lo(pw.z), bf_hi(pw.z), bf_lo(pw.w), bf_hi(pw.w)};
;                     float o[8];
; #pragma unroll
;                     for (int j = 0; j < 4; ++j) {
;                         o[j] = hh[j] + pp[j] * frcp(1.0f + fexp2(-acc[ai][bj][m][0][j] * LOG2E));
;                         o[4 + j] = hh[4 + j] + pp[4 + j] * frcp(1.0f + fexp2(-acc[ai][bj][m][1][j] * LOG2E));
;                     }
;                     v4u w; w.x = cvt_pk(o[0], o[1]); w.y = cvt_pk(o[2], o[3]); w.z = cvt_pk(o[4], o[5]); w.w = cvt_pk(o[6], o[7]);
;                     *(v4u*)(XB + (size_t)row * DM + c0) = w;
; #pragma unroll
;                     for (int j = 0; j < 8; ++j) ss += o[j] * o[j];
;                 }
;                 ss += __shfl_xor(ss, 16); ss += __shfl_xor(ss, 32);
;                 if (fq == 0) __hip_atomic_fetch_add(ssq + row, ss, __ATOMIC_RELAXED, __HIP_MEMORY_SCOPE_AGENT);
;             }
.LBB0_843:
	s_or_b64 exec, exec, s[50:51]
	v_mul_f32_e32 v40, 0xbfb8aa3b, v40
	v_exp_f32_e32 v40, v40
	v_mul_f32_e32 v41, 0xbfb8aa3b, v41
	v_exp_f32_e32 v41, v41
	s_waitcnt vmcnt(13)
	v_lshlrev_b32_e32 v54, 16, v110
	v_add_f32_e32 v40, 1.0, v40
	v_rcp_f32_e32 v40, v40
	s_waitcnt vmcnt(11)
	v_lshlrev_b32_e32 v62, 16, v106
	v_mul_f32_e32 v45, 0xbfb8aa3b, v45
	v_mul_f32_e32 v44, 0xbfb8aa3b, v44
	v_exp_f32_e32 v45, v45
	v_fmac_f32_e32 v54, v40, v62
	v_add_f32_e32 v40, 1.0, v41
	v_mul_f32_e32 v41, 0xbfb8aa3b, v46
	v_mul_f32_e32 v42, 0xbfb8aa3b, v42
	v_exp_f32_e32 v44, v44
	v_rcp_f32_e32 v40, v40
	v_exp_f32_e32 v41, v41
	v_exp_f32_e32 v42, v42
	v_mul_f32_e32 v32, 0xbfb8aa3b, v32
	v_exp_f32_e32 v32, v32
	v_and_b32_e32 v55, 0xffff0000, v110
	v_and_b32_e32 v63, 0xffff0000, v106
	v_add_f32_e32 v45, 1.0, v45
	v_add_f32_e32 v44, 1.0, v44
	v_rcp_f32_e32 v45, v45
	v_fmac_f32_e32 v55, v40, v63
	v_add_f32_e32 v40, 1.0, v41
	v_add_f32_e32 v41, 1.0, v42
	v_mul_f32_e32 v42, 0xbfb8aa3b, v47
	v_rcp_f32_e32 v44, v44
	v_rcp_f32_e32 v40, v40
	v_exp_f32_e32 v42, v42
	v_add_f32_e32 v32, 1.0, v32
	v_mul_f32_e32 v33, 0xbfb8aa3b, v33
	v_rcp_f32_e32 v32, v32
	v_exp_f32_e32 v33, v33
	v_and_b32_e32 v51, 0xffff0000, v108
	v_and_b32_e32 v59, 0xffff0000, v104
	v_lshlrev_b32_e32 v50, 16, v108
	v_lshlrev_b32_e32 v52, 16, v109
	v_lshlrev_b32_e32 v58, 16, v104
	v_lshlrev_b32_e32 v60, 16, v105
	v_fmac_f32_e32 v51, v45, v59
	v_fmac_f32_e32 v50, v44, v58
	v_add_f32_e32 v42, 1.0, v42
	v_fmac_f32_e32 v52, v40, v60
	v_cvt_pk_bf16_f32 v40, v50, v51
	v_mul_f32_e32 v44, v51, v51
	v_lshlrev_b32_e32 v51, 16, v102
	s_waitcnt vmcnt(10)
	v_lshlrev_b32_e32 v60, 16, v98
	v_rcp_f32_e32 v41, v41
	v_rcp_f32_e32 v42, v42
	v_fmac_f32_e32 v51, v32, v60
	v_add_f32_e32 v32, 1.0, v33
	v_mul_f32_e32 v33, 0xbfb8aa3b, v38
	v_mul_f32_e32 v34, 0xbfb8aa3b, v34
	v_mul_f32_e32 v43, 0xbfb8aa3b, v43
	v_rcp_f32_e32 v32, v32
	v_exp_f32_e32 v33, v33
	v_exp_f32_e32 v34, v34
	v_exp_f32_e32 v43, v43
	v_mul_f32_e32 v36, 0xbfb8aa3b, v36
	v_and_b32_e32 v53, 0xffff0000, v109
	v_lshlrev_b32_e32 v56, 16, v111
	v_and_b32_e32 v61, 0xffff0000, v105
	v_lshlrev_b32_e32 v104, 16, v107
	v_fmac_f32_e32 v44, v50, v50
	v_exp_f32_e32 v36, v36
	v_mul_f32_e32 v37, 0xbfb8aa3b, v37
	v_fmac_f32_e32 v56, v41, v104
	v_fmac_f32_e32 v53, v42, v61
	v_cvt_pk_bf16_f32 v41, v52, v53
	v_fmac_f32_e32 v44, v52, v52
	v_and_b32_e32 v52, 0xffff0000, v102
	v_and_b32_e32 v61, 0xffff0000, v98
	v_exp_f32_e32 v37, v37
	v_fmac_f32_e32 v52, v32, v61
	v_add_f32_e32 v32, 1.0, v33
	v_add_f32_e32 v33, 1.0, v34
	v_mul_f32_e32 v34, 0xbfb8aa3b, v39
	v_add_f32_e32 v43, 1.0, v43
	v_exp_f32_e32 v34, v34
	v_rcp_f32_e32 v43, v43
	v_add_f32_e32 v36, 1.0, v36
	v_fmac_f32_e32 v44, v53, v53
	v_rcp_f32_e32 v36, v36
	v_add_f32_e32 v37, 1.0, v37
	v_fmac_f32_e32 v44, v54, v54
	v_rcp_f32_e32 v37, v37
	v_mul_f32_e32 v35, 0xbfb8aa3b, v35
	v_and_b32_e32 v57, 0xffff0000, v111
	v_and_b32_e32 v105, 0xffff0000, v107
	v_fmac_f32_e32 v44, v55, v55
	v_rcp_f32_e32 v32, v32
	v_exp_f32_e32 v35, v35
	v_add_f32_e32 v34, 1.0, v34
	v_fmac_f32_e32 v57, v43, v105
	v_fmac_f32_e32 v44, v56, v56
	v_lshlrev_b32_e32 v45, 16, v100
	v_lshlrev_b32_e32 v43, 16, v96
	v_rcp_f32_e32 v34, v34
	v_cvt_pk_bf16_f32 v42, v54, v55
	v_fmac_f32_e32 v44, v57, v57
	v_and_b32_e32 v46, 0xffff0000, v100
	v_and_b32_e32 v55, 0xffff0000, v96
	v_fmac_f32_e32 v45, v36, v43
	v_lshlrev_b32_e32 v47, 16, v101
	v_lshlrev_b32_e32 v58, 16, v97
	v_fmac_f32_e32 v46, v37, v55
	v_fmac_f32_e32 v44, v45, v45
	v_and_b32_e32 v50, 0xffff0000, v101
	v_and_b32_e32 v59, 0xffff0000, v97
	v_rcp_f32_e32 v33, v33
	v_add_f32_e32 v35, 1.0, v35
	v_fmac_f32_e32 v47, v32, v58
	v_fmac_f32_e32 v44, v46, v46
	v_rcp_f32_e32 v35, v35
	v_fmac_f32_e32 v50, v34, v59
	v_fmac_f32_e32 v44, v47, v47
	v_fmac_f32_e32 v44, v50, v50
	v_lshlrev_b32_e32 v53, 16, v103
	v_lshlrev_b32_e32 v62, 16, v99
	v_fmac_f32_e32 v44, v51, v51
	v_and_b32_e32 v54, 0xffff0000, v103
	v_and_b32_e32 v63, 0xffff0000, v99
	v_fmac_f32_e32 v53, v33, v62
	v_fmac_f32_e32 v44, v52, v52
	v_fmac_f32_e32 v54, v35, v63
	v_fmac_f32_e32 v44, v53, v53
	v_fmac_f32_e32 v44, v54, v54
	ds_bpermute_b32 v32, v197, v44
	s_waitcnt lgkmcnt(1)
	v_lshlrev_b64 v[48:49], 11, v[116:117]
	v_lshl_add_u64 v[48:49], s[48:49], 0, v[48:49]
	v_lshl_add_u64 v[38:39], v[120:121], 1, v[48:49]
	v_cvt_pk_bf16_f32 v43, v56, v57
	s_waitcnt lgkmcnt(0)
	v_add_f32_e32 v32, v44, v32
	ds_bpermute_b32 v33, v198, v32
	global_store_dwordx4 v[38:39], v[40:43], off sc1
	v_cvt_pk_bf16_f32 v34, v45, v46
	v_cvt_pk_bf16_f32 v35, v47, v50
	v_cvt_pk_bf16_f32 v36, v51, v52
	v_cvt_pk_bf16_f32 v37, v53, v54
	global_store_dwordx4 v[38:39], v[34:37], off offset:256 sc1
	s_and_saveexec_b64 s[50:51], vcc
	s_cbranch_execz .LBB0_845
	s_waitcnt lgkmcnt(0)
	v_add_f32_e32 v34, v32, v33
	v_lshl_add_u64 v[32:33], v[116:117], 2, s[42:43]
	global_atomic_add_f32 v[32:33], v34, off
; __device__ __forceinline__ unsigned cvt_pk(float lo, float hi) { unsigned r; asm("v_cvt_pk_bf16_f32 %0, %1, %2" : "=v"(r) : "v"(lo), "v"(hi)); return r; }
; __device__ __forceinline__ float fexp2(float x) { return __builtin_amdgcn_exp2f(x); }
; __device__ __forceinline__ float frcp(float x) { return __builtin_amdgcn_rcpf(x); }
;     __device__ __forceinline__ void operator()(AccRef acc, const pg8::Unit& u, int wr, int wc, int, int) const {
;     ...
;                 for (int bj = 0; bj < 2; ++bj) {
;                     const int c0 = u.pn * 256 + bj * 128 + wc * 32 + 8 * fq;
;                     const v4u hw = hwv[m][bj], pw = pwv[m][bj];
;                     const float hh[8] = {bf_lo(hw.x), bf_hi(hw.x), bf_lo(hw.y), bf_hi(hw.y), bf_lo(hw.z), bf_hi(hw.z), bf_lo(hw.w), bf_hi(hw.w)};
;                     const float pp[8] = {bf_lo(pw.x), bf_hi(pw.x), bf_lo(pw.y), bf_hi(pw.y), bf_lo(pw.z), bf_hi(pw.z), bf_lo(pw.w), bf_hi(pw.w)};
;                     float o[8];
; #pragma unroll
;                     for (int j = 0; j < 4; ++j) {
;                         o[j] = hh[j] + pp[j] * frcp(1.0f + fexp2(-acc[ai][bj][m][0][j] * LOG2E));
;                         o[4 + j] = hh[4 + j] + pp[4 + j] * frcp(1.0f + fexp2(-acc[ai][bj][m][1][j] * LOG2E));
;                     }
;                     v4u w; w.x = cvt_pk(o[0], o[1]); w.y = cvt_pk(o[2], o[3]); w.z = cvt_pk(o[4], o[5]); w.w = cvt_pk(o[6], o[7]);
;                     *(v4u*)(XB + (size_t)row * DM + c0) = w;
; #pragma unroll
;                     for (int j = 0; j < 8; ++j) ss += o[j] * o[j];
;                 }
;                 ss += __shfl_xor(ss, 16); ss += __shfl_xor(ss, 32);
;                 if (fq == 0) __hip_atomic_fetch_add(ssq + row, ss, __ATOMIC_RELAXED, __HIP_MEMORY_SCOPE_AGENT);
;             }
.LBB0_845:
	s_or_b64 exec, exec, s[50:51]
	v_mul_f32_e32 v24, 0xbfb8aa3b, v24
	v_exp_f32_e32 v24, v24
	v_mul_f32_e32 v25, 0xbfb8aa3b, v25
	v_exp_f32_e32 v25, v25
	s_waitcnt vmcnt(11)
	v_lshlrev_b32_e32 v38, 16, v94
	v_add_f32_e32 v24, 1.0, v24
	v_rcp_f32_e32 v24, v24
	s_waitcnt vmcnt(9)
	v_lshlrev_b32_e32 v46, 16, v90
	v_mul_f32_e32 v29, 0xbfb8aa3b, v29
	v_mul_f32_e32 v28, 0xbfb8aa3b, v28
	v_exp_f32_e32 v29, v29
	v_fmac_f32_e32 v38, v24, v46
	v_add_f32_e32 v24, 1.0, v25
	v_mul_f32_e32 v25, 0xbfb8aa3b, v30
	v_mul_f32_e32 v26, 0xbfb8aa3b, v26
	v_exp_f32_e32 v28, v28
	v_rcp_f32_e32 v24, v24
	v_exp_f32_e32 v25, v25
	v_exp_f32_e32 v26, v26
	v_mul_f32_e32 v16, 0xbfb8aa3b, v16
	v_exp_f32_e32 v16, v16
	v_and_b32_e32 v39, 0xffff0000, v94
	v_and_b32_e32 v47, 0xffff0000, v90
	v_add_f32_e32 v29, 1.0, v29
	v_add_f32_e32 v28, 1.0, v28
	v_rcp_f32_e32 v29, v29
	v_fmac_f32_e32 v39, v24, v47
	v_add_f32_e32 v24, 1.0, v25
	v_add_f32_e32 v25, 1.0, v26
	v_mul_f32_e32 v26, 0xbfb8aa3b, v31
	v_rcp_f32_e32 v28, v28
	v_rcp_f32_e32 v24, v24
	v_exp_f32_e32 v26, v26
	v_add_f32_e32 v16, 1.0, v16
	v_mul_f32_e32 v17, 0xbfb8aa3b, v17
	v_rcp_f32_e32 v16, v16
	v_exp_f32_e32 v17, v17
	v_and_b32_e32 v35, 0xffff0000, v92
	v_and_b32_e32 v43, 0xffff0000, v88
	v_lshlrev_b32_e32 v34, 16, v92
	v_lshlrev_b32_e32 v36, 16, v93
	v_lshlrev_b32_e32 v42, 16, v88
	v_lshlrev_b32_e32 v44, 16, v89
	v_fmac_f32_e32 v35, v29, v43
	v_fmac_f32_e32 v34, v28, v42
	v_add_f32_e32 v26, 1.0, v26
	v_fmac_f32_e32 v36, v24, v44
	v_cvt_pk_bf16_f32 v24, v34, v35
	v_mul_f32_e32 v28, v35, v35
	v_lshlrev_b32_e32 v35, 16, v86
	s_waitcnt vmcnt(8)
	v_lshlrev_b32_e32 v44, 16, v82
	v_rcp_f32_e32 v25, v25
	v_rcp_f32_e32 v26, v26
	v_fmac_f32_e32 v35, v16, v44
	v_add_f32_e32 v16, 1.0, v17
	v_mul_f32_e32 v17, 0xbfb8aa3b, v22
	v_mul_f32_e32 v18, 0xbfb8aa3b, v18
	v_mul_f32_e32 v27, 0xbfb8aa3b, v27
	v_rcp_f32_e32 v16, v16
	v_exp_f32_e32 v17, v17
	v_exp_f32_e32 v18, v18
	v_exp_f32_e32 v27, v27
	v_mul_f32_e32 v20, 0xbfb8aa3b, v20
	v_and_b32_e32 v37, 0xffff0000, v93
	v_lshlrev_b32_e32 v40, 16, v95
	v_and_b32_e32 v45, 0xffff0000, v89
	v_lshlrev_b32_e32 v48, 16, v91
	v_fmac_f32_e32 v28, v34, v34
	v_exp_f32_e32 v20, v20
	v_mul_f32_e32 v21, 0xbfb8aa3b, v21
	v_fmac_f32_e32 v40, v25, v48
	v_fmac_f32_e32 v37, v26, v45
	v_cvt_pk_bf16_f32 v25, v36, v37
	v_fmac_f32_e32 v28, v36, v36
	v_and_b32_e32 v36, 0xffff0000, v86
	v_and_b32_e32 v45, 0xffff0000, v82
	v_exp_f32_e32 v21, v21
	v_fmac_f32_e32 v36, v16, v45
	v_add_f32_e32 v16, 1.0, v17
	v_add_f32_e32 v17, 1.0, v18
	v_mul_f32_e32 v18, 0xbfb8aa3b, v23
	v_add_f32_e32 v27, 1.0, v27
	v_exp_f32_e32 v18, v18
	v_rcp_f32_e32 v27, v27
	v_add_f32_e32 v20, 1.0, v20
	v_fmac_f32_e32 v28, v37, v37
	v_rcp_f32_e32 v20, v20
	v_add_f32_e32 v21, 1.0, v21
	v_fmac_f32_e32 v28, v38, v38
	v_rcp_f32_e32 v21, v21
	v_mul_f32_e32 v19, 0xbfb8aa3b, v19
	v_and_b32_e32 v41, 0xffff0000, v95
	v_and_b32_e32 v49, 0xffff0000, v91
	v_fmac_f32_e32 v28, v39, v39
	v_rcp_f32_e32 v16, v16
	v_exp_f32_e32 v19, v19
	v_add_f32_e32 v18, 1.0, v18
	v_fmac_f32_e32 v41, v27, v49
	v_fmac_f32_e32 v28, v40, v40
	v_lshlrev_b32_e32 v29, 16, v84
	v_lshlrev_b32_e32 v27, 16, v80
	v_rcp_f32_e32 v18, v18
	v_cvt_pk_bf16_f32 v26, v38, v39
	v_fmac_f32_e32 v28, v41, v41
	v_and_b32_e32 v30, 0xffff0000, v84
	v_and_b32_e32 v39, 0xffff0000, v80
	v_fmac_f32_e32 v29, v20, v27
	v_lshlrev_b32_e32 v31, 16, v85
	v_lshlrev_b32_e32 v42, 16, v81
	v_fmac_f32_e32 v30, v21, v39
	v_fmac_f32_e32 v28, v29, v29
	v_and_b32_e32 v34, 0xffff0000, v85
	v_and_b32_e32 v43, 0xffff0000, v81
	v_rcp_f32_e32 v17, v17
	v_add_f32_e32 v19, 1.0, v19
	v_fmac_f32_e32 v31, v16, v42
	v_fmac_f32_e32 v28, v30, v30
	v_rcp_f32_e32 v19, v19
	v_fmac_f32_e32 v34, v18, v43
	v_fmac_f32_e32 v28, v31, v31
	v_fmac_f32_e32 v28, v34, v34
	v_lshlrev_b32_e32 v37, 16, v87
	v_lshlrev_b32_e32 v46, 16, v83
	v_fmac_f32_e32 v28, v35, v35
	v_and_b32_e32 v38, 0xffff0000, v87
	v_and_b32_e32 v47, 0xffff0000, v83
	v_fmac_f32_e32 v37, v17, v46
	v_fmac_f32_e32 v28, v36, v36
	v_fmac_f32_e32 v38, v19, v47
	v_fmac_f32_e32 v28, v37, v37
	v_fmac_f32_e32 v28, v38, v38
	ds_bpermute_b32 v16, v197, v28
	s_waitcnt lgkmcnt(1)
	v_lshlrev_b64 v[32:33], 11, v[114:115]
	v_lshl_add_u64 v[32:33], s[48:49], 0, v[32:33]
	v_lshl_add_u64 v[22:23], v[120:121], 1, v[32:33]
	v_cvt_pk_bf16_f32 v27, v40, v41
	s_waitcnt lgkmcnt(0)
	v_add_f32_e32 v16, v28, v16
	ds_bpermute_b32 v17, v198, v16
	global_store_dwordx4 v[22:23], v[24:27], off sc1
	v_cvt_pk_bf16_f32 v18, v29, v30
	v_cvt_pk_bf16_f32 v19, v31, v34
	v_cvt_pk_bf16_f32 v20, v35, v36
	v_cvt_pk_bf16_f32 v21, v37, v38
	global_store_dwordx4 v[22:23], v[18:21], off offset:256 sc1
	s_and_saveexec_b64 s[50:51], vcc
	s_cbranch_execz .LBB0_847
	s_waitcnt lgkmcnt(0)
	v_add_f32_e32 v18, v16, v17
	v_lshl_add_u64 v[16:17], v[114:115], 2, s[42:43]
	global_atomic_add_f32 v[16:17], v18, off
; __device__ __forceinline__ unsigned cvt_pk(float lo, float hi) { unsigned r; asm("v_cvt_pk_bf16_f32 %0, %1, %2" : "=v"(r) : "v"(lo), "v"(hi)); return r; }
; __device__ __forceinline__ float fexp2(float x) { return __builtin_amdgcn_exp2f(x); }
; __device__ __forceinline__ float frcp(float x) { return __builtin_amdgcn_rcpf(x); }
;     __device__ __forceinline__ void operator()(AccRef acc, const pg8::Unit& u, int wr, int wc, int, int) const {
;     ...
;                 for (int bj = 0; bj < 2; ++bj) {
;                     const int c0 = u.pn * 256 + bj * 128 + wc * 32 + 8 * fq;
;                     const v4u hw = hwv[m][bj], pw = pwv[m][bj];
;                     const float hh[8] = {bf_lo(hw.x), bf_hi(hw.x), bf_lo(hw.y), bf_hi(hw.y), bf_lo(hw.z), bf_hi(hw.z), bf_lo(hw.w), bf_hi(hw.w)};
;                     const float pp[8] = {bf_lo(pw.x), bf_hi(pw.x), bf_lo(pw.y), bf_hi(pw.y), bf_lo(pw.z), bf_hi(pw.z), bf_lo(pw.w), bf_hi(pw.w)};
;                     float o[8];
; #pragma unroll
;                     for (int j = 0; j < 4; ++j) {
;                         o[j] = hh[j] + pp[j] * frcp(1.0f + fexp2(-acc[ai][bj][m][0][j] * LOG2E));
;                         o[4 + j] = hh[4 + j] + pp[4 + j] * frcp(1.0f + fexp2(-acc[ai][bj][m][1][j] * LOG2E));
;                     }
;                     v4u w; w.x = cvt_pk(o[0], o[1]); w.y = cvt_pk(o[2], o[3]); w.z = cvt_pk(o[4], o[5]); w.w = cvt_pk(o[6], o[7]);
;                     *(v4u*)(XB + (size_t)row * DM + c0) = w;
; #pragma unroll
;                     for (int j = 0; j < 8; ++j) ss += o[j] * o[j];
;                 }
;                 ss += __shfl_xor(ss, 16); ss += __shfl_xor(ss, 32);
;                 if (fq == 0) __hip_atomic_fetch_add(ssq + row, ss, __ATOMIC_RELAXED, __HIP_MEMORY_SCOPE_AGENT);
;             }
.LBB0_847:
	s_or_b64 exec, exec, s[50:51]
	v_mul_f32_e32 v8, 0xbfb8aa3b, v8
	v_exp_f32_e32 v8, v8
	v_mul_f32_e32 v9, 0xbfb8aa3b, v9
	v_exp_f32_e32 v9, v9
	s_waitcnt vmcnt(9)
	v_lshlrev_b32_e32 v22, 16, v78
	v_add_f32_e32 v8, 1.0, v8
	v_rcp_f32_e32 v8, v8
	s_waitcnt vmcnt(7)
	v_lshlrev_b32_e32 v30, 16, v74
	v_mul_f32_e32 v13, 0xbfb8aa3b, v13
	v_mul_f32_e32 v12, 0xbfb8aa3b, v12
	v_exp_f32_e32 v13, v13
	v_fmac_f32_e32 v22, v8, v30
	v_add_f32_e32 v8, 1.0, v9
	v_mul_f32_e32 v9, 0xbfb8aa3b, v14
	v_mul_f32_e32 v10, 0xbfb8aa3b, v10
	v_exp_f32_e32 v12, v12
	v_rcp_f32_e32 v8, v8
	v_exp_f32_e32 v9, v9
	v_exp_f32_e32 v10, v10
	v_mul_f32_e32 v0, 0xbfb8aa3b, v0
	v_exp_f32_e32 v0, v0
	v_and_b32_e32 v23, 0xffff0000, v78
	v_and_b32_e32 v31, 0xffff0000, v74
	v_add_f32_e32 v13, 1.0, v13
	v_add_f32_e32 v12, 1.0, v12
	v_rcp_f32_e32 v13, v13
	v_fmac_f32_e32 v23, v8, v31
	v_add_f32_e32 v8, 1.0, v9
	v_add_f32_e32 v9, 1.0, v10
	v_mul_f32_e32 v10, 0xbfb8aa3b, v15
	v_rcp_f32_e32 v12, v12
	v_rcp_f32_e32 v8, v8
	v_exp_f32_e32 v10, v10
	v_add_f32_e32 v0, 1.0, v0
	v_mul_f32_e32 v1, 0xbfb8aa3b, v1
	v_rcp_f32_e32 v0, v0
	v_exp_f32_e32 v1, v1
	v_and_b32_e32 v19, 0xffff0000, v76
	v_and_b32_e32 v27, 0xffff0000, v72
	v_lshlrev_b32_e32 v18, 16, v76
	v_lshlrev_b32_e32 v20, 16, v77
	v_lshlrev_b32_e32 v26, 16, v72
	v_lshlrev_b32_e32 v28, 16, v73
	v_fmac_f32_e32 v19, v13, v27
	v_fmac_f32_e32 v18, v12, v26
	v_add_f32_e32 v10, 1.0, v10
	v_fmac_f32_e32 v20, v8, v28
	v_cvt_pk_bf16_f32 v8, v18, v19
	v_mul_f32_e32 v12, v19, v19
	v_lshlrev_b32_e32 v19, 16, v70
	s_waitcnt vmcnt(6)
	v_lshlrev_b32_e32 v28, 16, v66
	v_rcp_f32_e32 v9, v9
	v_rcp_f32_e32 v10, v10
	v_fmac_f32_e32 v19, v0, v28
	v_add_f32_e32 v0, 1.0, v1
	v_mul_f32_e32 v1, 0xbfb8aa3b, v6
	v_mul_f32_e32 v2, 0xbfb8aa3b, v2
	v_mul_f32_e32 v11, 0xbfb8aa3b, v11
	v_rcp_f32_e32 v0, v0
	v_exp_f32_e32 v1, v1
	v_exp_f32_e32 v2, v2
	v_exp_f32_e32 v11, v11
	v_mul_f32_e32 v4, 0xbfb8aa3b, v4
	v_and_b32_e32 v21, 0xffff0000, v77
	v_lshlrev_b32_e32 v24, 16, v79
	v_and_b32_e32 v29, 0xffff0000, v73
	v_lshlrev_b32_e32 v32, 16, v75
	v_fmac_f32_e32 v12, v18, v18
	v_exp_f32_e32 v4, v4
	v_mul_f32_e32 v5, 0xbfb8aa3b, v5
	v_fmac_f32_e32 v24, v9, v32
	v_fmac_f32_e32 v21, v10, v29
	v_cvt_pk_bf16_f32 v9, v20, v21
	v_fmac_f32_e32 v12, v20, v20
	v_and_b32_e32 v20, 0xffff0000, v70
	v_and_b32_e32 v29, 0xffff0000, v66
	v_exp_f32_e32 v5, v5
	v_fmac_f32_e32 v20, v0, v29
	v_add_f32_e32 v0, 1.0, v1
	v_add_f32_e32 v1, 1.0, v2
	v_mul_f32_e32 v2, 0xbfb8aa3b, v7
	v_add_f32_e32 v11, 1.0, v11
	v_exp_f32_e32 v2, v2
	v_rcp_f32_e32 v11, v11
	v_add_f32_e32 v4, 1.0, v4
	v_fmac_f32_e32 v12, v21, v21
	v_rcp_f32_e32 v4, v4
	v_add_f32_e32 v5, 1.0, v5
	v_fmac_f32_e32 v12, v22, v22
	v_rcp_f32_e32 v5, v5
	v_mul_f32_e32 v3, 0xbfb8aa3b, v3
	v_and_b32_e32 v25, 0xffff0000, v79
	v_and_b32_e32 v33, 0xffff0000, v75
	v_fmac_f32_e32 v12, v23, v23
	v_rcp_f32_e32 v0, v0
	v_exp_f32_e32 v3, v3
	v_add_f32_e32 v2, 1.0, v2
	v_fmac_f32_e32 v25, v11, v33
	v_fmac_f32_e32 v12, v24, v24
	v_lshlrev_b32_e32 v13, 16, v68
	v_lshlrev_b32_e32 v11, 16, v64
	v_rcp_f32_e32 v2, v2
	v_cvt_pk_bf16_f32 v10, v22, v23
	v_fmac_f32_e32 v12, v25, v25
	v_and_b32_e32 v14, 0xffff0000, v68
	v_and_b32_e32 v23, 0xffff0000, v64
	v_fmac_f32_e32 v13, v4, v11
	v_lshlrev_b32_e32 v15, 16, v69
	v_lshlrev_b32_e32 v26, 16, v65
	v_fmac_f32_e32 v14, v5, v23
	v_fmac_f32_e32 v12, v13, v13
	v_and_b32_e32 v18, 0xffff0000, v69
	v_and_b32_e32 v27, 0xffff0000, v65
	v_rcp_f32_e32 v1, v1
	v_add_f32_e32 v3, 1.0, v3
	v_fmac_f32_e32 v15, v0, v26
	v_fmac_f32_e32 v12, v14, v14
	v_rcp_f32_e32 v3, v3
	v_fmac_f32_e32 v18, v2, v27
	v_fmac_f32_e32 v12, v15, v15
	v_fmac_f32_e32 v12, v18, v18
	v_lshlrev_b32_e32 v21, 16, v71
	v_lshlrev_b32_e32 v30, 16, v67
	v_fmac_f32_e32 v12, v19, v19
	v_and_b32_e32 v22, 0xffff0000, v71
	v_and_b32_e32 v31, 0xffff0000, v67
	v_fmac_f32_e32 v21, v1, v30
	v_fmac_f32_e32 v12, v20, v20
	v_fmac_f32_e32 v22, v3, v31
	v_fmac_f32_e32 v12, v21, v21
	v_fmac_f32_e32 v12, v22, v22
	ds_bpermute_b32 v0, v197, v12
	s_waitcnt lgkmcnt(1)
	v_lshlrev_b64 v[16:17], 11, v[112:113]
	v_lshl_add_u64 v[16:17], s[48:49], 0, v[16:17]
	v_lshl_add_u64 v[6:7], v[120:121], 1, v[16:17]
	v_cvt_pk_bf16_f32 v11, v24, v25
	s_waitcnt lgkmcnt(0)
	v_add_f32_e32 v0, v12, v0
	ds_bpermute_b32 v1, v198, v0
	global_store_dwordx4 v[6:7], v[8:11], off sc1
	v_cvt_pk_bf16_f32 v2, v13, v14
	v_cvt_pk_bf16_f32 v3, v15, v18
	v_cvt_pk_bf16_f32 v4, v19, v20
	v_cvt_pk_bf16_f32 v5, v21, v22
	global_store_dwordx4 v[6:7], v[2:5], off offset:256 sc1
	s_and_saveexec_b64 s[48:49], vcc
	s_cbranch_execz .LBB0_849
	s_waitcnt lgkmcnt(0)
	v_add_f32_e32 v2, v0, v1
	v_lshl_add_u64 v[0:1], v[112:113], 2, s[42:43]
	global_atomic_add_f32 v[0:1], v2, off

; __device__ __forceinline__ unsigned cvt_pk(float lo, float hi) { unsigned r; asm("v_cvt_pk_bf16_f32 %0, %1, %2" : "=v"(r) : "v"(lo), "v"(hi)); return r; }
;     __device__ __forceinline__ void operator()(AccRef acc, const pg8::Unit& u, int wr, int wc, int, int) const {
;     ...
; #pragma unroll
;         for (int ai = 0; ai < 2; ++ai)
; #pragma unroll
;             for (int m = 0; m < 4; ++m) {
;                 const int row = u.pm * 256 + ai * 128 + wr * 64 + m * 16 + fr;
; #pragma unroll
;                 for (int bj = 0; bj < 2; ++bj) {
;                     const int c0 = u.pn * 256 + bj * 128 + wc * 32 + 8 * fq;
;                     const f32x4 o0 = acc[ai][bj][m][0], o1 = acc[ai][bj][m][1];
;                     v4u w; w.x = cvt_pk(o0[0], o0[1]); w.y = cvt_pk(o0[2], o0[3]); w.z = cvt_pk(o1[0], o1[1]); w.w = cvt_pk(o1[2], o1[3]);
;                     *(v4u*)(PP + (size_t)row * DM + c0) = w;
;                 }
.LBB0_1327:
	s_mov_b64 s[36:37], s[22:23]
	s_mov_b64 s[38:39], s[20:21]
	s_add_u32 s36, s38, 0x3600000
	v_mov_b32_e32 v137, v196
	s_addc_u32 s37, s39, 0
	s_lshl_b32 s13, s30, 8
	s_add_i32 s13, s13, s35
	v_and_or_b32 v136, v137, 15, s13
	s_lshl_b32 s13, s26, 8
	v_ashrrev_i32_e32 v137, 1, v137
	v_and_b32_e32 v137, -8, v137
	s_or_b32 s13, s13, s28
	v_cvt_pk_bf16_f32 v68, v68, v69
	v_cvt_pk_bf16_f32 v69, v70, v71
	v_cvt_pk_bf16_f32 v70, v64, v65
	v_add_u32_e32 v64, 0x80, v136
	v_add_u32_e32 v144, s13, v137
	v_ashrrev_i32_e32 v137, 31, v136
	v_ashrrev_i32_e32 v65, 31, v64
	v_lshlrev_b64 v[146:147], 11, v[136:137]
	v_ashrrev_i32_e32 v145, 31, v144
	v_cvt_pk_bf16_f32 v112, v112, v113
	v_cvt_pk_bf16_f32 v113, v114, v115
	v_cvt_pk_bf16_f32 v114, v104, v105
	v_or_b32_e32 v104, 16, v136
	v_lshlrev_b64 v[64:65], 11, v[64:65]
	v_cvt_pk_bf16_f32 v48, v48, v49
	v_cvt_pk_bf16_f32 v49, v50, v51
	v_cvt_pk_bf16_f32 v50, v40, v41
	v_add_u32_e32 v40, 0x90, v136
	v_lshl_add_u64 v[146:147], s[36:37], 0, v[146:147]
	v_cvt_pk_bf16_f32 v124, v124, v125
	v_cvt_pk_bf16_f32 v125, v126, v127
	v_cvt_pk_bf16_f32 v126, v120, v121
	v_lshlrev_b64 v[120:121], 1, v[144:145]
	v_ashrrev_i32_e32 v105, 31, v104
	v_lshl_add_u64 v[64:65], s[36:37], 0, v[64:65]
	v_ashrrev_i32_e32 v41, 31, v40
	v_cvt_pk_bf16_f32 v127, v122, v123
	v_lshl_add_u64 v[122:123], v[146:147], 0, v[120:121]
	v_lshlrev_b64 v[104:105], 11, v[104:105]
	v_cvt_pk_bf16_f32 v96, v96, v97
	v_cvt_pk_bf16_f32 v97, v98, v99
	v_cvt_pk_bf16_f32 v98, v88, v89
	v_or_b32_e32 v88, 32, v136
	v_cvt_pk_bf16_f32 v60, v60, v61
	v_cvt_pk_bf16_f32 v61, v62, v63
	v_cvt_pk_bf16_f32 v62, v56, v57
	v_lshl_add_u64 v[56:57], v[64:65], 0, v[120:121]
	v_lshlrev_b64 v[40:41], 11, v[40:41]
	v_cvt_pk_bf16_f32 v32, v32, v33
	v_cvt_pk_bf16_f32 v33, v34, v35
	v_cvt_pk_bf16_f32 v34, v24, v25
	v_add_u32_e32 v24, 0xa0, v136
	v_cvt_pk_bf16_f32 v115, v106, v107
	global_store_dwordx4 v[122:123], v[112:115], off offset:256 sc1
	v_ashrrev_i32_e32 v89, 31, v88
	v_cvt_pk_bf16_f32 v51, v42, v43
	global_store_dwordx4 v[56:57], v[48:51], off offset:256 sc1
	v_lshl_add_u64 v[112:113], s[36:37], 0, v[104:105]
	v_ashrrev_i32_e32 v25, 31, v24
	v_lshl_add_u64 v[48:49], s[36:37], 0, v[40:41]
	v_cvt_pk_bf16_f32 v106, v108, v109
	v_lshl_add_u64 v[108:109], v[112:113], 0, v[120:121]
	v_lshlrev_b64 v[88:89], 11, v[88:89]
	v_cvt_pk_bf16_f32 v80, v80, v81
	v_cvt_pk_bf16_f32 v81, v82, v83
	v_cvt_pk_bf16_f32 v82, v72, v73
	v_or_b32_e32 v72, 48, v136
	v_cvt_pk_bf16_f32 v42, v44, v45
	v_lshl_add_u64 v[44:45], v[48:49], 0, v[120:121]
	v_lshlrev_b64 v[24:25], 11, v[24:25]
	v_cvt_pk_bf16_f32 v16, v16, v17
	v_cvt_pk_bf16_f32 v17, v18, v19
	v_cvt_pk_bf16_f32 v18, v8, v9
	v_add_u32_e32 v8, 0xb0, v136
	v_cvt_pk_bf16_f32 v99, v90, v91
	global_store_dwordx4 v[108:109], v[96:99], off offset:256 sc1
	v_ashrrev_i32_e32 v73, 31, v72
	v_cvt_pk_bf16_f32 v35, v26, v27
	global_store_dwordx4 v[44:45], v[32:35], off offset:256 sc1
	v_lshl_add_u64 v[96:97], s[36:37], 0, v[88:89]
	v_ashrrev_i32_e32 v9, 31, v8
	v_lshl_add_u64 v[32:33], s[36:37], 0, v[24:25]
	v_cvt_pk_bf16_f32 v90, v92, v93
	v_lshl_add_u64 v[92:93], v[96:97], 0, v[120:121]
	v_lshlrev_b64 v[72:73], 11, v[72:73]
	v_cvt_pk_bf16_f32 v26, v28, v29
	v_lshl_add_u64 v[28:29], v[32:33], 0, v[120:121]
	v_lshlrev_b64 v[8:9], 11, v[8:9]
	v_cvt_pk_bf16_f32 v83, v74, v75
	global_store_dwordx4 v[92:93], v[80:83], off offset:256 sc1
	v_cvt_pk_bf16_f32 v19, v10, v11
	global_store_dwordx4 v[28:29], v[16:19], off offset:256 sc1
	v_readlane_b32 s74, v249, 39
	v_lshl_add_u64 v[80:81], s[36:37], 0, v[72:73]
	v_lshl_add_u64 v[16:17], s[36:37], 0, v[8:9]
	v_cvt_pk_bf16_f32 v74, v76, v77
	v_lshl_add_u64 v[76:77], v[80:81], 0, v[120:121]
	v_cvt_pk_bf16_f32 v10, v12, v13
	v_lshl_add_u64 v[12:13], v[16:17], 0, v[120:121]
	s_andn2_b64 vcc, exec, s[16:17]
	s_mov_b64 s[16:17], -1
	v_readlane_b32 s75, v249, 40
	global_store_dwordx4 v[122:123], v[124:127], off sc1
	v_cvt_pk_bf16_f32 v104, v116, v117
	v_cvt_pk_bf16_f32 v105, v118, v119
	v_cvt_pk_bf16_f32 v107, v110, v111
	global_store_dwordx4 v[108:109], v[104:107], off sc1
	v_cvt_pk_bf16_f32 v88, v100, v101
	v_cvt_pk_bf16_f32 v89, v102, v103
	v_cvt_pk_bf16_f32 v91, v94, v95
	global_store_dwordx4 v[92:93], v[88:91], off sc1
	v_cvt_pk_bf16_f32 v72, v84, v85
	v_cvt_pk_bf16_f32 v73, v86, v87
	v_cvt_pk_bf16_f32 v75, v78, v79
	global_store_dwordx4 v[76:77], v[72:75], off sc1
	v_cvt_pk_bf16_f32 v71, v66, v67
	global_store_dwordx4 v[76:77], v[68:71], off offset:256 sc1
	v_cvt_pk_bf16_f32 v63, v58, v59
	global_store_dwordx4 v[56:57], v[60:63], off sc1
	v_cvt_pk_bf16_f32 v40, v52, v53
	v_cvt_pk_bf16_f32 v41, v54, v55
	v_cvt_pk_bf16_f32 v43, v46, v47
	global_store_dwordx4 v[44:45], v[40:43], off sc1
	v_cvt_pk_bf16_f32 v24, v36, v37
	v_cvt_pk_bf16_f32 v25, v38, v39
	v_cvt_pk_bf16_f32 v27, v30, v31
	global_store_dwordx4 v[28:29], v[24:27], off sc1
	v_cvt_pk_bf16_f32 v8, v20, v21
	v_cvt_pk_bf16_f32 v9, v22, v23
	v_cvt_pk_bf16_f32 v11, v14, v15
	global_store_dwordx4 v[12:13], v[8:11], off sc1
	v_cvt_pk_bf16_f32 v4, v4, v5
	v_cvt_pk_bf16_f32 v5, v6, v7
	v_cvt_pk_bf16_f32 v6, v0, v1
	v_cvt_pk_bf16_f32 v7, v2, v3
	global_store_dwordx4 v[12:13], v[4:7], off offset:256 sc1
	s_cbranch_vccnz .LBB0_1317
	s_andn2_b64 vcc, exec, s[8:9]
	s_cbranch_vccnz .LBB0_1316
	s_barrier
	s_branch .LBB0_1316

; __device__ __forceinline__ float fexp2(float x) { return __builtin_amdgcn_exp2f(x); }
; __device__ __forceinline__ float frcp(float x) { return __builtin_amdgcn_rcpf(x); }
;     __device__ __forceinline__ void operator()(AccRef acc, const pg8::Unit& u, int wr, int wc, int, int) const {
;     ...
;         for (int ai = 0; ai < 2; ++ai) {
;             v4u hwv[4][2], pwv[4][2];
; #pragma unroll
;             for (int m = 0; m < 4; ++m) { const int row = u.pm * 256 + ai * 128 + wr * 64 + m * 16 + fr;
; #pragma unroll
;                 for (int bj = 0; bj < 2; ++bj) { const size_t off = (size_t)row * DM + u.pn * 256 + bj * 128 + wc * 32 + 8 * fq; hwv[m][bj] = *(const v4u*)(HB + off); pwv[m][bj] = *(const v4u*)(XB + off); } }
;             asm volatile("" ::: "memory");
; #pragma unroll
;             for (int m = 0; m < 4; ++m) {
;                 const int row = u.pm * 256 + ai * 128 + wr * 64 + m * 16 + fr;
;                 float ss = 0.f;
; #pragma unroll
;                 for (int bj = 0; bj < 2; ++bj) {
;                     const int c0 = u.pn * 256 + bj * 128 + wc * 32 + 8 * fq;
;                     const v4u hw = hwv[m][bj], pw = pwv[m][bj];
;                     const float hh[8] = {bf_lo(hw.x), bf_hi(hw.x), bf_lo(hw.y), bf_hi(hw.y), bf_lo(hw.z), bf_hi(hw.z), bf_lo(hw.w), bf_hi(hw.w)};
;                     const float pp[8] = {bf_lo(pw.x), bf_hi(pw.x), bf_lo(pw.y), bf_hi(pw.y), bf_lo(pw.z), bf_hi(pw.z), bf_lo(pw.w), bf_hi(pw.w)};
;                     float o[8];
; #pragma unroll
;                     for (int j = 0; j < 4; ++j) {
;                         o[j] = hh[j] + pp[j] * frcp(1.0f + fexp2(-acc[ai][bj][m][0][j] * LOG2E));
;                         o[4 + j] = hh[4 + j] + pp[4 + j] * frcp(1.0f + fexp2(-acc[ai][bj][m][1][j] * LOG2E));
;                     }
.LBB0_1372:
	s_mov_b64 s[24:25], s[20:21]
	s_mov_b64 s[26:27], s[22:23]
	s_add_u32 s38, s24, 0x7800000
	s_addc_u32 s39, s25, 0
	s_add_u32 s26, s24, 0x3600000
	s_addc_u32 s27, s25, 0
	s_add_u32 s24, s24, 0x85000
	v_mov_b32_e32 v134, v196
	s_addc_u32 s25, s25, 0
	s_lshl_b32 s11, s36, 8
	s_add_i32 s11, s11, s35
	s_lshl_b32 s30, s30, 8
	v_ashrrev_i32_e32 v128, 1, v134
	v_and_or_b32 v190, v134, 15, s11
	s_ashr_i32 s31, s30, 31
	v_and_b32_e32 v128, -8, v128
	v_ashrrev_i32_e32 v129, 31, v128
	s_or_b64 s[50:51], s[30:31], s[28:29]
	v_ashrrev_i32_e32 v191, 31, v190
	v_lshl_add_u64 v[188:189], s[50:51], 0, v[128:129]
	v_lshlrev_b64 v[130:131], 10, v[190:191]
	v_lshl_add_u64 v[130:131], v[188:189], 0, v[130:131]
	v_lshlrev_b64 v[130:131], 1, v[130:131]
	v_lshl_add_u64 v[132:133], s[38:39], 0, v[130:131]
	v_lshl_add_u64 v[130:131], s[26:27], 0, v[130:131]
	global_load_dwordx4 v[204:207], v[132:133], off
	global_load_dwordx4 v[212:215], v[132:133], off offset:256
	global_load_dwordx4 v[208:211], v[130:131], off
	global_load_dwordx4 v[216:219], v[130:131], off offset:256
	v_mul_f32_e32 v124, 0xbfb8aa3b, v124
	v_exp_f32_e32 v124, v124
	v_mul_f32_e32 v120, 0xbfb8aa3b, v120
	v_exp_f32_e32 v120, v120
	v_mul_f32_e32 v125, 0xbfb8aa3b, v125
	v_add_f32_e32 v124, 1.0, v124
	v_rcp_f32_e32 v225, v124
	v_or_b32_e32 v194, 16, v190
	v_or_b32_e32 v192, 32, v190
	v_or_b32_e32 v124, 48, v190
	v_exp_f32_e32 v224, v125
	v_add_f32_e32 v120, 1.0, v120
	s_or_b32 s11, s30, s28
	v_ashrrev_i32_e32 v195, 31, v194
	v_ashrrev_i32_e32 v193, 31, v192
	v_ashrrev_i32_e32 v125, 31, v124
	v_cmp_gt_u32_e32 vcc, 16, v134
	v_rcp_f32_e32 v226, v120
	v_add_u32_e32 v120, s11, v128
	v_lshlrev_b64 v[128:129], 11, v[190:191]
	v_lshlrev_b64 v[134:135], 10, v[194:195]
	v_lshlrev_b64 v[136:137], 10, v[192:193]
	v_lshlrev_b64 v[138:139], 10, v[124:125]
	v_lshl_add_u64 v[220:221], s[26:27], 0, v[128:129]
	v_lshl_add_u64 v[128:129], v[134:135], 0, v[188:189]
	v_lshl_add_u64 v[134:135], v[136:137], 0, v[188:189]
	v_lshl_add_u64 v[136:137], v[138:139], 0, v[188:189]
	v_lshlrev_b64 v[128:129], 1, v[128:129]
	v_lshlrev_b64 v[134:135], 1, v[134:135]
	v_lshlrev_b64 v[132:133], 1, v[136:137]
	v_lshl_add_u64 v[130:131], s[38:39], 0, v[128:129]
	v_lshl_add_u64 v[128:129], s[26:27], 0, v[128:129]
	v_lshl_add_u64 v[136:137], s[38:39], 0, v[134:135]
	v_lshl_add_u64 v[134:135], s[26:27], 0, v[134:135]
	v_lshl_add_u64 v[138:139], s[38:39], 0, v[132:133]
	v_lshl_add_u64 v[222:223], s[26:27], 0, v[132:133]
	global_load_dwordx4 v[172:175], v[130:131], off
	global_load_dwordx4 v[164:167], v[130:131], off offset:256
	global_load_dwordx4 v[168:171], v[128:129], off
	global_load_dwordx4 v[160:163], v[128:129], off offset:256
	global_load_dwordx4 v[156:159], v[136:137], off
	global_load_dwordx4 v[148:151], v[136:137], off offset:256
	global_load_dwordx4 v[152:155], v[134:135], off
	global_load_dwordx4 v[144:147], v[134:135], off offset:256
	global_load_dwordx4 v[140:143], v[138:139], off
	s_nop 0
	global_load_dwordx4 v[132:135], v[138:139], off offset:256
	s_nop 0
	global_load_dwordx4 v[136:139], v[222:223], off
	global_load_dwordx4 v[128:131], v[222:223], off offset:256
	v_mul_f32_e32 v121, 0xbfb8aa3b, v121
	v_exp_f32_e32 v121, v121
	v_mul_f32_e32 v126, 0xbfb8aa3b, v126
	v_exp_f32_e32 v126, v126
	v_mul_f32_e32 v112, 0xbfb8aa3b, v112
	v_add_f32_e32 v121, 1.0, v121
	v_rcp_f32_e32 v121, v121
	v_exp_f32_e32 v112, v112
	v_mul_f32_e32 v122, 0xbfb8aa3b, v122
	v_mul_f32_e32 v123, 0xbfb8aa3b, v123
	v_exp_f32_e32 v122, v122
	v_exp_f32_e32 v123, v123
	v_add_f32_e32 v112, 1.0, v112
	v_mul_f32_e32 v113, 0xbfb8aa3b, v113
	v_rcp_f32_e32 v112, v112
	v_exp_f32_e32 v113, v113
	v_add_f32_e32 v224, 1.0, v224
	v_add_f32_e32 v122, 1.0, v122
	v_add_f32_e32 v123, 1.0, v123
	v_rcp_f32_e32 v224, v224
	v_rcp_f32_e32 v122, v122
	v_rcp_f32_e32 v123, v123
	v_mul_f32_e32 v114, 0xbfb8aa3b, v114
	v_exp_f32_e32 v114, v114
	v_mul_f32_e32 v116, 0xbfb8aa3b, v116
	v_exp_f32_e32 v116, v116
	v_mul_f32_e32 v117, 0xbfb8aa3b, v117
	v_exp_f32_e32 v117, v117
	v_mul_f32_e32 v115, 0xbfb8aa3b, v115
	v_add_f32_e32 v116, 1.0, v116
	v_rcp_f32_e32 v116, v116
	v_add_f32_e32 v117, 1.0, v117
	v_rcp_f32_e32 v117, v117
	v_exp_f32_e32 v115, v115
	s_waitcnt vmcnt(0)
	v_lshlrev_b32_e32 v229, 16, v206
	v_and_b32_e32 v230, 0xffff0000, v206
	v_lshlrev_b32_e32 v231, 16, v207
	v_and_b32_e32 v232, 0xffff0000, v207
	v_lshlrev_b32_e32 v206, 16, v209
	v_and_b32_e32 v207, 0xffff0000, v209
	v_and_b32_e32 v209, 0xffff0000, v210
	v_fmac_f32_e32 v230, v121, v209
	v_add_f32_e32 v121, 1.0, v126
	v_mul_f32_e32 v126, 0xbfb8aa3b, v127
	v_rcp_f32_e32 v121, v121
	v_exp_f32_e32 v126, v126
	v_lshlrev_b32_e32 v222, 16, v204
	v_and_b32_e32 v223, 0xffff0000, v204
	v_lshlrev_b32_e32 v227, 16, v205
	v_and_b32_e32 v228, 0xffff0000, v205
	v_lshlrev_b32_e32 v204, 16, v208
	v_and_b32_e32 v205, 0xffff0000, v208
	v_lshlrev_b32_e32 v208, 16, v210
	v_fmac_f32_e32 v229, v226, v208
	v_add_f32_e32 v126, 1.0, v126
	v_fmac_f32_e32 v227, v121, v206
	v_lshlrev_b32_e32 v127, 16, v213
	v_and_b32_e32 v208, 0xffff0000, v213
	v_lshlrev_b32_e32 v209, 16, v214
	v_lshlrev_b32_e32 v121, 16, v216
	v_and_b32_e32 v213, 0xffff0000, v216
	v_lshlrev_b32_e32 v216, 16, v218
	v_rcp_f32_e32 v126, v126
	v_fmac_f32_e32 v209, v112, v216
	v_add_f32_e32 v112, 1.0, v113
	v_mul_f32_e32 v113, 0xbfb8aa3b, v118
	v_rcp_f32_e32 v112, v112
	v_exp_f32_e32 v113, v113
	v_lshlrev_b32_e32 v210, 16, v211
	v_and_b32_e32 v211, 0xffff0000, v211
	v_fmac_f32_e32 v223, v224, v205
	v_fmac_f32_e32 v231, v122, v210
	v_fmac_f32_e32 v228, v126, v207
	v_fmac_f32_e32 v232, v123, v211
	v_lshlrev_b32_e32 v123, 16, v212
	v_and_b32_e32 v126, 0xffff0000, v212
; __device__ __forceinline__ unsigned cvt_pk(float lo, float hi) { unsigned r; asm("v_cvt_pk_bf16_f32 %0, %1, %2" : "=v"(r) : "v"(lo), "v"(hi)); return r; }
; __device__ __forceinline__ float fexp2(float x) { return __builtin_amdgcn_exp2f(x); }
; __device__ __forceinline__ float frcp(float x) { return __builtin_amdgcn_rcpf(x); }
;     __device__ __forceinline__ void operator()(AccRef acc, const pg8::Unit& u, int wr, int wc, int, int) const {
;     ...
;             for (int m = 0; m < 4; ++m) {
;                 const int row = u.pm * 256 + ai * 128 + wr * 64 + m * 16 + fr;
;                 float ss = 0.f;
; #pragma unroll
;                 for (int bj = 0; bj < 2; ++bj) {
;                     const int c0 = u.pn * 256 + bj * 128 + wc * 32 + 8 * fq;
;                     const v4u hw = hwv[m][bj], pw = pwv[m][bj];
;                     const float hh[8] = {bf_lo(hw.x), bf_hi(hw.x), bf_lo(hw.y), bf_hi(hw.y), bf_lo(hw.z), bf_hi(hw.z), bf_lo(hw.w), bf_hi(hw.w)};
;                     const float pp[8] = {bf_lo(pw.x), bf_hi(pw.x), bf_lo(pw.y), bf_hi(pw.y), bf_lo(pw.z), bf_hi(pw.z), bf_lo(pw.w), bf_hi(pw.w)};
;                     float o[8];
; #pragma unroll
;                     for (int j = 0; j < 4; ++j) {
;                         o[j] = hh[j] + pp[j] * frcp(1.0f + fexp2(-acc[ai][bj][m][0][j] * LOG2E));
;                         o[4 + j] = hh[4 + j] + pp[4 + j] * frcp(1.0f + fexp2(-acc[ai][bj][m][1][j] * LOG2E));
;                     }
;                     v4u w; w.x = cvt_pk(o[0], o[1]); w.y = cvt_pk(o[2], o[3]); w.z = cvt_pk(o[4], o[5]); w.w = cvt_pk(o[6], o[7]);
;                     *(v4u*)(XB + (size_t)row * DM + c0) = w;
; #pragma unroll
;                     for (int j = 0; j < 8; ++j) ss += o[j] * o[j];
;                 }
;                 ss += __shfl_xor(ss, 16); ss += __shfl_xor(ss, 32);
;                 if (fq == 0) __hip_atomic_fetch_add(ssq + row, ss, __ATOMIC_RELAXED, __HIP_MEMORY_SCOPE_AGENT);
;             }
	v_and_b32_e32 v210, 0xffff0000, v214
	v_lshlrev_b32_e32 v211, 16, v215
	v_and_b32_e32 v212, 0xffff0000, v215
	v_lshlrev_b32_e32 v214, 16, v217
	v_and_b32_e32 v215, 0xffff0000, v217
	v_and_b32_e32 v217, 0xffff0000, v218
	v_fmac_f32_e32 v222, v225, v204
	v_mul_f32_e32 v122, v223, v223
	v_fmac_f32_e32 v210, v112, v217
	v_add_f32_e32 v112, 1.0, v113
	v_add_f32_e32 v113, 1.0, v114
	v_mul_f32_e32 v114, 0xbfb8aa3b, v119
	v_fmac_f32_e32 v122, v222, v222
	v_exp_f32_e32 v114, v114
	v_fmac_f32_e32 v122, v227, v227
	v_fmac_f32_e32 v122, v228, v228
	v_fmac_f32_e32 v122, v229, v229
	v_fmac_f32_e32 v122, v230, v230
	v_rcp_f32_e32 v112, v112
	v_add_f32_e32 v114, 1.0, v114
	v_fmac_f32_e32 v122, v231, v231
	v_rcp_f32_e32 v114, v114
	v_fmac_f32_e32 v122, v232, v232
	v_fmac_f32_e32 v123, v116, v121
	v_fmac_f32_e32 v126, v117, v213
	v_fmac_f32_e32 v122, v123, v123
	v_rcp_f32_e32 v113, v113
	v_add_f32_e32 v115, 1.0, v115
	v_fmac_f32_e32 v127, v112, v214
	v_fmac_f32_e32 v122, v126, v126
	v_rcp_f32_e32 v115, v115
	v_fmac_f32_e32 v208, v114, v215
	v_fmac_f32_e32 v122, v127, v127
	v_fmac_f32_e32 v122, v208, v208
	v_lshlrev_b32_e32 v218, 16, v219
	v_fmac_f32_e32 v122, v209, v209
	v_and_b32_e32 v219, 0xffff0000, v219
	v_fmac_f32_e32 v211, v113, v218
	v_fmac_f32_e32 v122, v210, v210
	v_fmac_f32_e32 v212, v115, v219
	v_fmac_f32_e32 v122, v211, v211
	v_fmac_f32_e32 v122, v212, v212
	ds_bpermute_b32 v112, v197, v122
	v_ashrrev_i32_e32 v121, 31, v120
	v_lshl_add_u64 v[118:119], v[120:121], 1, v[220:221]
	v_cvt_pk_bf16_f32 v204, v222, v223
	v_cvt_pk_bf16_f32 v205, v227, v228
	s_waitcnt lgkmcnt(0)
	v_add_f32_e32 v112, v122, v112
	ds_bpermute_b32 v113, v198, v112
	v_cvt_pk_bf16_f32 v206, v229, v230
	v_cvt_pk_bf16_f32 v207, v231, v232
	global_store_dwordx4 v[118:119], v[204:207], off sc1
	v_cvt_pk_bf16_f32 v114, v123, v126
	v_cvt_pk_bf16_f32 v115, v127, v208
	v_cvt_pk_bf16_f32 v116, v209, v210
	v_cvt_pk_bf16_f32 v117, v211, v212
	global_store_dwordx4 v[118:119], v[114:117], off offset:256 sc1
	s_and_saveexec_b64 s[30:31], vcc
	s_cbranch_execz .LBB0_1374
	s_waitcnt lgkmcnt(0)
	v_add_f32_e32 v114, v112, v113
	v_lshl_add_u64 v[112:113], v[190:191], 2, s[24:25]
	global_atomic_add_f32 v[112:113], v114, off
.LBB0_1374:
	s_or_b64 exec, exec, s[30:31]
	v_mul_f32_e32 v104, 0xbfb8aa3b, v104
	v_exp_f32_e32 v104, v104
	v_mul_f32_e32 v105, 0xbfb8aa3b, v105
	v_exp_f32_e32 v105, v105
	v_lshlrev_b32_e32 v114, 16, v172
	v_add_f32_e32 v104, 1.0, v104
	v_rcp_f32_e32 v104, v104
	v_and_b32_e32 v115, 0xffff0000, v172
	v_lshlrev_b32_e32 v118, 16, v174
	v_lshlrev_b32_e32 v172, 16, v170
	v_fmac_f32_e32 v118, v104, v172
	v_add_f32_e32 v104, 1.0, v105
	v_mul_f32_e32 v105, 0xbfb8aa3b, v110
	v_mul_f32_e32 v106, 0xbfb8aa3b, v106
	v_rcp_f32_e32 v104, v104
	v_exp_f32_e32 v105, v105
	v_exp_f32_e32 v106, v106
	v_mul_f32_e32 v109, 0xbfb8aa3b, v109
	v_mul_f32_e32 v108, 0xbfb8aa3b, v108
	v_exp_f32_e32 v109, v109
	v_and_b32_e32 v119, 0xffff0000, v174
	v_exp_f32_e32 v108, v108
	v_and_b32_e32 v170, 0xffff0000, v170
	v_fmac_f32_e32 v119, v104, v170
	v_add_f32_e32 v104, 1.0, v105
	v_add_f32_e32 v105, 1.0, v106
	v_mul_f32_e32 v106, 0xbfb8aa3b, v111
	v_exp_f32_e32 v106, v106
	v_add_f32_e32 v109, 1.0, v109
	v_add_f32_e32 v108, 1.0, v108
	v_rcp_f32_e32 v109, v109
	v_mul_f32_e32 v107, 0xbfb8aa3b, v107
	v_rcp_f32_e32 v108, v108
	v_exp_f32_e32 v107, v107
	v_mul_f32_e32 v96, 0xbfb8aa3b, v96
	v_rcp_f32_e32 v104, v104
	v_add_f32_e32 v106, 1.0, v106
	v_exp_f32_e32 v96, v96
	v_and_b32_e32 v127, 0xffff0000, v168
	v_rcp_f32_e32 v106, v106
	v_lshlrev_b32_e32 v126, 16, v168
	v_fmac_f32_e32 v115, v109, v127
	v_lshlrev_b32_e32 v116, 16, v173
	v_lshlrev_b32_e32 v168, 16, v169
	v_fmac_f32_e32 v114, v108, v126
	v_add_f32_e32 v107, 1.0, v107
	v_mul_f32_e32 v108, v115, v115
	v_and_b32_e32 v117, 0xffff0000, v173
	v_and_b32_e32 v169, 0xffff0000, v169
	v_rcp_f32_e32 v107, v107
	v_fmac_f32_e32 v116, v104, v168
	v_fmac_f32_e32 v108, v114, v114
	v_add_f32_e32 v96, 1.0, v96
	v_mul_f32_e32 v97, 0xbfb8aa3b, v97
	v_fmac_f32_e32 v117, v106, v169
	v_fmac_f32_e32 v108, v116, v116
	v_rcp_f32_e32 v96, v96
	v_exp_f32_e32 v97, v97
	v_fmac_f32_e32 v108, v117, v117
	v_and_b32_e32 v123, 0xffff0000, v175
	v_lshlrev_b32_e32 v173, 16, v171
	v_and_b32_e32 v171, 0xffff0000, v171
	v_fmac_f32_e32 v108, v118, v118
	v_fmac_f32_e32 v123, v107, v171
	v_cvt_pk_bf16_f32 v104, v114, v115
	v_cvt_pk_bf16_f32 v106, v118, v119
	v_fmac_f32_e32 v108, v119, v119
	v_lshlrev_b32_e32 v115, 16, v166
	v_lshlrev_b32_e32 v107, 16, v160
	v_and_b32_e32 v119, 0xffff0000, v160
	v_lshlrev_b32_e32 v160, 16, v162
	v_rcp_f32_e32 v105, v105
	v_fmac_f32_e32 v115, v96, v160
	v_add_f32_e32 v96, 1.0, v97
	v_mul_f32_e32 v97, 0xbfb8aa3b, v102
	v_mul_f32_e32 v98, 0xbfb8aa3b, v98
	v_rcp_f32_e32 v96, v96
	v_exp_f32_e32 v97, v97
	v_exp_f32_e32 v98, v98
	v_mul_f32_e32 v100, 0xbfb8aa3b, v100
	v_lshlrev_b32_e32 v122, 16, v175
	v_exp_f32_e32 v100, v100
	v_mul_f32_e32 v101, 0xbfb8aa3b, v101
	v_fmac_f32_e32 v122, v105, v173
	v_cvt_pk_bf16_f32 v105, v116, v117
	v_and_b32_e32 v116, 0xffff0000, v166
	v_lshlrev_b32_e32 v126, 16, v161
	v_and_b32_e32 v127, 0xffff0000, v161
	v_and_b32_e32 v161, 0xffff0000, v162
	v_exp_f32_e32 v101, v101
	v_fmac_f32_e32 v116, v96, v161
	v_add_f32_e32 v96, 1.0, v97
	v_add_f32_e32 v97, 1.0, v98
	v_mul_f32_e32 v98, 0xbfb8aa3b, v103
	v_exp_f32_e32 v98, v98
	v_add_f32_e32 v100, 1.0, v100
	v_rcp_f32_e32 v100, v100
	v_add_f32_e32 v101, 1.0, v101
	v_rcp_f32_e32 v101, v101
	v_mul_f32_e32 v99, 0xbfb8aa3b, v99
	v_rcp_f32_e32 v96, v96
	v_exp_f32_e32 v99, v99
	v_add_f32_e32 v98, 1.0, v98
	v_fmac_f32_e32 v108, v122, v122
	v_lshlrev_b32_e32 v109, 16, v164
	v_rcp_f32_e32 v98, v98
	v_fmac_f32_e32 v108, v123, v123
	v_and_b32_e32 v110, 0xffff0000, v164
	v_fmac_f32_e32 v109, v100, v107
	v_lshlrev_b32_e32 v111, 16, v165
	v_fmac_f32_e32 v110, v101, v119
	v_fmac_f32_e32 v108, v109, v109
	v_and_b32_e32 v114, 0xffff0000, v165
	v_rcp_f32_e32 v97, v97
	v_add_f32_e32 v99, 1.0, v99
	v_fmac_f32_e32 v111, v96, v126
	v_fmac_f32_e32 v108, v110, v110
	v_rcp_f32_e32 v99, v99
	v_fmac_f32_e32 v114, v98, v127
	v_fmac_f32_e32 v108, v111, v111
	v_fmac_f32_e32 v108, v114, v114
	v_lshlrev_b32_e32 v117, 16, v167
	v_lshlrev_b32_e32 v162, 16, v163
	v_fmac_f32_e32 v108, v115, v115
	v_and_b32_e32 v118, 0xffff0000, v167
	v_and_b32_e32 v163, 0xffff0000, v163
	v_fmac_f32_e32 v117, v97, v162
	v_fmac_f32_e32 v108, v116, v116
	v_fmac_f32_e32 v118, v99, v163
	v_fmac_f32_e32 v108, v117, v117
	v_fmac_f32_e32 v108, v118, v118
	ds_bpermute_b32 v96, v197, v108
	s_waitcnt lgkmcnt(1)
; __device__ __forceinline__ unsigned cvt_pk(float lo, float hi) { unsigned r; asm("v_cvt_pk_bf16_f32 %0, %1, %2" : "=v"(r) : "v"(lo), "v"(hi)); return r; }
; __device__ __forceinline__ float fexp2(float x) { return __builtin_amdgcn_exp2f(x); }
; __device__ __forceinline__ float frcp(float x) { return __builtin_amdgcn_rcpf(x); }
;     __device__ __forceinline__ void operator()(AccRef acc, const pg8::Unit& u, int wr, int wc, int, int) const {
;     ...
;                 for (int bj = 0; bj < 2; ++bj) {
;                     const int c0 = u.pn * 256 + bj * 128 + wc * 32 + 8 * fq;
;                     const v4u hw = hwv[m][bj], pw = pwv[m][bj];
;                     const float hh[8] = {bf_lo(hw.x), bf_hi(hw.x), bf_lo(hw.y), bf_hi(hw.y), bf_lo(hw.z), bf_hi(hw.z), bf_lo(hw.w), bf_hi(hw.w)};
;                     const float pp[8] = {bf_lo(pw.x), bf_hi(pw.x), bf_lo(pw.y), bf_hi(pw.y), bf_lo(pw.z), bf_hi(pw.z), bf_lo(pw.w), bf_hi(pw.w)};
;                     float o[8];
; #pragma unroll
;                     for (int j = 0; j < 4; ++j) {
;                         o[j] = hh[j] + pp[j] * frcp(1.0f + fexp2(-acc[ai][bj][m][0][j] * LOG2E));
;                         o[4 + j] = hh[4 + j] + pp[4 + j] * frcp(1.0f + fexp2(-acc[ai][bj][m][1][j] * LOG2E));
;                     }
;                     v4u w; w.x = cvt_pk(o[0], o[1]); w.y = cvt_pk(o[2], o[3]); w.z = cvt_pk(o[4], o[5]); w.w = cvt_pk(o[6], o[7]);
;                     *(v4u*)(XB + (size_t)row * DM + c0) = w;
; #pragma unroll
;                     for (int j = 0; j < 8; ++j) ss += o[j] * o[j];
;                 }
;                 ss += __shfl_xor(ss, 16); ss += __shfl_xor(ss, 32);
;                 if (fq == 0) __hip_atomic_fetch_add(ssq + row, ss, __ATOMIC_RELAXED, __HIP_MEMORY_SCOPE_AGENT);
;             }
	v_lshlrev_b64 v[112:113], 11, v[194:195]
	v_lshl_add_u64 v[112:113], s[26:27], 0, v[112:113]
	v_lshl_add_u64 v[102:103], v[120:121], 1, v[112:113]
	v_cvt_pk_bf16_f32 v107, v122, v123
	s_waitcnt lgkmcnt(0)
	v_add_f32_e32 v96, v108, v96
	ds_bpermute_b32 v97, v198, v96
	global_store_dwordx4 v[102:103], v[104:107], off sc1
	v_cvt_pk_bf16_f32 v98, v109, v110
	v_cvt_pk_bf16_f32 v99, v111, v114
	v_cvt_pk_bf16_f32 v100, v115, v116
	v_cvt_pk_bf16_f32 v101, v117, v118
	global_store_dwordx4 v[102:103], v[98:101], off offset:256 sc1
	s_and_saveexec_b64 s[30:31], vcc
	s_cbranch_execz .LBB0_1376
	s_waitcnt lgkmcnt(0)
	v_add_f32_e32 v98, v96, v97
	v_lshl_add_u64 v[96:97], v[194:195], 2, s[24:25]
	global_atomic_add_f32 v[96:97], v98, off
.LBB0_1376:
	s_or_b64 exec, exec, s[30:31]
	v_mul_f32_e32 v88, 0xbfb8aa3b, v88
	v_exp_f32_e32 v88, v88
	v_mul_f32_e32 v89, 0xbfb8aa3b, v89
	v_exp_f32_e32 v89, v89
	v_lshlrev_b32_e32 v102, 16, v158
	v_add_f32_e32 v88, 1.0, v88
	v_rcp_f32_e32 v88, v88
	v_lshlrev_b32_e32 v110, 16, v154
	v_mul_f32_e32 v93, 0xbfb8aa3b, v93
	v_mul_f32_e32 v92, 0xbfb8aa3b, v92
	v_exp_f32_e32 v93, v93
	v_fmac_f32_e32 v102, v88, v110
	v_add_f32_e32 v88, 1.0, v89
	v_mul_f32_e32 v89, 0xbfb8aa3b, v94
	v_mul_f32_e32 v90, 0xbfb8aa3b, v90
	v_exp_f32_e32 v92, v92
	v_rcp_f32_e32 v88, v88
	v_exp_f32_e32 v89, v89
	v_exp_f32_e32 v90, v90
	v_mul_f32_e32 v80, 0xbfb8aa3b, v80
	v_exp_f32_e32 v80, v80
	v_and_b32_e32 v103, 0xffff0000, v158
	v_and_b32_e32 v111, 0xffff0000, v154
	v_add_f32_e32 v93, 1.0, v93
	v_add_f32_e32 v92, 1.0, v92
	v_rcp_f32_e32 v93, v93
	v_fmac_f32_e32 v103, v88, v111
	v_add_f32_e32 v88, 1.0, v89
	v_add_f32_e32 v89, 1.0, v90
	v_mul_f32_e32 v90, 0xbfb8aa3b, v95
	v_rcp_f32_e32 v92, v92
	v_rcp_f32_e32 v88, v88
	v_exp_f32_e32 v90, v90
	v_add_f32_e32 v80, 1.0, v80
	v_mul_f32_e32 v81, 0xbfb8aa3b, v81
	v_rcp_f32_e32 v80, v80
	v_exp_f32_e32 v81, v81
	v_and_b32_e32 v99, 0xffff0000, v156
	v_and_b32_e32 v107, 0xffff0000, v152
	v_lshlrev_b32_e32 v98, 16, v156
	v_lshlrev_b32_e32 v100, 16, v157
	v_lshlrev_b32_e32 v106, 16, v152
	v_lshlrev_b32_e32 v108, 16, v153
	v_fmac_f32_e32 v99, v93, v107
	v_fmac_f32_e32 v98, v92, v106
	v_add_f32_e32 v90, 1.0, v90
	v_fmac_f32_e32 v100, v88, v108
	v_cvt_pk_bf16_f32 v88, v98, v99
	v_mul_f32_e32 v92, v99, v99
	v_lshlrev_b32_e32 v99, 16, v150
	v_lshlrev_b32_e32 v108, 16, v146
	v_rcp_f32_e32 v89, v89
	v_rcp_f32_e32 v90, v90
	v_fmac_f32_e32 v99, v80, v108
	v_add_f32_e32 v80, 1.0, v81
	v_mul_f32_e32 v81, 0xbfb8aa3b, v86
	v_mul_f32_e32 v82, 0xbfb8aa3b, v82
	v_mul_f32_e32 v91, 0xbfb8aa3b, v91
	v_rcp_f32_e32 v80, v80
	v_exp_f32_e32 v81, v81
	v_exp_f32_e32 v82, v82
	v_exp_f32_e32 v91, v91
	v_mul_f32_e32 v84, 0xbfb8aa3b, v84
	v_and_b32_e32 v101, 0xffff0000, v157
	v_lshlrev_b32_e32 v104, 16, v159
	v_and_b32_e32 v109, 0xffff0000, v153
	v_lshlrev_b32_e32 v112, 16, v155
	v_fmac_f32_e32 v92, v98, v98
	v_exp_f32_e32 v84, v84
	v_mul_f32_e32 v85, 0xbfb8aa3b, v85
	v_fmac_f32_e32 v104, v89, v112
	v_fmac_f32_e32 v101, v90, v109
	v_cvt_pk_bf16_f32 v89, v100, v101
	v_fmac_f32_e32 v92, v100, v100
	v_and_b32_e32 v100, 0xffff0000, v150
	v_and_b32_e32 v109, 0xffff0000, v146
	v_exp_f32_e32 v85, v85
	v_fmac_f32_e32 v100, v80, v109
	v_add_f32_e32 v80, 1.0, v81
	v_add_f32_e32 v81, 1.0, v82
	v_mul_f32_e32 v82, 0xbfb8aa3b, v87
	v_add_f32_e32 v91, 1.0, v91
	v_exp_f32_e32 v82, v82
	v_rcp_f32_e32 v91, v91
	v_add_f32_e32 v84, 1.0, v84
	v_fmac_f32_e32 v92, v101, v101
	v_rcp_f32_e32 v84, v84
	v_add_f32_e32 v85, 1.0, v85
	v_fmac_f32_e32 v92, v102, v102
	v_rcp_f32_e32 v85, v85
	v_mul_f32_e32 v83, 0xbfb8aa3b, v83
	v_and_b32_e32 v105, 0xffff0000, v159
	v_and_b32_e32 v113, 0xffff0000, v155
	v_fmac_f32_e32 v92, v103, v103
	v_rcp_f32_e32 v80, v80
	v_exp_f32_e32 v83, v83
	v_add_f32_e32 v82, 1.0, v82
	v_fmac_f32_e32 v105, v91, v113
	v_fmac_f32_e32 v92, v104, v104
	v_lshlrev_b32_e32 v93, 16, v148
	v_lshlrev_b32_e32 v91, 16, v144
	v_rcp_f32_e32 v82, v82
	v_cvt_pk_bf16_f32 v90, v102, v103
	v_fmac_f32_e32 v92, v105, v105
	v_and_b32_e32 v94, 0xffff0000, v148
	v_and_b32_e32 v103, 0xffff0000, v144
	v_fmac_f32_e32 v93, v84, v91
	v_lshlrev_b32_e32 v95, 16, v149
	v_lshlrev_b32_e32 v106, 16, v145
	v_fmac_f32_e32 v94, v85, v103
	v_fmac_f32_e32 v92, v93, v93
	v_and_b32_e32 v98, 0xffff0000, v149
	v_and_b32_e32 v107, 0xffff0000, v145
	v_rcp_f32_e32 v81, v81
	v_add_f32_e32 v83, 1.0, v83
	v_fmac_f32_e32 v95, v80, v106
	v_fmac_f32_e32 v92, v94, v94
	v_rcp_f32_e32 v83, v83
	v_fmac_f32_e32 v98, v82, v107
	v_fmac_f32_e32 v92, v95, v95
	v_fmac_f32_e32 v92, v98, v98
	v_lshlrev_b32_e32 v101, 16, v151
	v_lshlrev_b32_e32 v110, 16, v147
	v_fmac_f32_e32 v92, v99, v99
	v_and_b32_e32 v102, 0xffff0000, v151
	v_and_b32_e32 v111, 0xffff0000, v147
	v_fmac_f32_e32 v101, v81, v110
	v_fmac_f32_e32 v92, v100, v100
	v_fmac_f32_e32 v102, v83, v111
	v_fmac_f32_e32 v92, v101, v101
	v_fmac_f32_e32 v92, v102, v102
	ds_bpermute_b32 v80, v197, v92
	s_waitcnt lgkmcnt(1)
	v_lshlrev_b64 v[96:97], 11, v[192:193]
	v_lshl_add_u64 v[96:97], s[26:27], 0, v[96:97]
	v_lshl_add_u64 v[86:87], v[120:121], 1, v[96:97]
	v_cvt_pk_bf16_f32 v91, v104, v105
	s_waitcnt lgkmcnt(0)
	v_add_f32_e32 v80, v92, v80
	ds_bpermute_b32 v81, v198, v80
	global_store_dwordx4 v[86:87], v[88:91], off sc1
	v_cvt_pk_bf16_f32 v82, v93, v94
	v_cvt_pk_bf16_f32 v83, v95, v98
	v_cvt_pk_bf16_f32 v84, v99, v100
	v_cvt_pk_bf16_f32 v85, v101, v102
	global_store_dwordx4 v[86:87], v[82:85], off offset:256 sc1
	s_and_saveexec_b64 s[30:31], vcc
	s_cbranch_execz .LBB0_1378
	s_waitcnt lgkmcnt(0)
	v_add_f32_e32 v82, v80, v81
	v_lshl_add_u64 v[80:81], v[192:193], 2, s[24:25]
	global_atomic_add_f32 v[80:81], v82, off
; __device__ __forceinline__ unsigned cvt_pk(float lo, float hi) { unsigned r; asm("v_cvt_pk_bf16_f32 %0, %1, %2" : "=v"(r) : "v"(lo), "v"(hi)); return r; }
; __device__ __forceinline__ float fexp2(float x) { return __builtin_amdgcn_exp2f(x); }
; __device__ __forceinline__ float frcp(float x) { return __builtin_amdgcn_rcpf(x); }
;     __device__ __forceinline__ void operator()(AccRef acc, const pg8::Unit& u, int wr, int wc, int, int) const {
;     ...
;                 for (int bj = 0; bj < 2; ++bj) {
;                     const int c0 = u.pn * 256 + bj * 128 + wc * 32 + 8 * fq;
;                     const v4u hw = hwv[m][bj], pw = pwv[m][bj];
;                     const float hh[8] = {bf_lo(hw.x), bf_hi(hw.x), bf_lo(hw.y), bf_hi(hw.y), bf_lo(hw.z), bf_hi(hw.z), bf_lo(hw.w), bf_hi(hw.w)};
;                     const float pp[8] = {bf_lo(pw.x), bf_hi(pw.x), bf_lo(pw.y), bf_hi(pw.y), bf_lo(pw.z), bf_hi(pw.z), bf_lo(pw.w), bf_hi(pw.w)};
;                     float o[8];
; #pragma unroll
;                     for (int j = 0; j < 4; ++j) {
;                         o[j] = hh[j] + pp[j] * frcp(1.0f + fexp2(-acc[ai][bj][m][0][j] * LOG2E));
;                         o[4 + j] = hh[4 + j] + pp[4 + j] * frcp(1.0f + fexp2(-acc[ai][bj][m][1][j] * LOG2E));
;                     }
;                     v4u w; w.x = cvt_pk(o[0], o[1]); w.y = cvt_pk(o[2], o[3]); w.z = cvt_pk(o[4], o[5]); w.w = cvt_pk(o[6], o[7]);
;                     *(v4u*)(XB + (size_t)row * DM + c0) = w;
; #pragma unroll
;                     for (int j = 0; j < 8; ++j) ss += o[j] * o[j];
;                 }
;                 ss += __shfl_xor(ss, 16); ss += __shfl_xor(ss, 32);
;                 if (fq == 0) __hip_atomic_fetch_add(ssq + row, ss, __ATOMIC_RELAXED, __HIP_MEMORY_SCOPE_AGENT);
;             }
.LBB0_1378:
	s_or_b64 exec, exec, s[30:31]
	v_mul_f32_e32 v72, 0xbfb8aa3b, v72
	v_exp_f32_e32 v72, v72
	v_mul_f32_e32 v73, 0xbfb8aa3b, v73
	v_exp_f32_e32 v73, v73
	v_lshlrev_b32_e32 v86, 16, v142
	v_add_f32_e32 v72, 1.0, v72
	v_rcp_f32_e32 v72, v72
	v_lshlrev_b32_e32 v94, 16, v138
	v_mul_f32_e32 v77, 0xbfb8aa3b, v77
	v_mul_f32_e32 v76, 0xbfb8aa3b, v76
	v_exp_f32_e32 v77, v77
	v_fmac_f32_e32 v86, v72, v94
	v_add_f32_e32 v72, 1.0, v73
	v_mul_f32_e32 v73, 0xbfb8aa3b, v78
	v_mul_f32_e32 v74, 0xbfb8aa3b, v74
	v_exp_f32_e32 v76, v76
	v_rcp_f32_e32 v72, v72
	v_exp_f32_e32 v73, v73
	v_exp_f32_e32 v74, v74
	v_mul_f32_e32 v64, 0xbfb8aa3b, v64
	v_exp_f32_e32 v64, v64
	v_and_b32_e32 v87, 0xffff0000, v142
	v_and_b32_e32 v95, 0xffff0000, v138
	v_add_f32_e32 v77, 1.0, v77
	v_add_f32_e32 v76, 1.0, v76
	v_rcp_f32_e32 v77, v77
	v_fmac_f32_e32 v87, v72, v95
	v_add_f32_e32 v72, 1.0, v73
	v_add_f32_e32 v73, 1.0, v74
	v_mul_f32_e32 v74, 0xbfb8aa3b, v79
	v_rcp_f32_e32 v76, v76
	v_rcp_f32_e32 v72, v72
	v_exp_f32_e32 v74, v74
	v_add_f32_e32 v64, 1.0, v64
	v_mul_f32_e32 v65, 0xbfb8aa3b, v65
	v_rcp_f32_e32 v64, v64
	v_exp_f32_e32 v65, v65
	v_and_b32_e32 v83, 0xffff0000, v140
	v_and_b32_e32 v91, 0xffff0000, v136
	v_lshlrev_b32_e32 v82, 16, v140
	v_lshlrev_b32_e32 v84, 16, v141
	v_lshlrev_b32_e32 v90, 16, v136
	v_lshlrev_b32_e32 v92, 16, v137
	v_fmac_f32_e32 v83, v77, v91
	v_fmac_f32_e32 v82, v76, v90
	v_add_f32_e32 v74, 1.0, v74
	v_fmac_f32_e32 v84, v72, v92
	v_cvt_pk_bf16_f32 v72, v82, v83
	v_mul_f32_e32 v76, v83, v83
	v_lshlrev_b32_e32 v83, 16, v134
	v_lshlrev_b32_e32 v92, 16, v130
	v_rcp_f32_e32 v73, v73
	v_rcp_f32_e32 v74, v74
	v_fmac_f32_e32 v83, v64, v92
	v_add_f32_e32 v64, 1.0, v65
	v_mul_f32_e32 v65, 0xbfb8aa3b, v70
	v_mul_f32_e32 v66, 0xbfb8aa3b, v66
	v_mul_f32_e32 v75, 0xbfb8aa3b, v75
	v_rcp_f32_e32 v64, v64
	v_exp_f32_e32 v65, v65
	v_exp_f32_e32 v66, v66
	v_exp_f32_e32 v75, v75
	v_mul_f32_e32 v68, 0xbfb8aa3b, v68
	v_and_b32_e32 v85, 0xffff0000, v141
	v_lshlrev_b32_e32 v88, 16, v143
	v_and_b32_e32 v93, 0xffff0000, v137
	v_lshlrev_b32_e32 v96, 16, v139
	v_fmac_f32_e32 v76, v82, v82
	v_exp_f32_e32 v68, v68
	v_mul_f32_e32 v69, 0xbfb8aa3b, v69
	v_fmac_f32_e32 v88, v73, v96
	v_fmac_f32_e32 v85, v74, v93
	v_cvt_pk_bf16_f32 v73, v84, v85
	v_fmac_f32_e32 v76, v84, v84
	v_and_b32_e32 v84, 0xffff0000, v134
	v_and_b32_e32 v93, 0xffff0000, v130
	v_exp_f32_e32 v69, v69
	v_fmac_f32_e32 v84, v64, v93
	v_add_f32_e32 v64, 1.0, v65
	v_add_f32_e32 v65, 1.0, v66
	v_mul_f32_e32 v66, 0xbfb8aa3b, v71
	v_add_f32_e32 v75, 1.0, v75
	v_exp_f32_e32 v66, v66
	v_rcp_f32_e32 v75, v75
	v_add_f32_e32 v68, 1.0, v68
	v_fmac_f32_e32 v76, v85, v85
	v_rcp_f32_e32 v68, v68
	v_add_f32_e32 v69, 1.0, v69
	v_fmac_f32_e32 v76, v86, v86
	v_rcp_f32_e32 v69, v69
	v_mul_f32_e32 v67, 0xbfb8aa3b, v67
	v_and_b32_e32 v89, 0xffff0000, v143
	v_and_b32_e32 v97, 0xffff0000, v139
	v_fmac_f32_e32 v76, v87, v87
	v_rcp_f32_e32 v64, v64
	v_exp_f32_e32 v67, v67
	v_add_f32_e32 v66, 1.0, v66
	v_fmac_f32_e32 v89, v75, v97
	v_fmac_f32_e32 v76, v88, v88
	v_lshlrev_b32_e32 v77, 16, v132
	v_lshlrev_b32_e32 v75, 16, v128
	v_rcp_f32_e32 v66, v66
	v_cvt_pk_bf16_f32 v74, v86, v87
	v_fmac_f32_e32 v76, v89, v89
	v_and_b32_e32 v78, 0xffff0000, v132
	v_and_b32_e32 v87, 0xffff0000, v128
	v_fmac_f32_e32 v77, v68, v75
	v_lshlrev_b32_e32 v79, 16, v133
	v_lshlrev_b32_e32 v90, 16, v129
	v_fmac_f32_e32 v78, v69, v87
	v_fmac_f32_e32 v76, v77, v77
	v_and_b32_e32 v82, 0xffff0000, v133
	v_and_b32_e32 v91, 0xffff0000, v129
	v_rcp_f32_e32 v65, v65
	v_add_f32_e32 v67, 1.0, v67
	v_fmac_f32_e32 v79, v64, v90
	v_fmac_f32_e32 v76, v78, v78
	v_rcp_f32_e32 v67, v67
	v_fmac_f32_e32 v82, v66, v91
	v_fmac_f32_e32 v76, v79, v79
	v_fmac_f32_e32 v76, v82, v82
	v_lshlrev_b32_e32 v85, 16, v135
	v_lshlrev_b32_e32 v94, 16, v131
	v_fmac_f32_e32 v76, v83, v83
	v_and_b32_e32 v86, 0xffff0000, v135
	v_and_b32_e32 v95, 0xffff0000, v131
	v_fmac_f32_e32 v85, v65, v94
	v_fmac_f32_e32 v76, v84, v84
	v_fmac_f32_e32 v86, v67, v95
	v_fmac_f32_e32 v76, v85, v85
	v_fmac_f32_e32 v76, v86, v86
	ds_bpermute_b32 v64, v197, v76
	s_waitcnt lgkmcnt(1)
	v_lshlrev_b64 v[80:81], 11, v[124:125]
	v_lshl_add_u64 v[80:81], s[26:27], 0, v[80:81]
	v_lshl_add_u64 v[70:71], v[120:121], 1, v[80:81]
	v_cvt_pk_bf16_f32 v75, v88, v89
	s_waitcnt lgkmcnt(0)
	v_add_f32_e32 v64, v76, v64
	ds_bpermute_b32 v65, v198, v64
	global_store_dwordx4 v[70:71], v[72:75], off sc1
	v_cvt_pk_bf16_f32 v66, v77, v78
	v_cvt_pk_bf16_f32 v67, v79, v82
	v_cvt_pk_bf16_f32 v68, v83, v84
	v_cvt_pk_bf16_f32 v69, v85, v86
	global_store_dwordx4 v[70:71], v[66:69], off offset:256 sc1
	s_and_saveexec_b64 s[30:31], vcc
	s_cbranch_execz .LBB0_1380
	s_waitcnt lgkmcnt(0)
	v_add_f32_e32 v66, v64, v65
	v_lshl_add_u64 v[64:65], v[124:125], 2, s[24:25]
	global_atomic_add_f32 v[64:65], v66, off
; __device__ __forceinline__ unsigned cvt_pk(float lo, float hi) { unsigned r; asm("v_cvt_pk_bf16_f32 %0, %1, %2" : "=v"(r) : "v"(lo), "v"(hi)); return r; }
; __device__ __forceinline__ float fexp2(float x) { return __builtin_amdgcn_exp2f(x); }
;     __device__ __forceinline__ void operator()(AccRef acc, const pg8::Unit& u, int wr, int wc, int, int) const {
;     ...
;         for (int ai = 0; ai < 2; ++ai) {
;             v4u hwv[4][2], pwv[4][2];
; #pragma unroll
;             for (int m = 0; m < 4; ++m) { const int row = u.pm * 256 + ai * 128 + wr * 64 + m * 16 + fr;
; #pragma unroll
;                 for (int bj = 0; bj < 2; ++bj) { const size_t off = (size_t)row * DM + u.pn * 256 + bj * 128 + wc * 32 + 8 * fq; hwv[m][bj] = *(const v4u*)(HB + off); pwv[m][bj] = *(const v4u*)(XB + off); } }
;             asm volatile("" ::: "memory");
; #pragma unroll
;             for (int m = 0; m < 4; ++m) {
;                 const int row = u.pm * 256 + ai * 128 + wr * 64 + m * 16 + fr;
;                 float ss = 0.f;
; #pragma unroll
;                 for (int bj = 0; bj < 2; ++bj) {
;                     const int c0 = u.pn * 256 + bj * 128 + wc * 32 + 8 * fq;
;                     const v4u hw = hwv[m][bj], pw = pwv[m][bj];
;                     const float hh[8] = {bf_lo(hw.x), bf_hi(hw.x), bf_lo(hw.y), bf_hi(hw.y), bf_lo(hw.z), bf_hi(hw.z), bf_lo(hw.w), bf_hi(hw.w)};
;                     const float pp[8] = {bf_lo(pw.x), bf_hi(pw.x), bf_lo(pw.y), bf_hi(pw.y), bf_lo(pw.z), bf_hi(pw.z), bf_lo(pw.w), bf_hi(pw.w)};
;                     float o[8];
; #pragma unroll
;                     for (int j = 0; j < 4; ++j) {
;                         o[j] = hh[j] + pp[j] * frcp(1.0f + fexp2(-acc[ai][bj][m][0][j] * LOG2E));
;                         o[4 + j] = hh[4 + j] + pp[4 + j] * frcp(1.0f + fexp2(-acc[ai][bj][m][1][j] * LOG2E));
;                     }
;                     v4u w; w.x = cvt_pk(o[0], o[1]); w.y = cvt_pk(o[2], o[3]); w.z = cvt_pk(o[4], o[5]); w.w = cvt_pk(o[6], o[7]);
;                     *(v4u*)(XB + (size_t)row * DM + c0) = w;
; #pragma unroll
;                     for (int j = 0; j < 8; ++j) ss += o[j] * o[j];
;                 }
;                 ss += __shfl_xor(ss, 16); ss += __shfl_xor(ss, 32);
;                 if (fq == 0) __hip_atomic_fetch_add(ssq + row, ss, __ATOMIC_RELAXED, __HIP_MEMORY_SCOPE_AGENT);
;             }
.LBB0_1380:
	s_or_b64 exec, exec, s[30:31]
	v_add_u32_e32 v118, 0x80, v190
	v_ashrrev_i32_e32 v119, 31, v118
	s_waitcnt lgkmcnt(0)
	v_lshlrev_b64 v[64:65], 10, v[118:119]
	v_lshl_add_u64 v[64:65], v[64:65], 0, v[188:189]
	v_lshlrev_b64 v[64:65], 1, v[64:65]
	v_lshl_add_u64 v[66:67], s[38:39], 0, v[64:65]
	v_lshl_add_u64 v[64:65], s[26:27], 0, v[64:65]
	global_load_dwordx4 v[122:125], v[66:67], off
	global_load_dwordx4 v[130:133], v[66:67], off offset:256
	global_load_dwordx4 v[126:129], v[64:65], off
	global_load_dwordx4 v[134:137], v[64:65], off offset:256
	v_add_u32_e32 v116, 0x90, v190
	v_add_u32_e32 v114, 0xa0, v190
	v_add_u32_e32 v112, 0xb0, v190
	v_mul_f32_e32 v60, 0xbfb8aa3b, v60
	v_mul_f32_e32 v56, 0xbfb8aa3b, v56
	v_mul_f32_e32 v61, 0xbfb8aa3b, v61
	v_mul_f32_e32 v57, 0xbfb8aa3b, v57
	v_ashrrev_i32_e32 v117, 31, v116
	v_ashrrev_i32_e32 v115, 31, v114
	v_ashrrev_i32_e32 v113, 31, v112
	v_exp_f32_e32 v72, v60
	v_exp_f32_e32 v73, v56
	v_exp_f32_e32 v74, v61
	v_exp_f32_e32 v75, v57
	v_lshlrev_b64 v[56:57], 10, v[116:117]
	v_lshlrev_b64 v[60:61], 10, v[114:115]
	v_lshlrev_b64 v[68:69], 10, v[112:113]
	v_lshl_add_u64 v[56:57], v[56:57], 0, v[188:189]
	v_lshl_add_u64 v[60:61], v[60:61], 0, v[188:189]
	v_lshl_add_u64 v[68:69], v[68:69], 0, v[188:189]
	v_lshlrev_b64 v[70:71], 11, v[118:119]
	v_lshlrev_b64 v[56:57], 1, v[56:57]
	v_lshlrev_b64 v[60:61], 1, v[60:61]
	v_lshlrev_b64 v[66:67], 1, v[68:69]
	v_lshl_add_u64 v[138:139], s[26:27], 0, v[70:71]
	v_lshl_add_u64 v[68:69], s[38:39], 0, v[56:57]
	v_lshl_add_u64 v[70:71], s[38:39], 0, v[60:61]
	v_lshl_add_u64 v[64:65], s[38:39], 0, v[66:67]
	v_lshl_add_u64 v[66:67], s[26:27], 0, v[66:67]
	v_lshl_add_u64 v[56:57], s[26:27], 0, v[56:57]
	v_lshl_add_u64 v[60:61], s[26:27], 0, v[60:61]
	v_add_f32_e32 v140, 1.0, v72
	v_add_f32_e32 v141, 1.0, v73
	v_add_f32_e32 v142, 1.0, v74
	v_add_f32_e32 v143, 1.0, v75
	global_load_dwordx4 v[108:111], v[68:69], off
	global_load_dwordx4 v[100:103], v[68:69], off offset:256
	global_load_dwordx4 v[104:107], v[56:57], off
	global_load_dwordx4 v[96:99], v[56:57], off offset:256
	global_load_dwordx4 v[92:95], v[70:71], off
	global_load_dwordx4 v[84:87], v[70:71], off offset:256
	global_load_dwordx4 v[88:91], v[60:61], off
	global_load_dwordx4 v[80:83], v[60:61], off offset:256
	global_load_dwordx4 v[76:79], v[64:65], off
	s_nop 0
	global_load_dwordx4 v[68:71], v[64:65], off offset:256
	global_load_dwordx4 v[72:75], v[66:67], off
	s_nop 0
	global_load_dwordx4 v[64:67], v[66:67], off offset:256
	v_mul_f32_e32 v58, 0xbfb8aa3b, v58
	v_exp_f32_e32 v58, v58
	v_rcp_f32_e32 v57, v141
	v_mul_f32_e32 v62, 0xbfb8aa3b, v62
	v_rcp_f32_e32 v60, v142
	v_exp_f32_e32 v62, v62
	v_rcp_f32_e32 v56, v140
	v_mul_f32_e32 v48, 0xbfb8aa3b, v48
	v_exp_f32_e32 v48, v48
	v_add_f32_e32 v62, 1.0, v62
	v_mul_f32_e32 v49, 0xbfb8aa3b, v49
	v_exp_f32_e32 v49, v49
	v_add_f32_e32 v48, 1.0, v48
	v_rcp_f32_e32 v48, v48
	v_rcp_f32_e32 v61, v143
	v_mul_f32_e32 v50, 0xbfb8aa3b, v50
	v_mul_f32_e32 v59, 0xbfb8aa3b, v59
	v_exp_f32_e32 v50, v50
	v_exp_f32_e32 v59, v59
	v_mul_f32_e32 v52, 0xbfb8aa3b, v52
	v_exp_f32_e32 v52, v52
	v_mul_f32_e32 v53, 0xbfb8aa3b, v53
	v_exp_f32_e32 v53, v53
	v_add_f32_e32 v59, 1.0, v59
	v_rcp_f32_e32 v59, v59
	v_add_f32_e32 v52, 1.0, v52
	v_rcp_f32_e32 v52, v52
	v_add_f32_e32 v53, 1.0, v53
	v_rcp_f32_e32 v53, v53
	v_mul_f32_e32 v51, 0xbfb8aa3b, v51
	v_exp_f32_e32 v51, v51
	s_waitcnt vmcnt(15)
	v_lshlrev_b32_e32 v142, 16, v124
	v_lshlrev_b32_e32 v140, 16, v122
	s_waitcnt vmcnt(13)
	v_lshlrev_b32_e32 v146, 16, v128
	v_fmac_f32_e32 v142, v57, v146
	v_add_f32_e32 v57, 1.0, v58
	v_mul_f32_e32 v58, 0xbfb8aa3b, v63
	v_exp_f32_e32 v58, v58
	v_lshlrev_b32_e32 v144, 16, v126
	v_fmac_f32_e32 v140, v56, v144
	v_rcp_f32_e32 v56, v62
	v_add_f32_e32 v58, 1.0, v58
	v_and_b32_e32 v122, 0xffff0000, v122
	v_and_b32_e32 v126, 0xffff0000, v126
	v_rcp_f32_e32 v58, v58
	v_fmac_f32_e32 v122, v60, v126
	v_rcp_f32_e32 v57, v57
	v_lshlrev_b32_e32 v141, 16, v123
	v_lshlrev_b32_e32 v145, 16, v127
	v_mul_f32_e32 v60, v122, v122
	v_and_b32_e32 v123, 0xffff0000, v123
	v_and_b32_e32 v127, 0xffff0000, v127
	v_fmac_f32_e32 v141, v56, v145
	v_fmac_f32_e32 v60, v140, v140
	v_lshlrev_b32_e32 v143, 16, v125
	v_lshlrev_b32_e32 v147, 16, v129
	v_fmac_f32_e32 v123, v58, v127
	v_fmac_f32_e32 v60, v141, v141
	v_fmac_f32_e32 v143, v57, v147
	v_cvt_pk_bf16_f32 v56, v140, v122
	v_cvt_pk_bf16_f32 v57, v141, v123
	v_fmac_f32_e32 v60, v123, v123
	v_lshlrev_b32_e32 v63, 16, v131
	v_and_b32_e32 v122, 0xffff0000, v131
	v_lshlrev_b32_e32 v123, 16, v132
	s_waitcnt vmcnt(12)
	v_lshlrev_b32_e32 v131, 16, v136
	v_fmac_f32_e32 v123, v48, v131
	v_add_f32_e32 v48, 1.0, v49
	v_mul_f32_e32 v49, 0xbfb8aa3b, v54
	v_rcp_f32_e32 v48, v48
	v_exp_f32_e32 v49, v49
	v_and_b32_e32 v124, 0xffff0000, v124
	v_and_b32_e32 v128, 0xffff0000, v128
	v_fmac_f32_e32 v124, v61, v128
	v_fmac_f32_e32 v60, v142, v142
	v_cvt_pk_bf16_f32 v58, v142, v124
	v_fmac_f32_e32 v60, v124, v124
	v_and_b32_e32 v124, 0xffff0000, v132
	v_and_b32_e32 v132, 0xffff0000, v136
	v_fmac_f32_e32 v124, v48, v132
	v_add_f32_e32 v48, 1.0, v49
	v_add_f32_e32 v49, 1.0, v50
	v_mul_f32_e32 v50, 0xbfb8aa3b, v55
	v_exp_f32_e32 v50, v50
	v_and_b32_e32 v125, 0xffff0000, v125
	v_and_b32_e32 v129, 0xffff0000, v129
	v_rcp_f32_e32 v48, v48
	v_add_f32_e32 v50, 1.0, v50
	v_fmac_f32_e32 v125, v59, v129
	v_fmac_f32_e32 v60, v143, v143
	v_lshlrev_b32_e32 v61, 16, v130
	v_lshlrev_b32_e32 v59, 16, v134
	v_rcp_f32_e32 v50, v50
	v_fmac_f32_e32 v60, v125, v125
	v_and_b32_e32 v62, 0xffff0000, v130
	v_and_b32_e32 v128, 0xffff0000, v134
	v_fmac_f32_e32 v61, v52, v59
	v_lshlrev_b32_e32 v129, 16, v135
	v_fmac_f32_e32 v62, v53, v128
	v_fmac_f32_e32 v60, v61, v61
	v_and_b32_e32 v130, 0xffff0000, v135
	v_rcp_f32_e32 v49, v49
	v_add_f32_e32 v51, 1.0, v51
	v_fmac_f32_e32 v63, v48, v129
	v_fmac_f32_e32 v60, v62, v62
	v_rcp_f32_e32 v51, v51
	v_fmac_f32_e32 v122, v50, v130
	v_fmac_f32_e32 v60, v63, v63
	v_fmac_f32_e32 v60, v122, v122
	v_lshlrev_b32_e32 v126, 16, v133
	v_and_b32_e32 v127, 0xffff0000, v133
	v_lshlrev_b32_e32 v133, 16, v137
	v_fmac_f32_e32 v60, v123, v123
	v_and_b32_e32 v134, 0xffff0000, v137
	v_fmac_f32_e32 v126, v49, v133
	v_fmac_f32_e32 v60, v124, v124
	v_fmac_f32_e32 v127, v51, v134
	v_fmac_f32_e32 v60, v126, v126
	v_fmac_f32_e32 v60, v127, v127
	ds_bpermute_b32 v48, v197, v60
	v_lshl_add_u64 v[54:55], v[120:121], 1, v[138:139]
	v_cvt_pk_bf16_f32 v59, v143, v125
	global_store_dwordx4 v[54:55], v[56:59], off sc1
	v_cvt_pk_bf16_f32 v50, v61, v62
	s_waitcnt lgkmcnt(0)
	v_add_f32_e32 v48, v60, v48
	ds_bpermute_b32 v49, v198, v48
	v_cvt_pk_bf16_f32 v51, v63, v122
	v_cvt_pk_bf16_f32 v52, v123, v124
	v_cvt_pk_bf16_f32 v53, v126, v127
	global_store_dwordx4 v[54:55], v[50:53], off offset:256 sc1
	s_and_saveexec_b64 s[30:31], vcc
	s_cbranch_execz .LBB0_1382
	s_waitcnt lgkmcnt(0)
	v_add_f32_e32 v50, v48, v49
	v_lshl_add_u64 v[48:49], v[118:119], 2, s[24:25]
	global_atomic_add_f32 v[48:49], v50, off
; __device__ __forceinline__ unsigned cvt_pk(float lo, float hi) { unsigned r; asm("v_cvt_pk_bf16_f32 %0, %1, %2" : "=v"(r) : "v"(lo), "v"(hi)); return r; }
; __device__ __forceinline__ float fexp2(float x) { return __builtin_amdgcn_exp2f(x); }
; __device__ __forceinline__ float frcp(float x) { return __builtin_amdgcn_rcpf(x); }
;     __device__ __forceinline__ void operator()(AccRef acc, const pg8::Unit& u, int wr, int wc, int, int) const {
;     ...
;                 for (int bj = 0; bj < 2; ++bj) {
;                     const int c0 = u.pn * 256 + bj * 128 + wc * 32 + 8 * fq;
;                     const v4u hw = hwv[m][bj], pw = pwv[m][bj];
;                     const float hh[8] = {bf_lo(hw.x), bf_hi(hw.x), bf_lo(hw.y), bf_hi(hw.y), bf_lo(hw.z), bf_hi(hw.z), bf_lo(hw.w), bf_hi(hw.w)};
;                     const float pp[8] = {bf_lo(pw.x), bf_hi(pw.x), bf_lo(pw.y), bf_hi(pw.y), bf_lo(pw.z), bf_hi(pw.z), bf_lo(pw.w), bf_hi(pw.w)};
;                     float o[8];
; #pragma unroll
;                     for (int j = 0; j < 4; ++j) {
;                         o[j] = hh[j] + pp[j] * frcp(1.0f + fexp2(-acc[ai][bj][m][0][j] * LOG2E));
;                         o[4 + j] = hh[4 + j] + pp[4 + j] * frcp(1.0f + fexp2(-acc[ai][bj][m][1][j] * LOG2E));
;                     }
;                     v4u w; w.x = cvt_pk(o[0], o[1]); w.y = cvt_pk(o[2], o[3]); w.z = cvt_pk(o[4], o[5]); w.w = cvt_pk(o[6], o[7]);
;                     *(v4u*)(XB + (size_t)row * DM + c0) = w;
; #pragma unroll
;                     for (int j = 0; j < 8; ++j) ss += o[j] * o[j];
;                 }
;                 ss += __shfl_xor(ss, 16); ss += __shfl_xor(ss, 32);
;                 if (fq == 0) __hip_atomic_fetch_add(ssq + row, ss, __ATOMIC_RELAXED, __HIP_MEMORY_SCOPE_AGENT);
;             }
.LBB0_1382:
	s_or_b64 exec, exec, s[30:31]
	v_mul_f32_e32 v40, 0xbfb8aa3b, v40
	v_exp_f32_e32 v40, v40
	v_mul_f32_e32 v41, 0xbfb8aa3b, v41
	v_exp_f32_e32 v41, v41
	s_waitcnt vmcnt(13)
	v_lshlrev_b32_e32 v54, 16, v110
	v_add_f32_e32 v40, 1.0, v40
	v_rcp_f32_e32 v40, v40
	s_waitcnt vmcnt(11)
	v_lshlrev_b32_e32 v62, 16, v106
	v_mul_f32_e32 v45, 0xbfb8aa3b, v45
	v_mul_f32_e32 v44, 0xbfb8aa3b, v44
	v_exp_f32_e32 v45, v45
	v_fmac_f32_e32 v54, v40, v62
	v_add_f32_e32 v40, 1.0, v41
	v_mul_f32_e32 v41, 0xbfb8aa3b, v46
	v_mul_f32_e32 v42, 0xbfb8aa3b, v42
	v_exp_f32_e32 v44, v44
	v_rcp_f32_e32 v40, v40
	v_exp_f32_e32 v41, v41
	v_exp_f32_e32 v42, v42
	v_mul_f32_e32 v32, 0xbfb8aa3b, v32
	v_exp_f32_e32 v32, v32
	v_and_b32_e32 v55, 0xffff0000, v110
	v_and_b32_e32 v63, 0xffff0000, v106
	v_add_f32_e32 v45, 1.0, v45
	v_add_f32_e32 v44, 1.0, v44
	v_rcp_f32_e32 v45, v45
	v_fmac_f32_e32 v55, v40, v63
	v_add_f32_e32 v40, 1.0, v41
	v_add_f32_e32 v41, 1.0, v42
	v_mul_f32_e32 v42, 0xbfb8aa3b, v47
	v_rcp_f32_e32 v44, v44
	v_rcp_f32_e32 v40, v40
	v_exp_f32_e32 v42, v42
	v_add_f32_e32 v32, 1.0, v32
	v_mul_f32_e32 v33, 0xbfb8aa3b, v33
	v_rcp_f32_e32 v32, v32
	v_exp_f32_e32 v33, v33
	v_and_b32_e32 v51, 0xffff0000, v108
	v_and_b32_e32 v59, 0xffff0000, v104
	v_lshlrev_b32_e32 v50, 16, v108
	v_lshlrev_b32_e32 v52, 16, v109
	v_lshlrev_b32_e32 v58, 16, v104
	v_lshlrev_b32_e32 v60, 16, v105
	v_fmac_f32_e32 v51, v45, v59
	v_fmac_f32_e32 v50, v44, v58
	v_add_f32_e32 v42, 1.0, v42
	v_fmac_f32_e32 v52, v40, v60
	v_cvt_pk_bf16_f32 v40, v50, v51
	v_mul_f32_e32 v44, v51, v51
	v_lshlrev_b32_e32 v51, 16, v102
	s_waitcnt vmcnt(10)
	v_lshlrev_b32_e32 v60, 16, v98
	v_rcp_f32_e32 v41, v41
	v_rcp_f32_e32 v42, v42
	v_fmac_f32_e32 v51, v32, v60
	v_add_f32_e32 v32, 1.0, v33
	v_mul_f32_e32 v33, 0xbfb8aa3b, v38
	v_mul_f32_e32 v34, 0xbfb8aa3b, v34
	v_mul_f32_e32 v43, 0xbfb8aa3b, v43
	v_rcp_f32_e32 v32, v32
	v_exp_f32_e32 v33, v33
	v_exp_f32_e32 v34, v34
	v_exp_f32_e32 v43, v43
	v_mul_f32_e32 v36, 0xbfb8aa3b, v36
	v_and_b32_e32 v53, 0xffff0000, v109
	v_lshlrev_b32_e32 v56, 16, v111
	v_and_b32_e32 v61, 0xffff0000, v105
	v_lshlrev_b32_e32 v104, 16, v107
	v_fmac_f32_e32 v44, v50, v50
	v_exp_f32_e32 v36, v36
	v_mul_f32_e32 v37, 0xbfb8aa3b, v37
	v_fmac_f32_e32 v56, v41, v104
	v_fmac_f32_e32 v53, v42, v61
	v_cvt_pk_bf16_f32 v41, v52, v53
	v_fmac_f32_e32 v44, v52, v52
	v_and_b32_e32 v52, 0xffff0000, v102
	v_and_b32_e32 v61, 0xffff0000, v98
	v_exp_f32_e32 v37, v37
	v_fmac_f32_e32 v52, v32, v61
	v_add_f32_e32 v32, 1.0, v33
	v_add_f32_e32 v33, 1.0, v34
	v_mul_f32_e32 v34, 0xbfb8aa3b, v39
	v_add_f32_e32 v43, 1.0, v43
	v_exp_f32_e32 v34, v34
	v_rcp_f32_e32 v43, v43
	v_add_f32_e32 v36, 1.0, v36
	v_fmac_f32_e32 v44, v53, v53
	v_rcp_f32_e32 v36, v36
	v_add_f32_e32 v37, 1.0, v37
	v_fmac_f32_e32 v44, v54, v54
	v_rcp_f32_e32 v37, v37
	v_mul_f32_e32 v35, 0xbfb8aa3b, v35
	v_and_b32_e32 v57, 0xffff0000, v111
	v_and_b32_e32 v105, 0xffff0000, v107
	v_fmac_f32_e32 v44, v55, v55
	v_rcp_f32_e32 v32, v32
	v_exp_f32_e32 v35, v35
	v_add_f32_e32 v34, 1.0, v34
	v_fmac_f32_e32 v57, v43, v105
	v_fmac_f32_e32 v44, v56, v56
	v_lshlrev_b32_e32 v45, 16, v100
	v_lshlrev_b32_e32 v43, 16, v96
	v_rcp_f32_e32 v34, v34
	v_cvt_pk_bf16_f32 v42, v54, v55
	v_fmac_f32_e32 v44, v57, v57
	v_and_b32_e32 v46, 0xffff0000, v100
	v_and_b32_e32 v55, 0xffff0000, v96
	v_fmac_f32_e32 v45, v36, v43
	v_lshlrev_b32_e32 v47, 16, v101
	v_lshlrev_b32_e32 v58, 16, v97
	v_fmac_f32_e32 v46, v37, v55
	v_fmac_f32_e32 v44, v45, v45
	v_and_b32_e32 v50, 0xffff0000, v101
	v_and_b32_e32 v59, 0xffff0000, v97
	v_rcp_f32_e32 v33, v33
	v_add_f32_e32 v35, 1.0, v35
	v_fmac_f32_e32 v47, v32, v58
	v_fmac_f32_e32 v44, v46, v46
	v_rcp_f32_e32 v35, v35
	v_fmac_f32_e32 v50, v34, v59
	v_fmac_f32_e32 v44, v47, v47
	v_fmac_f32_e32 v44, v50, v50
	v_lshlrev_b32_e32 v53, 16, v103
	v_lshlrev_b32_e32 v62, 16, v99
	v_fmac_f32_e32 v44, v51, v51
	v_and_b32_e32 v54, 0xffff0000, v103
	v_and_b32_e32 v63, 0xffff0000, v99
	v_fmac_f32_e32 v53, v33, v62
	v_fmac_f32_e32 v44, v52, v52
	v_fmac_f32_e32 v54, v35, v63
	v_fmac_f32_e32 v44, v53, v53
	v_fmac_f32_e32 v44, v54, v54
	ds_bpermute_b32 v32, v197, v44
	s_waitcnt lgkmcnt(1)
	v_lshlrev_b64 v[48:49], 11, v[116:117]
	v_lshl_add_u64 v[48:49], s[26:27], 0, v[48:49]
	v_lshl_add_u64 v[38:39], v[120:121], 1, v[48:49]
	v_cvt_pk_bf16_f32 v43, v56, v57
	s_waitcnt lgkmcnt(0)
	v_add_f32_e32 v32, v44, v32
	ds_bpermute_b32 v33, v198, v32
	global_store_dwordx4 v[38:39], v[40:43], off sc1
	v_cvt_pk_bf16_f32 v34, v45, v46
	v_cvt_pk_bf16_f32 v35, v47, v50
	v_cvt_pk_bf16_f32 v36, v51, v52
	v_cvt_pk_bf16_f32 v37, v53, v54
	global_store_dwordx4 v[38:39], v[34:37], off offset:256 sc1
	s_and_saveexec_b64 s[30:31], vcc
	s_cbranch_execz .LBB0_1384
	s_waitcnt lgkmcnt(0)
	v_add_f32_e32 v34, v32, v33
	v_lshl_add_u64 v[32:33], v[116:117], 2, s[24:25]
	global_atomic_add_f32 v[32:33], v34, off
; __device__ __forceinline__ unsigned cvt_pk(float lo, float hi) { unsigned r; asm("v_cvt_pk_bf16_f32 %0, %1, %2" : "=v"(r) : "v"(lo), "v"(hi)); return r; }
; __device__ __forceinline__ float fexp2(float x) { return __builtin_amdgcn_exp2f(x); }
; __device__ __forceinline__ float frcp(float x) { return __builtin_amdgcn_rcpf(x); }
;     __device__ __forceinline__ void operator()(AccRef acc, const pg8::Unit& u, int wr, int wc, int, int) const {
;     ...
;                 for (int bj = 0; bj < 2; ++bj) {
;                     const int c0 = u.pn * 256 + bj * 128 + wc * 32 + 8 * fq;
;                     const v4u hw = hwv[m][bj], pw = pwv[m][bj];
;                     const float hh[8] = {bf_lo(hw.x), bf_hi(hw.x), bf_lo(hw.y), bf_hi(hw.y), bf_lo(hw.z), bf_hi(hw.z), bf_lo(hw.w), bf_hi(hw.w)};
;                     const float pp[8] = {bf_lo(pw.x), bf_hi(pw.x), bf_lo(pw.y), bf_hi(pw.y), bf_lo(pw.z), bf_hi(pw.z), bf_lo(pw.w), bf_hi(pw.w)};
;                     float o[8];
; #pragma unroll
;                     for (int j = 0; j < 4; ++j) {
;                         o[j] = hh[j] + pp[j] * frcp(1.0f + fexp2(-acc[ai][bj][m][0][j] * LOG2E));
;                         o[4 + j] = hh[4 + j] + pp[4 + j] * frcp(1.0f + fexp2(-acc[ai][bj][m][1][j] * LOG2E));
;                     }
;                     v4u w; w.x = cvt_pk(o[0], o[1]); w.y = cvt_pk(o[2], o[3]); w.z = cvt_pk(o[4], o[5]); w.w = cvt_pk(o[6], o[7]);
;                     *(v4u*)(XB + (size_t)row * DM + c0) = w;
; #pragma unroll
;                     for (int j = 0; j < 8; ++j) ss += o[j] * o[j];
;                 }
;                 ss += __shfl_xor(ss, 16); ss += __shfl_xor(ss, 32);
;                 if (fq == 0) __hip_atomic_fetch_add(ssq + row, ss, __ATOMIC_RELAXED, __HIP_MEMORY_SCOPE_AGENT);
;             }
.LBB0_1384:
	s_or_b64 exec, exec, s[30:31]
	v_mul_f32_e32 v24, 0xbfb8aa3b, v24
	v_exp_f32_e32 v24, v24
	v_mul_f32_e32 v25, 0xbfb8aa3b, v25
	v_exp_f32_e32 v25, v25
	s_waitcnt vmcnt(11)
	v_lshlrev_b32_e32 v38, 16, v94
	v_add_f32_e32 v24, 1.0, v24
	v_rcp_f32_e32 v24, v24
	s_waitcnt vmcnt(9)
	v_lshlrev_b32_e32 v46, 16, v90
	v_mul_f32_e32 v29, 0xbfb8aa3b, v29
	v_mul_f32_e32 v28, 0xbfb8aa3b, v28
	v_exp_f32_e32 v29, v29
	v_fmac_f32_e32 v38, v24, v46
	v_add_f32_e32 v24, 1.0, v25
	v_mul_f32_e32 v25, 0xbfb8aa3b, v30
	v_mul_f32_e32 v26, 0xbfb8aa3b, v26
	v_exp_f32_e32 v28, v28
	v_rcp_f32_e32 v24, v24
	v_exp_f32_e32 v25, v25
	v_exp_f32_e32 v26, v26
	v_mul_f32_e32 v16, 0xbfb8aa3b, v16
	v_exp_f32_e32 v16, v16
	v_and_b32_e32 v39, 0xffff0000, v94
	v_and_b32_e32 v47, 0xffff0000, v90
	v_add_f32_e32 v29, 1.0, v29
	v_add_f32_e32 v28, 1.0, v28
	v_rcp_f32_e32 v29, v29
	v_fmac_f32_e32 v39, v24, v47
	v_add_f32_e32 v24, 1.0, v25
	v_add_f32_e32 v25, 1.0, v26
	v_mul_f32_e32 v26, 0xbfb8aa3b, v31
	v_rcp_f32_e32 v28, v28
	v_rcp_f32_e32 v24, v24
	v_exp_f32_e32 v26, v26
	v_add_f32_e32 v16, 1.0, v16
	v_mul_f32_e32 v17, 0xbfb8aa3b, v17
	v_rcp_f32_e32 v16, v16
	v_exp_f32_e32 v17, v17
	v_and_b32_e32 v35, 0xffff0000, v92
	v_and_b32_e32 v43, 0xffff0000, v88
	v_lshlrev_b32_e32 v34, 16, v92
	v_lshlrev_b32_e32 v36, 16, v93
	v_lshlrev_b32_e32 v42, 16, v88
	v_lshlrev_b32_e32 v44, 16, v89
	v_fmac_f32_e32 v35, v29, v43
	v_fmac_f32_e32 v34, v28, v42
	v_add_f32_e32 v26, 1.0, v26
	v_fmac_f32_e32 v36, v24, v44
	v_cvt_pk_bf16_f32 v24, v34, v35
	v_mul_f32_e32 v28, v35, v35
	v_lshlrev_b32_e32 v35, 16, v86
	s_waitcnt vmcnt(8)
	v_lshlrev_b32_e32 v44, 16, v82
	v_rcp_f32_e32 v25, v25
	v_rcp_f32_e32 v26, v26
	v_fmac_f32_e32 v35, v16, v44
	v_add_f32_e32 v16, 1.0, v17
	v_mul_f32_e32 v17, 0xbfb8aa3b, v22
	v_mul_f32_e32 v18, 0xbfb8aa3b, v18
	v_mul_f32_e32 v27, 0xbfb8aa3b, v27
	v_rcp_f32_e32 v16, v16
	v_exp_f32_e32 v17, v17
	v_exp_f32_e32 v18, v18
	v_exp_f32_e32 v27, v27
	v_mul_f32_e32 v20, 0xbfb8aa3b, v20
	v_and_b32_e32 v37, 0xffff0000, v93
	v_lshlrev_b32_e32 v40, 16, v95
	v_and_b32_e32 v45, 0xffff0000, v89
	v_lshlrev_b32_e32 v48, 16, v91
	v_fmac_f32_e32 v28, v34, v34
	v_exp_f32_e32 v20, v20
	v_mul_f32_e32 v21, 0xbfb8aa3b, v21
	v_fmac_f32_e32 v40, v25, v48
	v_fmac_f32_e32 v37, v26, v45
	v_cvt_pk_bf16_f32 v25, v36, v37
	v_fmac_f32_e32 v28, v36, v36
	v_and_b32_e32 v36, 0xffff0000, v86
	v_and_b32_e32 v45, 0xffff0000, v82
	v_exp_f32_e32 v21, v21
	v_fmac_f32_e32 v36, v16, v45
	v_add_f32_e32 v16, 1.0, v17
	v_add_f32_e32 v17, 1.0, v18
	v_mul_f32_e32 v18, 0xbfb8aa3b, v23
	v_add_f32_e32 v27, 1.0, v27
	v_exp_f32_e32 v18, v18
	v_rcp_f32_e32 v27, v27
	v_add_f32_e32 v20, 1.0, v20
	v_fmac_f32_e32 v28, v37, v37
	v_rcp_f32_e32 v20, v20
	v_add_f32_e32 v21, 1.0, v21
	v_fmac_f32_e32 v28, v38, v38
	v_rcp_f32_e32 v21, v21
	v_mul_f32_e32 v19, 0xbfb8aa3b, v19
	v_and_b32_e32 v41, 0xffff0000, v95
	v_and_b32_e32 v49, 0xffff0000, v91
	v_fmac_f32_e32 v28, v39, v39
	v_rcp_f32_e32 v16, v16
	v_exp_f32_e32 v19, v19
	v_add_f32_e32 v18, 1.0, v18
	v_fmac_f32_e32 v41, v27, v49
	v_fmac_f32_e32 v28, v40, v40
	v_lshlrev_b32_e32 v29, 16, v84
	v_lshlrev_b32_e32 v27, 16, v80
	v_rcp_f32_e32 v18, v18
	v_cvt_pk_bf16_f32 v26, v38, v39
	v_fmac_f32_e32 v28, v41, v41
	v_and_b32_e32 v30, 0xffff0000, v84
	v_and_b32_e32 v39, 0xffff0000, v80
	v_fmac_f32_e32 v29, v20, v27
	v_lshlrev_b32_e32 v31, 16, v85
	v_lshlrev_b32_e32 v42, 16, v81
	v_fmac_f32_e32 v30, v21, v39
	v_fmac_f32_e32 v28, v29, v29
	v_and_b32_e32 v34, 0xffff0000, v85
	v_and_b32_e32 v43, 0xffff0000, v81
	v_rcp_f32_e32 v17, v17
	v_add_f32_e32 v19, 1.0, v19
	v_fmac_f32_e32 v31, v16, v42
	v_fmac_f32_e32 v28, v30, v30
	v_rcp_f32_e32 v19, v19
	v_fmac_f32_e32 v34, v18, v43
	v_fmac_f32_e32 v28, v31, v31
	v_fmac_f32_e32 v28, v34, v34
	v_lshlrev_b32_e32 v37, 16, v87
	v_lshlrev_b32_e32 v46, 16, v83
	v_fmac_f32_e32 v28, v35, v35
	v_and_b32_e32 v38, 0xffff0000, v87
	v_and_b32_e32 v47, 0xffff0000, v83
	v_fmac_f32_e32 v37, v17, v46
	v_fmac_f32_e32 v28, v36, v36
	v_fmac_f32_e32 v38, v19, v47
	v_fmac_f32_e32 v28, v37, v37
	v_fmac_f32_e32 v28, v38, v38
	ds_bpermute_b32 v16, v197, v28
	s_waitcnt lgkmcnt(1)
	v_lshlrev_b64 v[32:33], 11, v[114:115]
	v_lshl_add_u64 v[32:33], s[26:27], 0, v[32:33]
	v_lshl_add_u64 v[22:23], v[120:121], 1, v[32:33]
	v_cvt_pk_bf16_f32 v27, v40, v41
	s_waitcnt lgkmcnt(0)
	v_add_f32_e32 v16, v28, v16
	ds_bpermute_b32 v17, v198, v16
	global_store_dwordx4 v[22:23], v[24:27], off sc1
	v_cvt_pk_bf16_f32 v18, v29, v30
	v_cvt_pk_bf16_f32 v19, v31, v34
	v_cvt_pk_bf16_f32 v20, v35, v36
	v_cvt_pk_bf16_f32 v21, v37, v38
	global_store_dwordx4 v[22:23], v[18:21], off offset:256 sc1
	s_and_saveexec_b64 s[30:31], vcc
	s_cbranch_execz .LBB0_1386
	s_waitcnt lgkmcnt(0)
	v_add_f32_e32 v18, v16, v17
	v_lshl_add_u64 v[16:17], v[114:115], 2, s[24:25]
	global_atomic_add_f32 v[16:17], v18, off
; __device__ __forceinline__ unsigned cvt_pk(float lo, float hi) { unsigned r; asm("v_cvt_pk_bf16_f32 %0, %1, %2" : "=v"(r) : "v"(lo), "v"(hi)); return r; }
; __device__ __forceinline__ float fexp2(float x) { return __builtin_amdgcn_exp2f(x); }
; __device__ __forceinline__ float frcp(float x) { return __builtin_amdgcn_rcpf(x); }
;     __device__ __forceinline__ void operator()(AccRef acc, const pg8::Unit& u, int wr, int wc, int, int) const {
;     ...
;                 for (int bj = 0; bj < 2; ++bj) {
;                     const int c0 = u.pn * 256 + bj * 128 + wc * 32 + 8 * fq;
;                     const v4u hw = hwv[m][bj], pw = pwv[m][bj];
;                     const float hh[8] = {bf_lo(hw.x), bf_hi(hw.x), bf_lo(hw.y), bf_hi(hw.y), bf_lo(hw.z), bf_hi(hw.z), bf_lo(hw.w), bf_hi(hw.w)};
;                     const float pp[8] = {bf_lo(pw.x), bf_hi(pw.x), bf_lo(pw.y), bf_hi(pw.y), bf_lo(pw.z), bf_hi(pw.z), bf_lo(pw.w), bf_hi(pw.w)};
;                     float o[8];
; #pragma unroll
;                     for (int j = 0; j < 4; ++j) {
;                         o[j] = hh[j] + pp[j] * frcp(1.0f + fexp2(-acc[ai][bj][m][0][j] * LOG2E));
;                         o[4 + j] = hh[4 + j] + pp[4 + j] * frcp(1.0f + fexp2(-acc[ai][bj][m][1][j] * LOG2E));
;                     }
;                     v4u w; w.x = cvt_pk(o[0], o[1]); w.y = cvt_pk(o[2], o[3]); w.z = cvt_pk(o[4], o[5]); w.w = cvt_pk(o[6], o[7]);
;                     *(v4u*)(XB + (size_t)row * DM + c0) = w;
; #pragma unroll
;                     for (int j = 0; j < 8; ++j) ss += o[j] * o[j];
;                 }
;                 ss += __shfl_xor(ss, 16); ss += __shfl_xor(ss, 32);
;                 if (fq == 0) __hip_atomic_fetch_add(ssq + row, ss, __ATOMIC_RELAXED, __HIP_MEMORY_SCOPE_AGENT);
;             }
.LBB0_1386:
	s_or_b64 exec, exec, s[30:31]
	v_mul_f32_e32 v8, 0xbfb8aa3b, v8
	v_exp_f32_e32 v8, v8
	v_mul_f32_e32 v9, 0xbfb8aa3b, v9
	v_exp_f32_e32 v9, v9
	s_waitcnt vmcnt(9)
	v_lshlrev_b32_e32 v22, 16, v78
	v_add_f32_e32 v8, 1.0, v8
	v_rcp_f32_e32 v8, v8
	s_waitcnt vmcnt(7)
	v_lshlrev_b32_e32 v30, 16, v74
	v_mul_f32_e32 v13, 0xbfb8aa3b, v13
	v_mul_f32_e32 v12, 0xbfb8aa3b, v12
	v_exp_f32_e32 v13, v13
	v_fmac_f32_e32 v22, v8, v30
	v_add_f32_e32 v8, 1.0, v9
	v_mul_f32_e32 v9, 0xbfb8aa3b, v14
	v_mul_f32_e32 v10, 0xbfb8aa3b, v10
	v_exp_f32_e32 v12, v12
	v_rcp_f32_e32 v8, v8
	v_exp_f32_e32 v9, v9
	v_exp_f32_e32 v10, v10
	v_mul_f32_e32 v0, 0xbfb8aa3b, v0
	v_exp_f32_e32 v0, v0
	v_and_b32_e32 v23, 0xffff0000, v78
	v_and_b32_e32 v31, 0xffff0000, v74
	v_add_f32_e32 v13, 1.0, v13
	v_add_f32_e32 v12, 1.0, v12
	v_rcp_f32_e32 v13, v13
	v_fmac_f32_e32 v23, v8, v31
	v_add_f32_e32 v8, 1.0, v9
	v_add_f32_e32 v9, 1.0, v10
	v_mul_f32_e32 v10, 0xbfb8aa3b, v15
	v_rcp_f32_e32 v12, v12
	v_rcp_f32_e32 v8, v8
	v_exp_f32_e32 v10, v10
	v_add_f32_e32 v0, 1.0, v0
	v_mul_f32_e32 v1, 0xbfb8aa3b, v1
	v_rcp_f32_e32 v0, v0
	v_exp_f32_e32 v1, v1
	v_and_b32_e32 v19, 0xffff0000, v76
	v_and_b32_e32 v27, 0xffff0000, v72
	v_lshlrev_b32_e32 v18, 16, v76
	v_lshlrev_b32_e32 v20, 16, v77
	v_lshlrev_b32_e32 v26, 16, v72
	v_lshlrev_b32_e32 v28, 16, v73
	v_fmac_f32_e32 v19, v13, v27
	v_fmac_f32_e32 v18, v12, v26
	v_add_f32_e32 v10, 1.0, v10
	v_fmac_f32_e32 v20, v8, v28
	v_cvt_pk_bf16_f32 v8, v18, v19
	v_mul_f32_e32 v12, v19, v19
	v_lshlrev_b32_e32 v19, 16, v70
	s_waitcnt vmcnt(6)
	v_lshlrev_b32_e32 v28, 16, v66
	v_rcp_f32_e32 v9, v9
	v_rcp_f32_e32 v10, v10
	v_fmac_f32_e32 v19, v0, v28
	v_add_f32_e32 v0, 1.0, v1
	v_mul_f32_e32 v1, 0xbfb8aa3b, v6
	v_mul_f32_e32 v2, 0xbfb8aa3b, v2
	v_mul_f32_e32 v11, 0xbfb8aa3b, v11
	v_rcp_f32_e32 v0, v0
	v_exp_f32_e32 v1, v1
	v_exp_f32_e32 v2, v2
	v_exp_f32_e32 v11, v11
	v_mul_f32_e32 v4, 0xbfb8aa3b, v4
	v_and_b32_e32 v21, 0xffff0000, v77
	v_lshlrev_b32_e32 v24, 16, v79
	v_and_b32_e32 v29, 0xffff0000, v73
	v_lshlrev_b32_e32 v32, 16, v75
	v_fmac_f32_e32 v12, v18, v18
	v_exp_f32_e32 v4, v4
	v_mul_f32_e32 v5, 0xbfb8aa3b, v5
	v_fmac_f32_e32 v24, v9, v32
	v_fmac_f32_e32 v21, v10, v29
	v_cvt_pk_bf16_f32 v9, v20, v21
	v_fmac_f32_e32 v12, v20, v20
	v_and_b32_e32 v20, 0xffff0000, v70
	v_and_b32_e32 v29, 0xffff0000, v66
	v_exp_f32_e32 v5, v5
	v_fmac_f32_e32 v20, v0, v29
	v_add_f32_e32 v0, 1.0, v1
	v_add_f32_e32 v1, 1.0, v2
	v_mul_f32_e32 v2, 0xbfb8aa3b, v7
	v_add_f32_e32 v11, 1.0, v11
	v_exp_f32_e32 v2, v2
	v_rcp_f32_e32 v11, v11
	v_add_f32_e32 v4, 1.0, v4
	v_fmac_f32_e32 v12, v21, v21
	v_rcp_f32_e32 v4, v4
	v_add_f32_e32 v5, 1.0, v5
	v_fmac_f32_e32 v12, v22, v22
	v_rcp_f32_e32 v5, v5
	v_mul_f32_e32 v3, 0xbfb8aa3b, v3
	v_and_b32_e32 v25, 0xffff0000, v79
	v_and_b32_e32 v33, 0xffff0000, v75
	v_fmac_f32_e32 v12, v23, v23
	v_rcp_f32_e32 v0, v0
	v_exp_f32_e32 v3, v3
	v_add_f32_e32 v2, 1.0, v2
	v_fmac_f32_e32 v25, v11, v33
	v_fmac_f32_e32 v12, v24, v24
	v_lshlrev_b32_e32 v13, 16, v68
	v_lshlrev_b32_e32 v11, 16, v64
	v_rcp_f32_e32 v2, v2
	v_cvt_pk_bf16_f32 v10, v22, v23
	v_fmac_f32_e32 v12, v25, v25
	v_and_b32_e32 v14, 0xffff0000, v68
	v_and_b32_e32 v23, 0xffff0000, v64
	v_fmac_f32_e32 v13, v4, v11
	v_lshlrev_b32_e32 v15, 16, v69
	v_lshlrev_b32_e32 v26, 16, v65
	v_fmac_f32_e32 v14, v5, v23
	v_fmac_f32_e32 v12, v13, v13
	v_and_b32_e32 v18, 0xffff0000, v69
	v_and_b32_e32 v27, 0xffff0000, v65
	v_rcp_f32_e32 v1, v1
	v_add_f32_e32 v3, 1.0, v3
	v_fmac_f32_e32 v15, v0, v26
	v_fmac_f32_e32 v12, v14, v14
	v_rcp_f32_e32 v3, v3
	v_fmac_f32_e32 v18, v2, v27
	v_fmac_f32_e32 v12, v15, v15
	v_fmac_f32_e32 v12, v18, v18
	v_lshlrev_b32_e32 v21, 16, v71
	v_lshlrev_b32_e32 v30, 16, v67
	v_fmac_f32_e32 v12, v19, v19
	v_and_b32_e32 v22, 0xffff0000, v71
	v_and_b32_e32 v31, 0xffff0000, v67
	v_fmac_f32_e32 v21, v1, v30
	v_fmac_f32_e32 v12, v20, v20
	v_fmac_f32_e32 v22, v3, v31
	v_fmac_f32_e32 v12, v21, v21
	v_fmac_f32_e32 v12, v22, v22
	ds_bpermute_b32 v0, v197, v12
	s_waitcnt lgkmcnt(1)
	v_lshlrev_b64 v[16:17], 11, v[112:113]
	v_lshl_add_u64 v[16:17], s[26:27], 0, v[16:17]
	v_lshl_add_u64 v[6:7], v[120:121], 1, v[16:17]
	v_cvt_pk_bf16_f32 v11, v24, v25
	s_waitcnt lgkmcnt(0)
	v_add_f32_e32 v0, v12, v0
	ds_bpermute_b32 v1, v198, v0
	global_store_dwordx4 v[6:7], v[8:11], off sc1
	v_cvt_pk_bf16_f32 v2, v13, v14
	v_cvt_pk_bf16_f32 v3, v15, v18
	v_cvt_pk_bf16_f32 v4, v19, v20
	v_cvt_pk_bf16_f32 v5, v21, v22
	global_store_dwordx4 v[6:7], v[2:5], off offset:256 sc1
	s_and_saveexec_b64 s[26:27], vcc
	s_cbranch_execz .LBB0_1388
	s_waitcnt lgkmcnt(0)
	v_add_f32_e32 v2, v0, v1
	v_lshl_add_u64 v[0:1], v[112:113], 2, s[24:25]
	global_atomic_add_f32 v[0:1], v2, off
